# K-loops: the two inline-asm waits before each pre-MFMA barrier fused into one s_waitcnt vmcnt(8) lgkmcnt(0), on top of the no-setprio version
# speedup vs baseline: 1.0025x; 1.0002x over previous
; #define PG8_STAGE(bufoff, gbase, voff) do { _Pragma("unroll") for (int _i = 0; _i < 2; ++_i) \
;         __builtin_amdgcn_global_load_lds((const unsigned*)((const char*)(gbase) + (voff)[_i]), (LAS unsigned*)(lds + (bufoff) + ldsw + _i * 8192), 16, 0, 0); } while (0)
; #define PG8_LDA(dst, b, h) do { _Pragma("unroll") for (int m = 0; m < 4; ++m) _Pragma("unroll") for (int k = 0; k < 2; ++k) dst[m][k] = *(const LAS bf16x8*)(lds + PG8_SA(b, h) + aoff + m * 2048 + k * 1024); } while (0)
; #define PG8_LDB(dst, b, h) do { _Pragma("unroll") for (int n = 0; n < 2; ++n) _Pragma("unroll") for (int k = 0; k < 2; ++k) dst[n][k] = *(const LAS bf16x8*)(lds + PG8_SB(b, h) + boff + n * 2048 + k * 1024); } while (0)
; #define PG8_WAIT_V(n) asm volatile("s_waitcnt vmcnt(" #n ")" ::: "memory")
; #define PG8_BAR __builtin_amdgcn_s_barrier()
; template <class Epi, class Sched = StaticOrder, class EpiSub = NoSub, bool FAST = false>
; __device__ __forceinline__ void gemm_phase(LAS unsigned char* lds, const Gemm g, const Sched& S, const Epi& E, const EpiSub& ES = EpiSub()) {
;     ...
;         const bool has_next = S.next(ui + 1, nxt);
;         const size_t nko = (has_next && nxt.kb >= 0) ? nxt.kb * ksubB : 0;
;         const char* nA = has_next ? (const char*)g.A + (size_t)nxt.pm * tstepA + (size_t)nxt.pn * g.acs + nko : cA; const char* nB = has_next ? (const char*)g.Bt + (size_t)nxt.pn * tstepB + nko : cB;
;         const int nt = cur.kb < 0 ? ntMain : ntSub;
;         for (int t = 0; t < nt; t += 2) {
;             const bool last = (t == nt - 2);
;             const char* a1 = cA + (size_t)(t + 1) * kstep;
;             const char* a2 = last ? nA : cA + (size_t)(t + 2) * kstep; const char* b2 = last ? nB : cB + (size_t)(t + 2) * kstep;
;             const char* a3 = a2 + kstep; const char* b3 = b2 + kstep;
;             if constexpr (FAST && PG8_SP2) {
;             PG8_LDB(B0, 0, 0); PG8_LDB(B1, 0, 1); PG8_SCHED; PG8_LDA(At, 0, 0); PG8_STAGE(PG8_SA(1, 1), a1 + hstepA, voffA);
;             PG8_WAIT_V(8); PG8_WAIT_L(0); PG8_BAR; PG8_MMA(0, 0, At, B0); PG8_MMA(0, 1, At, B1); PG8_BAR; PG8_SCHED;
;             PG8_LDA(At, 0, 1); PG8_STAGE(PG8_SB(0, 0), b2, voffB); PG8_STAGE(PG8_SB(0, 1), b2 + hstepB, voffB); PG8_STAGE(PG8_SA(0, 0), a2, voffA);
;             PG8_WAIT_V(8); PG8_WAIT_L(0); PG8_BAR; PG8_MMA(1, 0, At, B0); PG8_MMA(1, 1, At, B1); PG8_BAR; PG8_SCHED;
.LBB0_215:
	s_ashr_i32 s15, s14, 31
	s_lshl_b64 s[2:3], s[14:15], 20
	v_readlane_b32 s16, v254, 36
	v_readlane_b32 s17, v254, 37
	s_add_u32 s16, s16, s2
	s_addc_u32 s17, s17, s3
	s_and_b64 s[2:3], s[0:1], exec
	s_cselect_b32 s2, s17, s23
	s_cselect_b32 s3, s16, s22
	s_ashr_i32 s13, s12, 31
	s_lshl_b64 s[18:19], s[12:13], 20
	s_add_u32 s18, s28, s18
	s_addc_u32 s19, s29, s19
	s_and_b64 s[26:27], s[0:1], exec
	s_cselect_b32 s13, s19, s25
	s_cselect_b32 s15, s18, s24
	s_add_u32 s22, s22, 0x80080
	s_addc_u32 s23, s23, 0
	s_add_u32 s48, s24, 0x100
	s_addc_u32 s49, s25, 0
	s_mov_b32 s50, -2
	ds_read_b128 v[154:157], v150
	ds_read_b128 v[158:161], v150 offset:1024
	ds_read_b128 v[162:165], v150 offset:2048
	ds_read_b128 v[166:169], v150 offset:3072
	ds_read_b128 v[170:173], v151
	ds_read_b128 v[174:177], v151 offset:1024
	ds_read_b128 v[178:181], v151 offset:2048
	ds_read_b128 v[182:185], v151 offset:3072
	s_add_u32 s24, s22, 0xfff80080
	s_addc_u32 s25, s23, -1
	s_cmp_eq_u32 s50, 28
	s_cselect_b32 s27, s2, s25
	s_cselect_b32 s26, s3, s24
	s_cselect_b32 s25, s13, s49
	s_cselect_b32 s24, s15, s48
	v_lshl_add_u64 v[144:145], s[22:23], 0, v[136:137]
	s_add_i32 m0, s21, 0xc000
	ds_read_b128 v[186:189], v152
	ds_read_b128 v[194:197], v152 offset:1024
	ds_read_b128 v[198:201], v152 offset:2048
	ds_read_b128 v[202:205], v152 offset:3072
	ds_read_b128 v[206:209], v152 offset:4096
	ds_read_b128 v[210:213], v152 offset:5120
	ds_read_b128 v[214:217], v152 offset:6144
	ds_read_b128 v[218:221], v152 offset:7168
	global_load_lds_dwordx4 v[144:145], off
	v_lshl_add_u64 v[144:145], s[22:23], 0, v[138:139]
	s_add_i32 m0, s21, 0xe000
	s_nop 0
	global_load_lds_dwordx4 v[144:145], off
	s_waitcnt vmcnt(8) lgkmcnt(0)
	s_barrier
	v_mfma_f32_16x16x32_bf16 v[124:127], v[154:157], v[186:189], 0
	v_mfma_f32_16x16x32_bf16 v[120:123], v[162:165], v[186:189], 0
	v_mfma_f32_16x16x32_bf16 v[116:119], v[154:157], v[198:201], 0
	v_mfma_f32_16x16x32_bf16 v[108:111], v[162:165], v[198:201], 0
	v_mfma_f32_16x16x32_bf16 v[100:103], v[154:157], v[206:209], 0
	v_mfma_f32_16x16x32_bf16 v[92:95], v[162:165], v[206:209], 0
	v_mfma_f32_16x16x32_bf16 v[84:87], v[154:157], v[214:217], 0
	v_mfma_f32_16x16x32_bf16 v[76:79], v[162:165], v[214:217], 0
	v_mfma_f32_16x16x32_bf16 v[124:127], v[158:161], v[194:197], v[124:127]
	v_mfma_f32_16x16x32_bf16 v[120:123], v[166:169], v[194:197], v[120:123]
	v_mfma_f32_16x16x32_bf16 v[116:119], v[158:161], v[202:205], v[116:119]
	v_mfma_f32_16x16x32_bf16 v[108:111], v[166:169], v[202:205], v[108:111]
	v_mfma_f32_16x16x32_bf16 v[100:103], v[158:161], v[210:213], v[100:103]
	v_mfma_f32_16x16x32_bf16 v[92:95], v[166:169], v[210:213], v[92:95]
	v_mfma_f32_16x16x32_bf16 v[84:87], v[158:161], v[218:221], v[84:87]
	v_mfma_f32_16x16x32_bf16 v[76:79], v[166:169], v[218:221], v[76:79]
	v_mfma_f32_16x16x32_bf16 v[112:115], v[170:173], v[186:189], 0
	v_mfma_f32_16x16x32_bf16 v[104:107], v[178:181], v[186:189], 0
	v_mfma_f32_16x16x32_bf16 v[96:99], v[170:173], v[198:201], 0
	v_mfma_f32_16x16x32_bf16 v[88:91], v[178:181], v[198:201], 0
	v_mfma_f32_16x16x32_bf16 v[80:83], v[170:173], v[206:209], 0
	v_mfma_f32_16x16x32_bf16 v[72:75], v[178:181], v[206:209], 0
	v_mfma_f32_16x16x32_bf16 v[68:71], v[170:173], v[214:217], 0
	v_mfma_f32_16x16x32_bf16 v[64:67], v[178:181], v[214:217], 0
	v_mfma_f32_16x16x32_bf16 v[112:115], v[174:177], v[194:197], v[112:115]
	v_mfma_f32_16x16x32_bf16 v[104:107], v[182:185], v[194:197], v[104:107]
	v_mfma_f32_16x16x32_bf16 v[96:99], v[174:177], v[202:205], v[96:99]
	v_mfma_f32_16x16x32_bf16 v[88:91], v[182:185], v[202:205], v[88:91]
	v_mfma_f32_16x16x32_bf16 v[80:83], v[174:177], v[210:213], v[80:83]
	v_mfma_f32_16x16x32_bf16 v[72:75], v[182:185], v[210:213], v[72:75]
	v_mfma_f32_16x16x32_bf16 v[68:71], v[174:177], v[218:221], v[68:71]
	v_mfma_f32_16x16x32_bf16 v[64:67], v[182:185], v[218:221], v[64:67]
	s_barrier
	s_add_i32 s51, s41, s30
	v_lshl_add_u64 v[144:145], s[24:25], 0, v[130:131]
	s_mov_b32 m0, s51
	ds_read_b128 v[186:189], v152 offset:16384
	ds_read_b128 v[194:197], v152 offset:17408
	ds_read_b128 v[198:201], v152 offset:18432
	ds_read_b128 v[202:205], v152 offset:19456
	ds_read_b128 v[206:209], v152 offset:20480
	ds_read_b128 v[210:213], v152 offset:21504
	ds_read_b128 v[214:217], v152 offset:22528
	ds_read_b128 v[218:221], v152 offset:23552
	global_load_lds_dwordx4 v[144:145], off
	s_add_i32 m0, s51, 0x2000
	s_add_u32 s68, s24, 0x80000
	v_lshl_add_u64 v[190:191], s[24:25], 0, v[134:135]
	s_addc_u32 s69, s25, 0
	s_add_i32 s51, s42, s30
	global_load_lds_dwordx4 v[190:191], off
	v_lshl_add_u64 v[222:223], s[68:69], 0, v[130:131]
	s_mov_b32 m0, s51
	v_lshl_add_u64 v[224:225], s[26:27], 0, v[132:133]
	global_load_lds_dwordx4 v[222:223], off
	v_lshl_add_u64 v[222:223], s[68:69], 0, v[134:135]
	s_add_i32 m0, s51, 0x2000
	s_nop 0
	global_load_lds_dwordx4 v[222:223], off
	v_lshl_add_u64 v[222:223], s[26:27], 0, v[128:129]
	s_mov_b32 m0, s21
	s_nop 0
	global_load_lds_dwordx4 v[222:223], off
	s_mov_b32 m0, s34
	s_nop 0
	global_load_lds_dwordx4 v[224:225], off
	s_waitcnt vmcnt(8) lgkmcnt(0)
	s_barrier
; #define PG8_STAGE(bufoff, gbase, voff) do { _Pragma("unroll") for (int _i = 0; _i < 2; ++_i) \
;         __builtin_amdgcn_global_load_lds((const unsigned*)((const char*)(gbase) + (voff)[_i]), (LAS unsigned*)(lds + (bufoff) + ldsw + _i * 8192), 16, 0, 0); } while (0)
; #define PG8_LDA(dst, b, h) do { _Pragma("unroll") for (int m = 0; m < 4; ++m) _Pragma("unroll") for (int k = 0; k < 2; ++k) dst[m][k] = *(const LAS bf16x8*)(lds + PG8_SA(b, h) + aoff + m * 2048 + k * 1024); } while (0)
; #define PG8_LDB(dst, b, h) do { _Pragma("unroll") for (int n = 0; n < 2; ++n) _Pragma("unroll") for (int k = 0; k < 2; ++k) dst[n][k] = *(const LAS bf16x8*)(lds + PG8_SB(b, h) + boff + n * 2048 + k * 1024); } while (0)
; #define PG8_MMA(ai, bj, At, Bt) do { __builtin_amdgcn_s_setprio(1); _Pragma("unroll") for (int m = 0; m < 4; ++m) _Pragma("unroll") for (int n = 0; n < 2; ++n) _Pragma("unroll") for (int k = 0; k < 2; ++k) \
;         acc[ai][bj][m][n] = __builtin_amdgcn_mfma_f32_16x16x32_bf16(Bt[n][k], At[m][k], acc[ai][bj][m][n], 0, 0, 0); __builtin_amdgcn_s_setprio(0); } while (0)
; #define PG8_WAIT_V(n) asm volatile("s_waitcnt vmcnt(" #n ")" ::: "memory")
; #define PG8_WAIT_L(n) asm volatile("s_waitcnt lgkmcnt(" #n ")" ::: "memory")
; #define PG8_BAR __builtin_amdgcn_s_barrier()
; #define PG8_SCHED __builtin_amdgcn_sched_barrier(0)
; template <class Epi, class Sched = StaticOrder, class EpiSub = NoSub, bool FAST = false>
; __device__ __forceinline__ void gemm_phase(LAS unsigned char* lds, const Gemm g, const Sched& S, const Epi& E, const EpiSub& ES = EpiSub()) {
;     ...
;             PG8_LDA(At, 0, 1); PG8_STAGE(PG8_SB(0, 0), b2, voffB); PG8_STAGE(PG8_SB(0, 1), b2 + hstepB, voffB); PG8_STAGE(PG8_SA(0, 0), a2, voffA);
;             PG8_WAIT_V(8); PG8_WAIT_L(0); PG8_BAR; PG8_MMA(1, 0, At, B0); PG8_MMA(1, 1, At, B1); PG8_BAR; PG8_SCHED;
;             PG8_LDB(B0, 1, 0); PG8_LDB(B1, 1, 1); PG8_SCHED; PG8_LDA(At, 1, 0); PG8_STAGE(PG8_SA(0, 1), a2 + hstepA, voffA);
;             PG8_WAIT_V(8); PG8_WAIT_L(0); PG8_BAR; PG8_MMA(0, 0, At, B0); PG8_MMA(0, 1, At, B1); PG8_BAR; PG8_SCHED;
	v_mfma_f32_16x16x32_bf16 v[60:63], v[154:157], v[186:189], 0
	v_mfma_f32_16x16x32_bf16 v[56:59], v[162:165], v[186:189], 0
	v_mfma_f32_16x16x32_bf16 v[52:55], v[154:157], v[198:201], 0
	v_mfma_f32_16x16x32_bf16 v[44:47], v[162:165], v[198:201], 0
	v_mfma_f32_16x16x32_bf16 v[36:39], v[154:157], v[206:209], 0
	v_mfma_f32_16x16x32_bf16 v[28:31], v[162:165], v[206:209], 0
	v_mfma_f32_16x16x32_bf16 v[20:23], v[154:157], v[214:217], 0
	v_mfma_f32_16x16x32_bf16 v[12:15], v[162:165], v[214:217], 0
	v_mfma_f32_16x16x32_bf16 v[60:63], v[158:161], v[194:197], v[60:63]
	v_mfma_f32_16x16x32_bf16 v[56:59], v[166:169], v[194:197], v[56:59]
	v_mfma_f32_16x16x32_bf16 v[52:55], v[158:161], v[202:205], v[52:55]
	v_mfma_f32_16x16x32_bf16 v[44:47], v[166:169], v[202:205], v[44:47]
	v_mfma_f32_16x16x32_bf16 v[36:39], v[158:161], v[210:213], v[36:39]
	v_mfma_f32_16x16x32_bf16 v[28:31], v[166:169], v[210:213], v[28:31]
	v_mfma_f32_16x16x32_bf16 v[20:23], v[158:161], v[218:221], v[20:23]
	v_mfma_f32_16x16x32_bf16 v[12:15], v[166:169], v[218:221], v[12:15]
	v_mfma_f32_16x16x32_bf16 v[48:51], v[170:173], v[186:189], 0
	v_mfma_f32_16x16x32_bf16 v[40:43], v[178:181], v[186:189], 0
	v_mfma_f32_16x16x32_bf16 v[32:35], v[170:173], v[198:201], 0
	v_mfma_f32_16x16x32_bf16 v[24:27], v[178:181], v[198:201], 0
	v_mfma_f32_16x16x32_bf16 v[16:19], v[170:173], v[206:209], 0
	v_mfma_f32_16x16x32_bf16 v[8:11], v[178:181], v[206:209], 0
	v_mfma_f32_16x16x32_bf16 v[4:7], v[170:173], v[214:217], 0
	v_mfma_f32_16x16x32_bf16 v[0:3], v[178:181], v[214:217], 0
	v_mfma_f32_16x16x32_bf16 v[48:51], v[174:177], v[194:197], v[48:51]
	v_mfma_f32_16x16x32_bf16 v[40:43], v[182:185], v[194:197], v[40:43]
	v_mfma_f32_16x16x32_bf16 v[32:35], v[174:177], v[202:205], v[32:35]
	v_mfma_f32_16x16x32_bf16 v[24:27], v[182:185], v[202:205], v[24:27]
	v_mfma_f32_16x16x32_bf16 v[16:19], v[174:177], v[210:213], v[16:19]
	v_mfma_f32_16x16x32_bf16 v[8:11], v[182:185], v[210:213], v[8:11]
	v_mfma_f32_16x16x32_bf16 v[4:7], v[174:177], v[218:221], v[4:7]
	v_mfma_f32_16x16x32_bf16 v[0:3], v[182:185], v[218:221], v[0:3]
	s_barrier
	s_add_i32 s51, 0, 0x18000
	v_add_u32_e32 v153, s51, v148
	s_add_i32 s68, 0, 0x1c000
	ds_read_b128 v[154:157], v153
	ds_read_b128 v[158:161], v153 offset:1024
	ds_read_b128 v[162:165], v153 offset:2048
	ds_read_b128 v[166:169], v153 offset:3072
	v_add_u32_e32 v153, s68, v148
	ds_read_b128 v[170:173], v153
	ds_read_b128 v[174:177], v153 offset:1024
	ds_read_b128 v[178:181], v153 offset:2048
	ds_read_b128 v[182:185], v153 offset:3072
	s_add_u32 s26, s26, 0x80000
	s_addc_u32 s27, s27, 0
	s_mov_b32 m0, s35
	v_lshl_add_u64 v[226:227], s[26:27], 0, v[128:129]
	ds_read_b128 v[186:189], v152 offset:32768
	ds_read_b128 v[194:197], v152 offset:33792
	ds_read_b128 v[198:201], v152 offset:34816
	ds_read_b128 v[202:205], v152 offset:35840
	ds_read_b128 v[206:209], v152 offset:36864
	ds_read_b128 v[210:213], v152 offset:37888
	ds_read_b128 v[214:217], v152 offset:38912
	ds_read_b128 v[218:221], v152 offset:39936
	global_load_lds_dwordx4 v[226:227], off
	v_lshl_add_u64 v[226:227], s[26:27], 0, v[132:133]
	s_mov_b32 m0, s36
	s_nop 0
	global_load_lds_dwordx4 v[226:227], off
	s_waitcnt vmcnt(8) lgkmcnt(0)
	s_barrier
	v_mfma_f32_16x16x32_bf16 v[124:127], v[154:157], v[186:189], v[124:127]
	v_mfma_f32_16x16x32_bf16 v[120:123], v[162:165], v[186:189], v[120:123]
	v_mfma_f32_16x16x32_bf16 v[116:119], v[154:157], v[198:201], v[116:119]
	v_mfma_f32_16x16x32_bf16 v[108:111], v[162:165], v[198:201], v[108:111]
	v_mfma_f32_16x16x32_bf16 v[100:103], v[154:157], v[206:209], v[100:103]
	v_mfma_f32_16x16x32_bf16 v[92:95], v[162:165], v[206:209], v[92:95]
	v_mfma_f32_16x16x32_bf16 v[84:87], v[154:157], v[214:217], v[84:87]
	v_mfma_f32_16x16x32_bf16 v[76:79], v[162:165], v[214:217], v[76:79]
	v_mfma_f32_16x16x32_bf16 v[124:127], v[158:161], v[194:197], v[124:127]
	v_mfma_f32_16x16x32_bf16 v[120:123], v[166:169], v[194:197], v[120:123]
	v_mfma_f32_16x16x32_bf16 v[116:119], v[158:161], v[202:205], v[116:119]
	v_mfma_f32_16x16x32_bf16 v[108:111], v[166:169], v[202:205], v[108:111]
	v_mfma_f32_16x16x32_bf16 v[100:103], v[158:161], v[210:213], v[100:103]
	v_mfma_f32_16x16x32_bf16 v[92:95], v[166:169], v[210:213], v[92:95]
	v_mfma_f32_16x16x32_bf16 v[84:87], v[158:161], v[218:221], v[84:87]
	v_mfma_f32_16x16x32_bf16 v[76:79], v[166:169], v[218:221], v[76:79]
	v_mfma_f32_16x16x32_bf16 v[112:115], v[170:173], v[186:189], v[112:115]
	v_mfma_f32_16x16x32_bf16 v[104:107], v[178:181], v[186:189], v[104:107]
	v_mfma_f32_16x16x32_bf16 v[96:99], v[170:173], v[198:201], v[96:99]
	v_mfma_f32_16x16x32_bf16 v[88:91], v[178:181], v[198:201], v[88:91]
	v_mfma_f32_16x16x32_bf16 v[80:83], v[170:173], v[206:209], v[80:83]
	v_mfma_f32_16x16x32_bf16 v[72:75], v[178:181], v[206:209], v[72:75]
	v_mfma_f32_16x16x32_bf16 v[68:71], v[170:173], v[214:217], v[68:71]
	v_mfma_f32_16x16x32_bf16 v[64:67], v[178:181], v[214:217], v[64:67]
	v_mfma_f32_16x16x32_bf16 v[112:115], v[174:177], v[194:197], v[112:115]
	v_mfma_f32_16x16x32_bf16 v[104:107], v[182:185], v[194:197], v[104:107]
	v_mfma_f32_16x16x32_bf16 v[96:99], v[174:177], v[202:205], v[96:99]
	v_mfma_f32_16x16x32_bf16 v[88:91], v[182:185], v[202:205], v[88:91]
	v_mfma_f32_16x16x32_bf16 v[80:83], v[174:177], v[210:213], v[80:83]
	v_mfma_f32_16x16x32_bf16 v[72:75], v[182:185], v[210:213], v[72:75]
	v_mfma_f32_16x16x32_bf16 v[68:71], v[174:177], v[218:221], v[68:71]
	v_mfma_f32_16x16x32_bf16 v[64:67], v[182:185], v[218:221], v[64:67]
	s_barrier
; #define PG8_STAGE(bufoff, gbase, voff) do { _Pragma("unroll") for (int _i = 0; _i < 2; ++_i) \
;         __builtin_amdgcn_global_load_lds((const unsigned*)((const char*)(gbase) + (voff)[_i]), (LAS unsigned*)(lds + (bufoff) + ldsw + _i * 8192), 16, 0, 0); } while (0)
; #define PG8_LDA(dst, b, h) do { _Pragma("unroll") for (int m = 0; m < 4; ++m) _Pragma("unroll") for (int k = 0; k < 2; ++k) dst[m][k] = *(const LAS bf16x8*)(lds + PG8_SA(b, h) + aoff + m * 2048 + k * 1024); } while (0)
; #define PG8_LDB(dst, b, h) do { _Pragma("unroll") for (int n = 0; n < 2; ++n) _Pragma("unroll") for (int k = 0; k < 2; ++k) dst[n][k] = *(const LAS bf16x8*)(lds + PG8_SB(b, h) + boff + n * 2048 + k * 1024); } while (0)
; template <class Epi, class Sched = StaticOrder, class EpiSub = NoSub, bool FAST = false>
; __device__ __forceinline__ void gemm_phase(LAS unsigned char* lds, const Gemm g, const Sched& S, const Epi& E, const EpiSub& ES = EpiSub()) {
;     ...
;         for (int t = 0; t < nt; t += 2) {
;             const bool last = (t == nt - 2);
;             const char* a1 = cA + (size_t)(t + 1) * kstep;
;             const char* a2 = last ? nA : cA + (size_t)(t + 2) * kstep; const char* b2 = last ? nB : cB + (size_t)(t + 2) * kstep;
;             const char* a3 = a2 + kstep; const char* b3 = b2 + kstep;
;             if constexpr (FAST && PG8_SP2) {
;             PG8_LDB(B0, 0, 0); PG8_LDB(B1, 0, 1); PG8_SCHED; PG8_LDA(At, 0, 0); PG8_STAGE(PG8_SA(1, 1), a1 + hstepA, voffA);
;             PG8_WAIT_V(8); PG8_WAIT_L(0); PG8_BAR; PG8_MMA(0, 0, At, B0); PG8_MMA(0, 1, At, B1); PG8_BAR; PG8_SCHED;
;             PG8_LDA(At, 0, 1); PG8_STAGE(PG8_SB(0, 0), b2, voffB); PG8_STAGE(PG8_SB(0, 1), b2 + hstepB, voffB); PG8_STAGE(PG8_SA(0, 0), a2, voffA);
;             PG8_WAIT_V(8); PG8_WAIT_L(0); PG8_BAR; PG8_MMA(1, 0, At, B0); PG8_MMA(1, 1, At, B1); PG8_BAR; PG8_SCHED;
;             PG8_LDB(B0, 1, 0); PG8_LDB(B1, 1, 1); PG8_SCHED; PG8_LDA(At, 1, 0); PG8_STAGE(PG8_SA(0, 1), a2 + hstepA, voffA);
;             PG8_WAIT_V(8); PG8_WAIT_L(0); PG8_BAR; PG8_MMA(0, 0, At, B0); PG8_MMA(0, 1, At, B1); PG8_BAR; PG8_SCHED;
;             PG8_LDA(At, 1, 1); PG8_STAGE(PG8_SB(1, 0), b3, voffB); PG8_STAGE(PG8_SB(1, 1), b3 + hstepB, voffB); PG8_STAGE(PG8_SA(1, 0), a3, voffA);
;             PG8_WAIT_V(8); PG8_WAIT_L(0); PG8_BAR; PG8_MMA(1, 0, At, B0); PG8_MMA(1, 1, At, B1); PG8_BAR; PG8_SCHED;
	s_add_i32 s26, s51, s30
	v_lshl_add_u64 v[144:145], v[144:145], 0, s[8:9]
	s_mov_b32 m0, s26
	ds_read_b128 v[186:189], v152 offset:49152
	ds_read_b128 v[194:197], v152 offset:50176
	ds_read_b128 v[198:201], v152 offset:51200
	ds_read_b128 v[202:205], v152 offset:52224
	ds_read_b128 v[206:209], v152 offset:53248
	ds_read_b128 v[210:213], v152 offset:54272
	ds_read_b128 v[214:217], v152 offset:55296
	ds_read_b128 v[218:221], v152 offset:56320
	global_load_lds_dwordx4 v[144:145], off
	s_add_i32 m0, s26, 0x2000
	s_add_u32 s24, s24, 0x80080
	v_lshl_add_u64 v[144:145], v[190:191], 0, s[8:9]
	s_addc_u32 s25, s25, 0
	s_add_i32 s26, s68, s30
	global_load_lds_dwordx4 v[144:145], off
	v_lshl_add_u64 v[144:145], s[24:25], 0, v[130:131]
	s_mov_b32 m0, s26
	s_nop 0
	global_load_lds_dwordx4 v[144:145], off
	v_lshl_add_u64 v[144:145], s[24:25], 0, v[134:135]
	s_add_i32 m0, s26, 0x2000
	s_nop 0
	global_load_lds_dwordx4 v[144:145], off
	v_lshl_add_u64 v[144:145], v[222:223], 0, s[8:9]
	s_mov_b32 m0, s39
	s_nop 0
	global_load_lds_dwordx4 v[144:145], off
	v_lshl_add_u64 v[144:145], v[224:225], 0, s[8:9]
	s_mov_b32 m0, s40
	s_nop 0
	global_load_lds_dwordx4 v[144:145], off
	s_waitcnt vmcnt(8) lgkmcnt(0)
	s_barrier
	v_mfma_f32_16x16x32_bf16 v[60:63], v[154:157], v[186:189], v[60:63]
	v_mfma_f32_16x16x32_bf16 v[56:59], v[162:165], v[186:189], v[56:59]
	v_mfma_f32_16x16x32_bf16 v[52:55], v[154:157], v[198:201], v[52:55]
	v_mfma_f32_16x16x32_bf16 v[44:47], v[162:165], v[198:201], v[44:47]
	v_mfma_f32_16x16x32_bf16 v[36:39], v[154:157], v[206:209], v[36:39]
	v_mfma_f32_16x16x32_bf16 v[28:31], v[162:165], v[206:209], v[28:31]
	v_mfma_f32_16x16x32_bf16 v[20:23], v[154:157], v[214:217], v[20:23]
	v_mfma_f32_16x16x32_bf16 v[12:15], v[162:165], v[214:217], v[12:15]
	v_mfma_f32_16x16x32_bf16 v[60:63], v[158:161], v[194:197], v[60:63]
	v_mfma_f32_16x16x32_bf16 v[56:59], v[166:169], v[194:197], v[56:59]
	v_mfma_f32_16x16x32_bf16 v[52:55], v[158:161], v[202:205], v[52:55]
	v_mfma_f32_16x16x32_bf16 v[44:47], v[166:169], v[202:205], v[44:47]
	v_mfma_f32_16x16x32_bf16 v[36:39], v[158:161], v[210:213], v[36:39]
	v_mfma_f32_16x16x32_bf16 v[28:31], v[166:169], v[210:213], v[28:31]
	v_mfma_f32_16x16x32_bf16 v[20:23], v[158:161], v[218:221], v[20:23]
	v_mfma_f32_16x16x32_bf16 v[12:15], v[166:169], v[218:221], v[12:15]
	v_mfma_f32_16x16x32_bf16 v[48:51], v[170:173], v[186:189], v[48:51]
	v_mfma_f32_16x16x32_bf16 v[40:43], v[178:181], v[186:189], v[40:43]
	v_mfma_f32_16x16x32_bf16 v[32:35], v[170:173], v[198:201], v[32:35]
	v_mfma_f32_16x16x32_bf16 v[24:27], v[178:181], v[198:201], v[24:27]
	v_mfma_f32_16x16x32_bf16 v[16:19], v[170:173], v[206:209], v[16:19]
	v_mfma_f32_16x16x32_bf16 v[8:11], v[178:181], v[206:209], v[8:11]
	v_mfma_f32_16x16x32_bf16 v[4:7], v[170:173], v[214:217], v[4:7]
	v_mfma_f32_16x16x32_bf16 v[0:3], v[178:181], v[214:217], v[0:3]
	v_mfma_f32_16x16x32_bf16 v[48:51], v[174:177], v[194:197], v[48:51]
	v_mfma_f32_16x16x32_bf16 v[40:43], v[182:185], v[194:197], v[40:43]
	v_mfma_f32_16x16x32_bf16 v[32:35], v[174:177], v[202:205], v[32:35]
	v_mfma_f32_16x16x32_bf16 v[24:27], v[182:185], v[202:205], v[24:27]
	v_mfma_f32_16x16x32_bf16 v[16:19], v[174:177], v[210:213], v[16:19]
	v_mfma_f32_16x16x32_bf16 v[8:11], v[182:185], v[210:213], v[8:11]
	v_mfma_f32_16x16x32_bf16 v[4:7], v[174:177], v[218:221], v[4:7]
	v_mfma_f32_16x16x32_bf16 v[0:3], v[182:185], v[218:221], v[0:3]
	s_barrier
	s_add_i32 s50, s50, 2
	s_add_u32 s22, s22, 0x100
	s_addc_u32 s23, s23, 0
	s_add_u32 s48, s48, 0x100
	s_addc_u32 s49, s49, 0
	s_cmp_gt_u32 s50, 29
	s_cbranch_scc1 .Lkpeel_216_exit
.LBB0_216:
	ds_read_b128 v[154:157], v150
	ds_read_b128 v[158:161], v150 offset:1024
	ds_read_b128 v[162:165], v150 offset:2048
	ds_read_b128 v[166:169], v150 offset:3072
	ds_read_b128 v[170:173], v151
	ds_read_b128 v[174:177], v151 offset:1024
	ds_read_b128 v[178:181], v151 offset:2048
	ds_read_b128 v[182:185], v151 offset:3072
	s_add_u32 s24, s22, 0xfff80080
	s_addc_u32 s25, s23, -1
	s_cmp_eq_u32 s50, 28
	s_cselect_b32 s27, s2, s25
	s_cselect_b32 s26, s3, s24
	s_cselect_b32 s25, s13, s49
	s_cselect_b32 s24, s15, s48
	v_lshl_add_u64 v[144:145], s[22:23], 0, v[136:137]
	s_add_i32 m0, s21, 0xc000
	ds_read_b128 v[186:189], v152
	ds_read_b128 v[194:197], v152 offset:1024
	ds_read_b128 v[198:201], v152 offset:2048
	ds_read_b128 v[202:205], v152 offset:3072
	ds_read_b128 v[206:209], v152 offset:4096
	ds_read_b128 v[210:213], v152 offset:5120
	ds_read_b128 v[214:217], v152 offset:6144
	ds_read_b128 v[218:221], v152 offset:7168
	global_load_lds_dwordx4 v[144:145], off
	v_lshl_add_u64 v[144:145], s[22:23], 0, v[138:139]
	s_add_i32 m0, s21, 0xe000
	s_nop 0
	global_load_lds_dwordx4 v[144:145], off
	s_waitcnt vmcnt(8) lgkmcnt(0)
	s_barrier
; #define PG8_STAGE(bufoff, gbase, voff) do { _Pragma("unroll") for (int _i = 0; _i < 2; ++_i) \
;         __builtin_amdgcn_global_load_lds((const unsigned*)((const char*)(gbase) + (voff)[_i]), (LAS unsigned*)(lds + (bufoff) + ldsw + _i * 8192), 16, 0, 0); } while (0)
; #define PG8_LDA(dst, b, h) do { _Pragma("unroll") for (int m = 0; m < 4; ++m) _Pragma("unroll") for (int k = 0; k < 2; ++k) dst[m][k] = *(const LAS bf16x8*)(lds + PG8_SA(b, h) + aoff + m * 2048 + k * 1024); } while (0)
; #define PG8_LDB(dst, b, h) do { _Pragma("unroll") for (int n = 0; n < 2; ++n) _Pragma("unroll") for (int k = 0; k < 2; ++k) dst[n][k] = *(const LAS bf16x8*)(lds + PG8_SB(b, h) + boff + n * 2048 + k * 1024); } while (0)
; #define PG8_MMA(ai, bj, At, Bt) do { __builtin_amdgcn_s_setprio(1); _Pragma("unroll") for (int m = 0; m < 4; ++m) _Pragma("unroll") for (int n = 0; n < 2; ++n) _Pragma("unroll") for (int k = 0; k < 2; ++k) \
;         acc[ai][bj][m][n] = __builtin_amdgcn_mfma_f32_16x16x32_bf16(Bt[n][k], At[m][k], acc[ai][bj][m][n], 0, 0, 0); __builtin_amdgcn_s_setprio(0); } while (0)
; #define PG8_WAIT_V(n) asm volatile("s_waitcnt vmcnt(" #n ")" ::: "memory")
; #define PG8_WAIT_L(n) asm volatile("s_waitcnt lgkmcnt(" #n ")" ::: "memory")
; #define PG8_BAR __builtin_amdgcn_s_barrier()
; #define PG8_SCHED __builtin_amdgcn_sched_barrier(0)
; template <class Epi, class Sched = StaticOrder, class EpiSub = NoSub, bool FAST = false>
; __device__ __forceinline__ void gemm_phase(LAS unsigned char* lds, const Gemm g, const Sched& S, const Epi& E, const EpiSub& ES = EpiSub()) {
;     ...
;             PG8_LDB(B0, 0, 0); PG8_LDB(B1, 0, 1); PG8_SCHED; PG8_LDA(At, 0, 0); PG8_STAGE(PG8_SA(1, 1), a1 + hstepA, voffA);
;             PG8_WAIT_V(8); PG8_WAIT_L(0); PG8_BAR; PG8_MMA(0, 0, At, B0); PG8_MMA(0, 1, At, B1); PG8_BAR; PG8_SCHED;
;             PG8_LDA(At, 0, 1); PG8_STAGE(PG8_SB(0, 0), b2, voffB); PG8_STAGE(PG8_SB(0, 1), b2 + hstepB, voffB); PG8_STAGE(PG8_SA(0, 0), a2, voffA);
;             PG8_WAIT_V(8); PG8_WAIT_L(0); PG8_BAR; PG8_MMA(1, 0, At, B0); PG8_MMA(1, 1, At, B1); PG8_BAR; PG8_SCHED;
	v_mfma_f32_16x16x32_bf16 v[124:127], v[154:157], v[186:189], v[124:127]
	v_mfma_f32_16x16x32_bf16 v[120:123], v[162:165], v[186:189], v[120:123]
	v_mfma_f32_16x16x32_bf16 v[116:119], v[154:157], v[198:201], v[116:119]
	v_mfma_f32_16x16x32_bf16 v[108:111], v[162:165], v[198:201], v[108:111]
	v_mfma_f32_16x16x32_bf16 v[100:103], v[154:157], v[206:209], v[100:103]
	v_mfma_f32_16x16x32_bf16 v[92:95], v[162:165], v[206:209], v[92:95]
	v_mfma_f32_16x16x32_bf16 v[84:87], v[154:157], v[214:217], v[84:87]
	v_mfma_f32_16x16x32_bf16 v[76:79], v[162:165], v[214:217], v[76:79]
	v_mfma_f32_16x16x32_bf16 v[124:127], v[158:161], v[194:197], v[124:127]
	v_mfma_f32_16x16x32_bf16 v[120:123], v[166:169], v[194:197], v[120:123]
	v_mfma_f32_16x16x32_bf16 v[116:119], v[158:161], v[202:205], v[116:119]
	v_mfma_f32_16x16x32_bf16 v[108:111], v[166:169], v[202:205], v[108:111]
	v_mfma_f32_16x16x32_bf16 v[100:103], v[158:161], v[210:213], v[100:103]
	v_mfma_f32_16x16x32_bf16 v[92:95], v[166:169], v[210:213], v[92:95]
	v_mfma_f32_16x16x32_bf16 v[84:87], v[158:161], v[218:221], v[84:87]
	v_mfma_f32_16x16x32_bf16 v[76:79], v[166:169], v[218:221], v[76:79]
	v_mfma_f32_16x16x32_bf16 v[112:115], v[170:173], v[186:189], v[112:115]
	v_mfma_f32_16x16x32_bf16 v[104:107], v[178:181], v[186:189], v[104:107]
	v_mfma_f32_16x16x32_bf16 v[96:99], v[170:173], v[198:201], v[96:99]
	v_mfma_f32_16x16x32_bf16 v[88:91], v[178:181], v[198:201], v[88:91]
	v_mfma_f32_16x16x32_bf16 v[80:83], v[170:173], v[206:209], v[80:83]
	v_mfma_f32_16x16x32_bf16 v[72:75], v[178:181], v[206:209], v[72:75]
	v_mfma_f32_16x16x32_bf16 v[68:71], v[170:173], v[214:217], v[68:71]
	v_mfma_f32_16x16x32_bf16 v[64:67], v[178:181], v[214:217], v[64:67]
	v_mfma_f32_16x16x32_bf16 v[112:115], v[174:177], v[194:197], v[112:115]
	v_mfma_f32_16x16x32_bf16 v[104:107], v[182:185], v[194:197], v[104:107]
	v_mfma_f32_16x16x32_bf16 v[96:99], v[174:177], v[202:205], v[96:99]
	v_mfma_f32_16x16x32_bf16 v[88:91], v[182:185], v[202:205], v[88:91]
	v_mfma_f32_16x16x32_bf16 v[80:83], v[174:177], v[210:213], v[80:83]
	v_mfma_f32_16x16x32_bf16 v[72:75], v[182:185], v[210:213], v[72:75]
	v_mfma_f32_16x16x32_bf16 v[68:71], v[174:177], v[218:221], v[68:71]
	v_mfma_f32_16x16x32_bf16 v[64:67], v[182:185], v[218:221], v[64:67]
	s_barrier
	s_add_i32 s51, s41, s30
	v_lshl_add_u64 v[144:145], s[24:25], 0, v[130:131]
	s_mov_b32 m0, s51
	ds_read_b128 v[186:189], v152 offset:16384
	ds_read_b128 v[194:197], v152 offset:17408
	ds_read_b128 v[198:201], v152 offset:18432
	ds_read_b128 v[202:205], v152 offset:19456
	ds_read_b128 v[206:209], v152 offset:20480
	ds_read_b128 v[210:213], v152 offset:21504
	ds_read_b128 v[214:217], v152 offset:22528
	ds_read_b128 v[218:221], v152 offset:23552
	global_load_lds_dwordx4 v[144:145], off
	s_add_i32 m0, s51, 0x2000
	s_add_u32 s68, s24, 0x80000
	v_lshl_add_u64 v[190:191], s[24:25], 0, v[134:135]
	s_addc_u32 s69, s25, 0
	s_add_i32 s51, s42, s30
	global_load_lds_dwordx4 v[190:191], off
	v_lshl_add_u64 v[222:223], s[68:69], 0, v[130:131]
	s_mov_b32 m0, s51
	v_lshl_add_u64 v[224:225], s[26:27], 0, v[132:133]
	global_load_lds_dwordx4 v[222:223], off
	v_lshl_add_u64 v[222:223], s[68:69], 0, v[134:135]
	s_add_i32 m0, s51, 0x2000
	s_nop 0
	global_load_lds_dwordx4 v[222:223], off
	v_lshl_add_u64 v[222:223], s[26:27], 0, v[128:129]
	s_mov_b32 m0, s21
	s_nop 0
	global_load_lds_dwordx4 v[222:223], off
	s_mov_b32 m0, s34
	s_nop 0
	global_load_lds_dwordx4 v[224:225], off
	s_waitcnt vmcnt(8) lgkmcnt(0)
	s_barrier
	v_mfma_f32_16x16x32_bf16 v[60:63], v[154:157], v[186:189], v[60:63]
	v_mfma_f32_16x16x32_bf16 v[56:59], v[162:165], v[186:189], v[56:59]
	v_mfma_f32_16x16x32_bf16 v[52:55], v[154:157], v[198:201], v[52:55]
	v_mfma_f32_16x16x32_bf16 v[44:47], v[162:165], v[198:201], v[44:47]
	v_mfma_f32_16x16x32_bf16 v[36:39], v[154:157], v[206:209], v[36:39]
	v_mfma_f32_16x16x32_bf16 v[28:31], v[162:165], v[206:209], v[28:31]
	v_mfma_f32_16x16x32_bf16 v[20:23], v[154:157], v[214:217], v[20:23]
	v_mfma_f32_16x16x32_bf16 v[12:15], v[162:165], v[214:217], v[12:15]
	v_mfma_f32_16x16x32_bf16 v[60:63], v[158:161], v[194:197], v[60:63]
	v_mfma_f32_16x16x32_bf16 v[56:59], v[166:169], v[194:197], v[56:59]
	v_mfma_f32_16x16x32_bf16 v[52:55], v[158:161], v[202:205], v[52:55]
	v_mfma_f32_16x16x32_bf16 v[44:47], v[166:169], v[202:205], v[44:47]
	v_mfma_f32_16x16x32_bf16 v[36:39], v[158:161], v[210:213], v[36:39]
	v_mfma_f32_16x16x32_bf16 v[28:31], v[166:169], v[210:213], v[28:31]
	v_mfma_f32_16x16x32_bf16 v[20:23], v[158:161], v[218:221], v[20:23]
	v_mfma_f32_16x16x32_bf16 v[12:15], v[166:169], v[218:221], v[12:15]
	v_mfma_f32_16x16x32_bf16 v[48:51], v[170:173], v[186:189], v[48:51]
	v_mfma_f32_16x16x32_bf16 v[40:43], v[178:181], v[186:189], v[40:43]
	v_mfma_f32_16x16x32_bf16 v[32:35], v[170:173], v[198:201], v[32:35]
	v_mfma_f32_16x16x32_bf16 v[24:27], v[178:181], v[198:201], v[24:27]
	v_mfma_f32_16x16x32_bf16 v[16:19], v[170:173], v[206:209], v[16:19]
	v_mfma_f32_16x16x32_bf16 v[8:11], v[178:181], v[206:209], v[8:11]
	v_mfma_f32_16x16x32_bf16 v[4:7], v[170:173], v[214:217], v[4:7]
	v_mfma_f32_16x16x32_bf16 v[0:3], v[178:181], v[214:217], v[0:3]
	v_mfma_f32_16x16x32_bf16 v[48:51], v[174:177], v[194:197], v[48:51]
	v_mfma_f32_16x16x32_bf16 v[40:43], v[182:185], v[194:197], v[40:43]
	v_mfma_f32_16x16x32_bf16 v[32:35], v[174:177], v[202:205], v[32:35]
	v_mfma_f32_16x16x32_bf16 v[24:27], v[182:185], v[202:205], v[24:27]
	v_mfma_f32_16x16x32_bf16 v[16:19], v[174:177], v[210:213], v[16:19]
	v_mfma_f32_16x16x32_bf16 v[8:11], v[182:185], v[210:213], v[8:11]
	v_mfma_f32_16x16x32_bf16 v[4:7], v[174:177], v[218:221], v[4:7]
	v_mfma_f32_16x16x32_bf16 v[0:3], v[182:185], v[218:221], v[0:3]
	s_barrier
; #define PG8_STAGE(bufoff, gbase, voff) do { _Pragma("unroll") for (int _i = 0; _i < 2; ++_i) \
;         __builtin_amdgcn_global_load_lds((const unsigned*)((const char*)(gbase) + (voff)[_i]), (LAS unsigned*)(lds + (bufoff) + ldsw + _i * 8192), 16, 0, 0); } while (0)
; #define PG8_LDA(dst, b, h) do { _Pragma("unroll") for (int m = 0; m < 4; ++m) _Pragma("unroll") for (int k = 0; k < 2; ++k) dst[m][k] = *(const LAS bf16x8*)(lds + PG8_SA(b, h) + aoff + m * 2048 + k * 1024); } while (0)
; #define PG8_LDB(dst, b, h) do { _Pragma("unroll") for (int n = 0; n < 2; ++n) _Pragma("unroll") for (int k = 0; k < 2; ++k) dst[n][k] = *(const LAS bf16x8*)(lds + PG8_SB(b, h) + boff + n * 2048 + k * 1024); } while (0)
; #define PG8_MMA(ai, bj, At, Bt) do { __builtin_amdgcn_s_setprio(1); _Pragma("unroll") for (int m = 0; m < 4; ++m) _Pragma("unroll") for (int n = 0; n < 2; ++n) _Pragma("unroll") for (int k = 0; k < 2; ++k) \
;         acc[ai][bj][m][n] = __builtin_amdgcn_mfma_f32_16x16x32_bf16(Bt[n][k], At[m][k], acc[ai][bj][m][n], 0, 0, 0); __builtin_amdgcn_s_setprio(0); } while (0)
; #define PG8_WAIT_V(n) asm volatile("s_waitcnt vmcnt(" #n ")" ::: "memory")
; #define PG8_WAIT_L(n) asm volatile("s_waitcnt lgkmcnt(" #n ")" ::: "memory")
; #define PG8_BAR __builtin_amdgcn_s_barrier()
; #define PG8_SCHED __builtin_amdgcn_sched_barrier(0)
; template <class Epi, class Sched = StaticOrder, class EpiSub = NoSub, bool FAST = false>
; __device__ __forceinline__ void gemm_phase(LAS unsigned char* lds, const Gemm g, const Sched& S, const Epi& E, const EpiSub& ES = EpiSub()) {
;     ...
;             PG8_LDB(B0, 1, 0); PG8_LDB(B1, 1, 1); PG8_SCHED; PG8_LDA(At, 1, 0); PG8_STAGE(PG8_SA(0, 1), a2 + hstepA, voffA);
;             PG8_WAIT_V(8); PG8_WAIT_L(0); PG8_BAR; PG8_MMA(0, 0, At, B0); PG8_MMA(0, 1, At, B1); PG8_BAR; PG8_SCHED;
;             PG8_LDA(At, 1, 1); PG8_STAGE(PG8_SB(1, 0), b3, voffB); PG8_STAGE(PG8_SB(1, 1), b3 + hstepB, voffB); PG8_STAGE(PG8_SA(1, 0), a3, voffA);
;             PG8_WAIT_V(8); PG8_WAIT_L(0); PG8_BAR; PG8_MMA(1, 0, At, B0); PG8_MMA(1, 1, At, B1); PG8_BAR; PG8_SCHED;
	s_add_i32 s51, 0, 0x18000
	v_add_u32_e32 v153, s51, v148
	s_add_i32 s68, 0, 0x1c000
	ds_read_b128 v[154:157], v153
	ds_read_b128 v[158:161], v153 offset:1024
	ds_read_b128 v[162:165], v153 offset:2048
	ds_read_b128 v[166:169], v153 offset:3072
	v_add_u32_e32 v153, s68, v148
	ds_read_b128 v[170:173], v153
	ds_read_b128 v[174:177], v153 offset:1024
	ds_read_b128 v[178:181], v153 offset:2048
	ds_read_b128 v[182:185], v153 offset:3072
	s_add_u32 s26, s26, 0x80000
	s_addc_u32 s27, s27, 0
	s_mov_b32 m0, s35
	v_lshl_add_u64 v[226:227], s[26:27], 0, v[128:129]
	ds_read_b128 v[186:189], v152 offset:32768
	ds_read_b128 v[194:197], v152 offset:33792
	ds_read_b128 v[198:201], v152 offset:34816
	ds_read_b128 v[202:205], v152 offset:35840
	ds_read_b128 v[206:209], v152 offset:36864
	ds_read_b128 v[210:213], v152 offset:37888
	ds_read_b128 v[214:217], v152 offset:38912
	ds_read_b128 v[218:221], v152 offset:39936
	global_load_lds_dwordx4 v[226:227], off
	v_lshl_add_u64 v[226:227], s[26:27], 0, v[132:133]
	s_mov_b32 m0, s36
	s_nop 0
	global_load_lds_dwordx4 v[226:227], off
	s_waitcnt vmcnt(8) lgkmcnt(0)
	s_barrier
	v_mfma_f32_16x16x32_bf16 v[124:127], v[154:157], v[186:189], v[124:127]
	v_mfma_f32_16x16x32_bf16 v[120:123], v[162:165], v[186:189], v[120:123]
	v_mfma_f32_16x16x32_bf16 v[116:119], v[154:157], v[198:201], v[116:119]
	v_mfma_f32_16x16x32_bf16 v[108:111], v[162:165], v[198:201], v[108:111]
	v_mfma_f32_16x16x32_bf16 v[100:103], v[154:157], v[206:209], v[100:103]
	v_mfma_f32_16x16x32_bf16 v[92:95], v[162:165], v[206:209], v[92:95]
	v_mfma_f32_16x16x32_bf16 v[84:87], v[154:157], v[214:217], v[84:87]
	v_mfma_f32_16x16x32_bf16 v[76:79], v[162:165], v[214:217], v[76:79]
	v_mfma_f32_16x16x32_bf16 v[124:127], v[158:161], v[194:197], v[124:127]
	v_mfma_f32_16x16x32_bf16 v[120:123], v[166:169], v[194:197], v[120:123]
	v_mfma_f32_16x16x32_bf16 v[116:119], v[158:161], v[202:205], v[116:119]
	v_mfma_f32_16x16x32_bf16 v[108:111], v[166:169], v[202:205], v[108:111]
	v_mfma_f32_16x16x32_bf16 v[100:103], v[158:161], v[210:213], v[100:103]
	v_mfma_f32_16x16x32_bf16 v[92:95], v[166:169], v[210:213], v[92:95]
	v_mfma_f32_16x16x32_bf16 v[84:87], v[158:161], v[218:221], v[84:87]
	v_mfma_f32_16x16x32_bf16 v[76:79], v[166:169], v[218:221], v[76:79]
	v_mfma_f32_16x16x32_bf16 v[112:115], v[170:173], v[186:189], v[112:115]
	v_mfma_f32_16x16x32_bf16 v[104:107], v[178:181], v[186:189], v[104:107]
	v_mfma_f32_16x16x32_bf16 v[96:99], v[170:173], v[198:201], v[96:99]
	v_mfma_f32_16x16x32_bf16 v[88:91], v[178:181], v[198:201], v[88:91]
	v_mfma_f32_16x16x32_bf16 v[80:83], v[170:173], v[206:209], v[80:83]
	v_mfma_f32_16x16x32_bf16 v[72:75], v[178:181], v[206:209], v[72:75]
	v_mfma_f32_16x16x32_bf16 v[68:71], v[170:173], v[214:217], v[68:71]
	v_mfma_f32_16x16x32_bf16 v[64:67], v[178:181], v[214:217], v[64:67]
	v_mfma_f32_16x16x32_bf16 v[112:115], v[174:177], v[194:197], v[112:115]
	v_mfma_f32_16x16x32_bf16 v[104:107], v[182:185], v[194:197], v[104:107]
	v_mfma_f32_16x16x32_bf16 v[96:99], v[174:177], v[202:205], v[96:99]
	v_mfma_f32_16x16x32_bf16 v[88:91], v[182:185], v[202:205], v[88:91]
	v_mfma_f32_16x16x32_bf16 v[80:83], v[174:177], v[210:213], v[80:83]
	v_mfma_f32_16x16x32_bf16 v[72:75], v[182:185], v[210:213], v[72:75]
	v_mfma_f32_16x16x32_bf16 v[68:71], v[174:177], v[218:221], v[68:71]
	v_mfma_f32_16x16x32_bf16 v[64:67], v[182:185], v[218:221], v[64:67]
	s_barrier
	s_add_i32 s26, s51, s30
	v_lshl_add_u64 v[144:145], v[144:145], 0, s[8:9]
	s_mov_b32 m0, s26
	ds_read_b128 v[186:189], v152 offset:49152
	ds_read_b128 v[194:197], v152 offset:50176
	ds_read_b128 v[198:201], v152 offset:51200
	ds_read_b128 v[202:205], v152 offset:52224
	ds_read_b128 v[206:209], v152 offset:53248
	ds_read_b128 v[210:213], v152 offset:54272
	ds_read_b128 v[214:217], v152 offset:55296
	ds_read_b128 v[218:221], v152 offset:56320
	global_load_lds_dwordx4 v[144:145], off
	s_add_i32 m0, s26, 0x2000
	s_add_u32 s24, s24, 0x80080
	v_lshl_add_u64 v[144:145], v[190:191], 0, s[8:9]
	s_addc_u32 s25, s25, 0
	s_add_i32 s26, s68, s30
	global_load_lds_dwordx4 v[144:145], off
	v_lshl_add_u64 v[144:145], s[24:25], 0, v[130:131]
	s_mov_b32 m0, s26
	s_nop 0
	global_load_lds_dwordx4 v[144:145], off
	v_lshl_add_u64 v[144:145], s[24:25], 0, v[134:135]
	s_add_i32 m0, s26, 0x2000
	s_nop 0
	global_load_lds_dwordx4 v[144:145], off
	v_lshl_add_u64 v[144:145], v[222:223], 0, s[8:9]
	s_mov_b32 m0, s39
	s_nop 0
	global_load_lds_dwordx4 v[144:145], off
	v_lshl_add_u64 v[144:145], v[224:225], 0, s[8:9]
	s_mov_b32 m0, s40
	s_nop 0
	global_load_lds_dwordx4 v[144:145], off
	s_waitcnt vmcnt(8) lgkmcnt(0)
	s_barrier
	v_mfma_f32_16x16x32_bf16 v[60:63], v[154:157], v[186:189], v[60:63]
	v_mfma_f32_16x16x32_bf16 v[56:59], v[162:165], v[186:189], v[56:59]
	v_mfma_f32_16x16x32_bf16 v[52:55], v[154:157], v[198:201], v[52:55]
	v_mfma_f32_16x16x32_bf16 v[44:47], v[162:165], v[198:201], v[44:47]
	v_mfma_f32_16x16x32_bf16 v[36:39], v[154:157], v[206:209], v[36:39]
	v_mfma_f32_16x16x32_bf16 v[28:31], v[162:165], v[206:209], v[28:31]
	v_mfma_f32_16x16x32_bf16 v[20:23], v[154:157], v[214:217], v[20:23]
	v_mfma_f32_16x16x32_bf16 v[12:15], v[162:165], v[214:217], v[12:15]
	v_mfma_f32_16x16x32_bf16 v[60:63], v[158:161], v[194:197], v[60:63]
	v_mfma_f32_16x16x32_bf16 v[56:59], v[166:169], v[194:197], v[56:59]
	v_mfma_f32_16x16x32_bf16 v[52:55], v[158:161], v[202:205], v[52:55]
	v_mfma_f32_16x16x32_bf16 v[44:47], v[166:169], v[202:205], v[44:47]
	v_mfma_f32_16x16x32_bf16 v[36:39], v[158:161], v[210:213], v[36:39]
	v_mfma_f32_16x16x32_bf16 v[28:31], v[166:169], v[210:213], v[28:31]
	v_mfma_f32_16x16x32_bf16 v[20:23], v[158:161], v[218:221], v[20:23]
	v_mfma_f32_16x16x32_bf16 v[12:15], v[166:169], v[218:221], v[12:15]
	v_mfma_f32_16x16x32_bf16 v[48:51], v[170:173], v[186:189], v[48:51]
	v_mfma_f32_16x16x32_bf16 v[40:43], v[178:181], v[186:189], v[40:43]
	v_mfma_f32_16x16x32_bf16 v[32:35], v[170:173], v[198:201], v[32:35]
	v_mfma_f32_16x16x32_bf16 v[24:27], v[178:181], v[198:201], v[24:27]
	v_mfma_f32_16x16x32_bf16 v[16:19], v[170:173], v[206:209], v[16:19]
	v_mfma_f32_16x16x32_bf16 v[8:11], v[178:181], v[206:209], v[8:11]
	v_mfma_f32_16x16x32_bf16 v[4:7], v[170:173], v[214:217], v[4:7]
	v_mfma_f32_16x16x32_bf16 v[0:3], v[178:181], v[214:217], v[0:3]
	v_mfma_f32_16x16x32_bf16 v[48:51], v[174:177], v[194:197], v[48:51]
	v_mfma_f32_16x16x32_bf16 v[40:43], v[182:185], v[194:197], v[40:43]
	v_mfma_f32_16x16x32_bf16 v[32:35], v[174:177], v[202:205], v[32:35]
	v_mfma_f32_16x16x32_bf16 v[24:27], v[182:185], v[202:205], v[24:27]
	v_mfma_f32_16x16x32_bf16 v[16:19], v[174:177], v[210:213], v[16:19]
	v_mfma_f32_16x16x32_bf16 v[8:11], v[182:185], v[210:213], v[8:11]
	v_mfma_f32_16x16x32_bf16 v[4:7], v[174:177], v[218:221], v[4:7]
	v_mfma_f32_16x16x32_bf16 v[0:3], v[182:185], v[218:221], v[0:3]
	s_barrier
	s_add_i32 s50, s50, 2
	s_add_u32 s22, s22, 0x100
	s_addc_u32 s23, s23, 0
	s_add_u32 s48, s48, 0x100
	s_addc_u32 s49, s49, 0
	s_cmp_gt_u32 s50, 29
	s_cbranch_scc0 .LBB0_216

; #define PG8_STAGE(bufoff, gbase, voff) do { _Pragma("unroll") for (int _i = 0; _i < 2; ++_i) \
;         __builtin_amdgcn_global_load_lds((const unsigned*)((const char*)(gbase) + (voff)[_i]), (LAS unsigned*)(lds + (bufoff) + ldsw + _i * 8192), 16, 0, 0); } while (0)
; #define PG8_LDA(dst, b, h) do { _Pragma("unroll") for (int m = 0; m < 4; ++m) _Pragma("unroll") for (int k = 0; k < 2; ++k) dst[m][k] = *(const LAS bf16x8*)(lds + PG8_SA(b, h) + aoff + m * 2048 + k * 1024); } while (0)
; #define PG8_LDB(dst, b, h) do { _Pragma("unroll") for (int n = 0; n < 2; ++n) _Pragma("unroll") for (int k = 0; k < 2; ++k) dst[n][k] = *(const LAS bf16x8*)(lds + PG8_SB(b, h) + boff + n * 2048 + k * 1024); } while (0)
; #define PG8_WAIT_V(n) asm volatile("s_waitcnt vmcnt(" #n ")" ::: "memory")
; #define PG8_BAR __builtin_amdgcn_s_barrier()
; template <class Epi, class Sched = StaticOrder, class EpiSub = NoSub, bool FAST = false>
; __device__ __forceinline__ void gemm_phase(LAS unsigned char* lds, const Gemm g, const Sched& S, const Epi& E, const EpiSub& ES = EpiSub()) {
;     ...
;         const bool has_next = S.next(ui + 1, nxt);
;         const size_t nko = (has_next && nxt.kb >= 0) ? nxt.kb * ksubB : 0;
;         const char* nA = has_next ? (const char*)g.A + (size_t)nxt.pm * tstepA + (size_t)nxt.pn * g.acs + nko : cA; const char* nB = has_next ? (const char*)g.Bt + (size_t)nxt.pn * tstepB + nko : cB;
;         const int nt = cur.kb < 0 ? ntMain : ntSub;
;         for (int t = 0; t < nt; t += 2) {
;             const bool last = (t == nt - 2);
;             const char* a1 = cA + (size_t)(t + 1) * kstep;
;             const char* a2 = last ? nA : cA + (size_t)(t + 2) * kstep; const char* b2 = last ? nB : cB + (size_t)(t + 2) * kstep;
;             const char* a3 = a2 + kstep; const char* b3 = b2 + kstep;
;             if constexpr (FAST && PG8_SP2) {
;             PG8_LDB(B0, 0, 0); PG8_LDB(B1, 0, 1); PG8_SCHED; PG8_LDA(At, 0, 0); PG8_STAGE(PG8_SA(1, 1), a1 + hstepA, voffA);
;             PG8_WAIT_V(8); PG8_WAIT_L(0); PG8_BAR; PG8_MMA(0, 0, At, B0); PG8_MMA(0, 1, At, B1); PG8_BAR; PG8_SCHED;
;             PG8_LDA(At, 0, 1); PG8_STAGE(PG8_SB(0, 0), b2, voffB); PG8_STAGE(PG8_SB(0, 1), b2 + hstepB, voffB); PG8_STAGE(PG8_SA(0, 0), a2, voffA);
;             PG8_WAIT_V(8); PG8_WAIT_L(0); PG8_BAR; PG8_MMA(1, 0, At, B0); PG8_MMA(1, 1, At, B1); PG8_BAR; PG8_SCHED;
.LBB0_599:
	s_cmp_gt_i32 s8, -1
	s_cselect_b64 s[30:31], -1, 0
	s_and_b64 s[30:31], s[28:29], s[30:31]
	s_lshl_b64 s[36:37], s[8:9], 9
	s_and_b64 s[30:31], s[30:31], exec
	s_cselect_b32 s7, s37, 0
	s_cselect_b32 s33, s36, 0
	s_ashr_i32 s27, s26, 31
	s_lshl_b64 s[30:31], s[26:27], 19
	s_add_u32 s1, s78, s30
	s_addc_u32 s5, s79, s31
	s_add_u32 s30, s1, s33
	s_addc_u32 s31, s5, s7
	s_and_b64 s[36:37], s[28:29], exec
	s_cselect_b32 s1, s31, s41
	s_cselect_b32 s5, s30, s40
	s_ashr_i32 s25, s24, 31
	s_lshl_b64 s[36:37], s[24:25], 19
	s_add_u32 s25, s2, s36
	s_addc_u32 s27, s3, s37
	s_add_u32 s36, s25, s33
	s_addc_u32 s37, s27, s7
	s_and_b64 s[38:39], s[28:29], exec
	s_cselect_b32 s7, s37, s43
	s_cselect_b32 s25, s36, s42
	s_cmp_gt_i32 s0, -1
	s_cselect_b64 s[38:39], -1, 0
	s_cmp_lt_i32 s0, 0
	s_cselect_b32 s27, 16, 4
	s_add_i32 s33, s27, -2
	s_add_u32 s40, s40, 0x40080
	s_addc_u32 s41, s41, 0
	s_add_u32 s48, s42, 0x100
	s_mov_b32 s50, 0
	s_addc_u32 s49, s43, 0
	ds_read_b128 v[100:103], v186
	ds_read_b128 v[112:115], v186 offset:1024
	ds_read_b128 v[124:127], v186 offset:2048
	ds_read_b128 v[136:139], v186 offset:3072
	ds_read_b128 v[144:147], v187
	ds_read_b128 v[148:151], v187 offset:1024
	ds_read_b128 v[152:155], v187 offset:2048
	ds_read_b128 v[170:173], v187 offset:3072
	s_add_i32 s51, s50, 2
	s_add_u32 s42, s40, 0xfffc0080
	s_addc_u32 s43, s41, -1
	s_cmp_eq_u32 s33, s50
	s_cselect_b32 s53, s1, s43
	s_cselect_b32 s52, s5, s42
	s_cselect_b32 s43, s7, s49
	s_cselect_b32 s42, s25, s48
	v_lshl_add_u64 v[190:191], s[40:41], 0, v[164:165]
	s_add_i32 m0, s55, 0xc000
	ds_read_b128 v[174:177], v188
	ds_read_b128 v[178:181], v188 offset:1024
	ds_read_b128 v[194:197], v188 offset:2048
	ds_read_b128 v[198:201], v188 offset:3072
	ds_read_b128 v[202:205], v188 offset:4096
	ds_read_b128 v[206:209], v188 offset:5120
	ds_read_b128 v[210:213], v188 offset:6144
	ds_read_b128 v[214:217], v188 offset:7168
	global_load_lds_dwordx4 v[190:191], off
	v_lshl_add_u64 v[190:191], s[40:41], 0, v[166:167]
	s_add_i32 m0, s55, 0xe000
	s_nop 0
	global_load_lds_dwordx4 v[190:191], off
	s_waitcnt vmcnt(8) lgkmcnt(0)
	s_barrier
	v_mfma_f32_16x16x32_bf16 v[140:143], v[100:103], v[174:177], 0
	v_mfma_f32_16x16x32_bf16 v[132:135], v[124:127], v[174:177], 0
	v_mfma_f32_16x16x32_bf16 v[116:119], v[100:103], v[194:197], 0
	v_mfma_f32_16x16x32_bf16 v[108:111], v[124:127], v[194:197], 0
	v_mfma_f32_16x16x32_bf16 v[92:95], v[100:103], v[202:205], 0
	v_mfma_f32_16x16x32_bf16 v[88:91], v[124:127], v[202:205], 0
	v_mfma_f32_16x16x32_bf16 v[76:79], v[100:103], v[210:213], 0
	v_mfma_f32_16x16x32_bf16 v[72:75], v[124:127], v[210:213], 0
	v_mfma_f32_16x16x32_bf16 v[140:143], v[112:115], v[178:181], v[140:143]
	v_mfma_f32_16x16x32_bf16 v[132:135], v[136:139], v[178:181], v[132:135]
	v_mfma_f32_16x16x32_bf16 v[116:119], v[112:115], v[198:201], v[116:119]
	v_mfma_f32_16x16x32_bf16 v[108:111], v[136:139], v[198:201], v[108:111]
	v_mfma_f32_16x16x32_bf16 v[92:95], v[112:115], v[206:209], v[92:95]
	v_mfma_f32_16x16x32_bf16 v[88:91], v[136:139], v[206:209], v[88:91]
	v_mfma_f32_16x16x32_bf16 v[76:79], v[112:115], v[214:217], v[76:79]
	v_mfma_f32_16x16x32_bf16 v[72:75], v[136:139], v[214:217], v[72:75]
	v_mfma_f32_16x16x32_bf16 v[128:131], v[144:147], v[174:177], 0
	v_mfma_f32_16x16x32_bf16 v[120:123], v[152:155], v[174:177], 0
	v_mfma_f32_16x16x32_bf16 v[104:107], v[144:147], v[194:197], 0
	v_mfma_f32_16x16x32_bf16 v[96:99], v[152:155], v[194:197], 0
	v_mfma_f32_16x16x32_bf16 v[84:87], v[144:147], v[202:205], 0
	v_mfma_f32_16x16x32_bf16 v[80:83], v[152:155], v[202:205], 0
	v_mfma_f32_16x16x32_bf16 v[68:71], v[144:147], v[210:213], 0
	v_mfma_f32_16x16x32_bf16 v[64:67], v[152:155], v[210:213], 0
	v_mfma_f32_16x16x32_bf16 v[128:131], v[148:151], v[178:181], v[128:131]
	v_mfma_f32_16x16x32_bf16 v[120:123], v[170:173], v[178:181], v[120:123]
	v_mfma_f32_16x16x32_bf16 v[104:107], v[148:151], v[198:201], v[104:107]
	v_mfma_f32_16x16x32_bf16 v[96:99], v[170:173], v[198:201], v[96:99]
	v_mfma_f32_16x16x32_bf16 v[84:87], v[148:151], v[206:209], v[84:87]
	v_mfma_f32_16x16x32_bf16 v[80:83], v[170:173], v[206:209], v[80:83]
	v_mfma_f32_16x16x32_bf16 v[68:71], v[148:151], v[214:217], v[68:71]
	v_mfma_f32_16x16x32_bf16 v[64:67], v[170:173], v[214:217], v[64:67]
	s_barrier
	s_add_i32 s50, s75, s54
	v_lshl_add_u64 v[190:191], s[42:43], 0, v[158:159]
	s_mov_b32 m0, s50
	ds_read_b128 v[174:177], v188 offset:16384
	ds_read_b128 v[178:181], v188 offset:17408
	ds_read_b128 v[194:197], v188 offset:18432
	ds_read_b128 v[198:201], v188 offset:19456
	ds_read_b128 v[202:205], v188 offset:20480
	ds_read_b128 v[206:209], v188 offset:21504
	ds_read_b128 v[210:213], v188 offset:22528
	ds_read_b128 v[214:217], v188 offset:23552
	global_load_lds_dwordx4 v[190:191], off
	s_add_i32 m0, s50, 0x2000
	s_add_u32 s70, s42, 0x40000
	v_lshl_add_u64 v[218:219], s[42:43], 0, v[162:163]
	s_addc_u32 s71, s43, 0
	s_add_i32 s50, s80, s54
	global_load_lds_dwordx4 v[218:219], off
	v_lshl_add_u64 v[220:221], s[70:71], 0, v[158:159]
	s_mov_b32 m0, s50
	v_lshl_add_u64 v[222:223], s[52:53], 0, v[160:161]
	global_load_lds_dwordx4 v[220:221], off
	v_lshl_add_u64 v[220:221], s[70:71], 0, v[162:163]
	s_add_i32 m0, s50, 0x2000
	s_nop 0
	global_load_lds_dwordx4 v[220:221], off
	v_lshl_add_u64 v[220:221], s[52:53], 0, v[156:157]
	s_mov_b32 m0, s55
	s_nop 0
	global_load_lds_dwordx4 v[220:221], off
	s_mov_b32 m0, s56
	s_nop 0
	global_load_lds_dwordx4 v[222:223], off
	s_waitcnt vmcnt(8) lgkmcnt(0)
	s_barrier
; #define PG8_STAGE(bufoff, gbase, voff) do { _Pragma("unroll") for (int _i = 0; _i < 2; ++_i) \
;         __builtin_amdgcn_global_load_lds((const unsigned*)((const char*)(gbase) + (voff)[_i]), (LAS unsigned*)(lds + (bufoff) + ldsw + _i * 8192), 16, 0, 0); } while (0)
; #define PG8_LDA(dst, b, h) do { _Pragma("unroll") for (int m = 0; m < 4; ++m) _Pragma("unroll") for (int k = 0; k < 2; ++k) dst[m][k] = *(const LAS bf16x8*)(lds + PG8_SA(b, h) + aoff + m * 2048 + k * 1024); } while (0)
; #define PG8_LDB(dst, b, h) do { _Pragma("unroll") for (int n = 0; n < 2; ++n) _Pragma("unroll") for (int k = 0; k < 2; ++k) dst[n][k] = *(const LAS bf16x8*)(lds + PG8_SB(b, h) + boff + n * 2048 + k * 1024); } while (0)
; #define PG8_MMA(ai, bj, At, Bt) do { __builtin_amdgcn_s_setprio(1); _Pragma("unroll") for (int m = 0; m < 4; ++m) _Pragma("unroll") for (int n = 0; n < 2; ++n) _Pragma("unroll") for (int k = 0; k < 2; ++k) \
;         acc[ai][bj][m][n] = __builtin_amdgcn_mfma_f32_16x16x32_bf16(Bt[n][k], At[m][k], acc[ai][bj][m][n], 0, 0, 0); __builtin_amdgcn_s_setprio(0); } while (0)
; #define PG8_WAIT_V(n) asm volatile("s_waitcnt vmcnt(" #n ")" ::: "memory")
; #define PG8_WAIT_L(n) asm volatile("s_waitcnt lgkmcnt(" #n ")" ::: "memory")
; #define PG8_BAR __builtin_amdgcn_s_barrier()
; #define PG8_SCHED __builtin_amdgcn_sched_barrier(0)
; template <class Epi, class Sched = StaticOrder, class EpiSub = NoSub, bool FAST = false>
; __device__ __forceinline__ void gemm_phase(LAS unsigned char* lds, const Gemm g, const Sched& S, const Epi& E, const EpiSub& ES = EpiSub()) {
;     ...
;             PG8_LDA(At, 0, 1); PG8_STAGE(PG8_SB(0, 0), b2, voffB); PG8_STAGE(PG8_SB(0, 1), b2 + hstepB, voffB); PG8_STAGE(PG8_SA(0, 0), a2, voffA);
;             PG8_WAIT_V(8); PG8_WAIT_L(0); PG8_BAR; PG8_MMA(1, 0, At, B0); PG8_MMA(1, 1, At, B1); PG8_BAR; PG8_SCHED;
;             PG8_LDB(B0, 1, 0); PG8_LDB(B1, 1, 1); PG8_SCHED; PG8_LDA(At, 1, 0); PG8_STAGE(PG8_SA(0, 1), a2 + hstepA, voffA);
;             PG8_WAIT_V(8); PG8_WAIT_L(0); PG8_BAR; PG8_MMA(0, 0, At, B0); PG8_MMA(0, 1, At, B1); PG8_BAR; PG8_SCHED;
	v_mfma_f32_16x16x32_bf16 v[60:63], v[100:103], v[174:177], 0
	v_mfma_f32_16x16x32_bf16 v[56:59], v[124:127], v[174:177], 0
	v_mfma_f32_16x16x32_bf16 v[44:47], v[100:103], v[194:197], 0
	v_mfma_f32_16x16x32_bf16 v[40:43], v[124:127], v[194:197], 0
	v_mfma_f32_16x16x32_bf16 v[28:31], v[100:103], v[202:205], 0
	v_mfma_f32_16x16x32_bf16 v[24:27], v[124:127], v[202:205], 0
	v_mfma_f32_16x16x32_bf16 v[12:15], v[100:103], v[210:213], 0
	v_mfma_f32_16x16x32_bf16 v[8:11], v[124:127], v[210:213], 0
	v_mfma_f32_16x16x32_bf16 v[60:63], v[112:115], v[178:181], v[60:63]
	v_mfma_f32_16x16x32_bf16 v[56:59], v[136:139], v[178:181], v[56:59]
	v_mfma_f32_16x16x32_bf16 v[44:47], v[112:115], v[198:201], v[44:47]
	v_mfma_f32_16x16x32_bf16 v[40:43], v[136:139], v[198:201], v[40:43]
	v_mfma_f32_16x16x32_bf16 v[28:31], v[112:115], v[206:209], v[28:31]
	v_mfma_f32_16x16x32_bf16 v[24:27], v[136:139], v[206:209], v[24:27]
	v_mfma_f32_16x16x32_bf16 v[12:15], v[112:115], v[214:217], v[12:15]
	v_mfma_f32_16x16x32_bf16 v[8:11], v[136:139], v[214:217], v[8:11]
	v_mfma_f32_16x16x32_bf16 v[52:55], v[144:147], v[174:177], 0
	v_mfma_f32_16x16x32_bf16 v[48:51], v[152:155], v[174:177], 0
	v_mfma_f32_16x16x32_bf16 v[36:39], v[144:147], v[194:197], 0
	v_mfma_f32_16x16x32_bf16 v[32:35], v[152:155], v[194:197], 0
	v_mfma_f32_16x16x32_bf16 v[20:23], v[144:147], v[202:205], 0
	v_mfma_f32_16x16x32_bf16 v[16:19], v[152:155], v[202:205], 0
	v_mfma_f32_16x16x32_bf16 v[4:7], v[144:147], v[210:213], 0
	v_mfma_f32_16x16x32_bf16 v[0:3], v[152:155], v[210:213], 0
	v_mfma_f32_16x16x32_bf16 v[52:55], v[148:151], v[178:181], v[52:55]
	v_mfma_f32_16x16x32_bf16 v[48:51], v[170:173], v[178:181], v[48:51]
	v_mfma_f32_16x16x32_bf16 v[36:39], v[148:151], v[198:201], v[36:39]
	v_mfma_f32_16x16x32_bf16 v[32:35], v[170:173], v[198:201], v[32:35]
	v_mfma_f32_16x16x32_bf16 v[20:23], v[148:151], v[206:209], v[20:23]
	v_mfma_f32_16x16x32_bf16 v[16:19], v[170:173], v[206:209], v[16:19]
	v_mfma_f32_16x16x32_bf16 v[4:7], v[148:151], v[214:217], v[4:7]
	v_mfma_f32_16x16x32_bf16 v[0:3], v[170:173], v[214:217], v[0:3]
	s_barrier
	s_add_i32 s50, 0, 0x18000
	s_add_i32 s70, 0, 0x1c000
	v_add_u32_e32 v136, s50, v183
	v_add_u32_e32 v170, s70, v183
	ds_read_b128 v[100:103], v136
	ds_read_b128 v[112:115], v136 offset:1024
	ds_read_b128 v[124:127], v136 offset:2048
	ds_read_b128 v[136:139], v136 offset:3072
	ds_read_b128 v[144:147], v170
	ds_read_b128 v[148:151], v170 offset:1024
	ds_read_b128 v[152:155], v170 offset:2048
	ds_read_b128 v[170:173], v170 offset:3072
	s_add_u32 s52, s52, 0x40000
	s_addc_u32 s53, s53, 0
	s_mov_b32 m0, s57
	v_lshl_add_u64 v[224:225], s[52:53], 0, v[156:157]
	ds_read_b128 v[174:177], v188 offset:32768
	ds_read_b128 v[178:181], v188 offset:33792
	ds_read_b128 v[194:197], v188 offset:34816
	ds_read_b128 v[198:201], v188 offset:35840
	ds_read_b128 v[202:205], v188 offset:36864
	ds_read_b128 v[206:209], v188 offset:37888
	ds_read_b128 v[210:213], v188 offset:38912
	ds_read_b128 v[214:217], v188 offset:39936
	global_load_lds_dwordx4 v[224:225], off
	v_lshl_add_u64 v[224:225], s[52:53], 0, v[160:161]
	s_mov_b32 m0, s58
	s_nop 0
	global_load_lds_dwordx4 v[224:225], off
	s_waitcnt vmcnt(8) lgkmcnt(0)
	s_barrier
	v_mfma_f32_16x16x32_bf16 v[140:143], v[100:103], v[174:177], v[140:143]
	v_mfma_f32_16x16x32_bf16 v[132:135], v[124:127], v[174:177], v[132:135]
	v_mfma_f32_16x16x32_bf16 v[116:119], v[100:103], v[194:197], v[116:119]
	v_mfma_f32_16x16x32_bf16 v[108:111], v[124:127], v[194:197], v[108:111]
	v_mfma_f32_16x16x32_bf16 v[92:95], v[100:103], v[202:205], v[92:95]
	v_mfma_f32_16x16x32_bf16 v[88:91], v[124:127], v[202:205], v[88:91]
	v_mfma_f32_16x16x32_bf16 v[76:79], v[100:103], v[210:213], v[76:79]
	v_mfma_f32_16x16x32_bf16 v[72:75], v[124:127], v[210:213], v[72:75]
	v_mfma_f32_16x16x32_bf16 v[140:143], v[112:115], v[178:181], v[140:143]
	v_mfma_f32_16x16x32_bf16 v[132:135], v[136:139], v[178:181], v[132:135]
	v_mfma_f32_16x16x32_bf16 v[116:119], v[112:115], v[198:201], v[116:119]
	v_mfma_f32_16x16x32_bf16 v[108:111], v[136:139], v[198:201], v[108:111]
	v_mfma_f32_16x16x32_bf16 v[92:95], v[112:115], v[206:209], v[92:95]
	v_mfma_f32_16x16x32_bf16 v[88:91], v[136:139], v[206:209], v[88:91]
	v_mfma_f32_16x16x32_bf16 v[76:79], v[112:115], v[214:217], v[76:79]
	v_mfma_f32_16x16x32_bf16 v[72:75], v[136:139], v[214:217], v[72:75]
	v_mfma_f32_16x16x32_bf16 v[128:131], v[144:147], v[174:177], v[128:131]
	v_mfma_f32_16x16x32_bf16 v[120:123], v[152:155], v[174:177], v[120:123]
	v_mfma_f32_16x16x32_bf16 v[104:107], v[144:147], v[194:197], v[104:107]
	v_mfma_f32_16x16x32_bf16 v[96:99], v[152:155], v[194:197], v[96:99]
	v_mfma_f32_16x16x32_bf16 v[84:87], v[144:147], v[202:205], v[84:87]
	v_mfma_f32_16x16x32_bf16 v[80:83], v[152:155], v[202:205], v[80:83]
	v_mfma_f32_16x16x32_bf16 v[68:71], v[144:147], v[210:213], v[68:71]
	v_mfma_f32_16x16x32_bf16 v[64:67], v[152:155], v[210:213], v[64:67]
	v_mfma_f32_16x16x32_bf16 v[128:131], v[148:151], v[178:181], v[128:131]
	v_mfma_f32_16x16x32_bf16 v[120:123], v[170:173], v[178:181], v[120:123]
	v_mfma_f32_16x16x32_bf16 v[104:107], v[148:151], v[198:201], v[104:107]
	v_mfma_f32_16x16x32_bf16 v[96:99], v[170:173], v[198:201], v[96:99]
	v_mfma_f32_16x16x32_bf16 v[84:87], v[148:151], v[206:209], v[84:87]
	v_mfma_f32_16x16x32_bf16 v[80:83], v[170:173], v[206:209], v[80:83]
	v_mfma_f32_16x16x32_bf16 v[68:71], v[148:151], v[214:217], v[68:71]
	v_mfma_f32_16x16x32_bf16 v[64:67], v[170:173], v[214:217], v[64:67]
	s_barrier
; #define PG8_STAGE(bufoff, gbase, voff) do { _Pragma("unroll") for (int _i = 0; _i < 2; ++_i) \
;         __builtin_amdgcn_global_load_lds((const unsigned*)((const char*)(gbase) + (voff)[_i]), (LAS unsigned*)(lds + (bufoff) + ldsw + _i * 8192), 16, 0, 0); } while (0)
; #define PG8_LDA(dst, b, h) do { _Pragma("unroll") for (int m = 0; m < 4; ++m) _Pragma("unroll") for (int k = 0; k < 2; ++k) dst[m][k] = *(const LAS bf16x8*)(lds + PG8_SA(b, h) + aoff + m * 2048 + k * 1024); } while (0)
; #define PG8_LDB(dst, b, h) do { _Pragma("unroll") for (int n = 0; n < 2; ++n) _Pragma("unroll") for (int k = 0; k < 2; ++k) dst[n][k] = *(const LAS bf16x8*)(lds + PG8_SB(b, h) + boff + n * 2048 + k * 1024); } while (0)
; template <class Epi, class Sched = StaticOrder, class EpiSub = NoSub, bool FAST = false>
; __device__ __forceinline__ void gemm_phase(LAS unsigned char* lds, const Gemm g, const Sched& S, const Epi& E, const EpiSub& ES = EpiSub()) {
;     ...
;         for (int t = 0; t < nt; t += 2) {
;             const bool last = (t == nt - 2);
;             const char* a1 = cA + (size_t)(t + 1) * kstep;
;             const char* a2 = last ? nA : cA + (size_t)(t + 2) * kstep; const char* b2 = last ? nB : cB + (size_t)(t + 2) * kstep;
;             const char* a3 = a2 + kstep; const char* b3 = b2 + kstep;
;             if constexpr (FAST && PG8_SP2) {
;             PG8_LDB(B0, 0, 0); PG8_LDB(B1, 0, 1); PG8_SCHED; PG8_LDA(At, 0, 0); PG8_STAGE(PG8_SA(1, 1), a1 + hstepA, voffA);
;             PG8_WAIT_V(8); PG8_WAIT_L(0); PG8_BAR; PG8_MMA(0, 0, At, B0); PG8_MMA(0, 1, At, B1); PG8_BAR; PG8_SCHED;
;             PG8_LDA(At, 0, 1); PG8_STAGE(PG8_SB(0, 0), b2, voffB); PG8_STAGE(PG8_SB(0, 1), b2 + hstepB, voffB); PG8_STAGE(PG8_SA(0, 0), a2, voffA);
;             PG8_WAIT_V(8); PG8_WAIT_L(0); PG8_BAR; PG8_MMA(1, 0, At, B0); PG8_MMA(1, 1, At, B1); PG8_BAR; PG8_SCHED;
;             PG8_LDB(B0, 1, 0); PG8_LDB(B1, 1, 1); PG8_SCHED; PG8_LDA(At, 1, 0); PG8_STAGE(PG8_SA(0, 1), a2 + hstepA, voffA);
;             PG8_WAIT_V(8); PG8_WAIT_L(0); PG8_BAR; PG8_MMA(0, 0, At, B0); PG8_MMA(0, 1, At, B1); PG8_BAR; PG8_SCHED;
;             PG8_LDA(At, 1, 1); PG8_STAGE(PG8_SB(1, 0), b3, voffB); PG8_STAGE(PG8_SB(1, 1), b3 + hstepB, voffB); PG8_STAGE(PG8_SA(1, 0), a3, voffA);
;             PG8_WAIT_V(8); PG8_WAIT_L(0); PG8_BAR; PG8_MMA(1, 0, At, B0); PG8_MMA(1, 1, At, B1); PG8_BAR; PG8_SCHED;
	s_add_i32 s50, s50, s54
	v_lshl_add_u64 v[190:191], v[190:191], 0, s[12:13]
	s_mov_b32 m0, s50
	ds_read_b128 v[174:177], v188 offset:49152
	ds_read_b128 v[178:181], v188 offset:50176
	ds_read_b128 v[194:197], v188 offset:51200
	ds_read_b128 v[198:201], v188 offset:52224
	ds_read_b128 v[202:205], v188 offset:53248
	ds_read_b128 v[206:209], v188 offset:54272
	ds_read_b128 v[210:213], v188 offset:55296
	ds_read_b128 v[214:217], v188 offset:56320
	global_load_lds_dwordx4 v[190:191], off
	s_add_i32 m0, s50, 0x2000
	s_add_u32 s42, s42, 0x40080
	v_lshl_add_u64 v[190:191], v[218:219], 0, s[12:13]
	s_addc_u32 s43, s43, 0
	s_add_i32 s50, s70, s54
	global_load_lds_dwordx4 v[190:191], off
	v_lshl_add_u64 v[190:191], s[42:43], 0, v[158:159]
	s_mov_b32 m0, s50
	s_nop 0
	global_load_lds_dwordx4 v[190:191], off
	v_lshl_add_u64 v[190:191], s[42:43], 0, v[162:163]
	s_add_i32 m0, s50, 0x2000
	s_nop 0
	global_load_lds_dwordx4 v[190:191], off
	v_lshl_add_u64 v[190:191], v[220:221], 0, s[12:13]
	s_mov_b32 m0, s69
	s_nop 0
	global_load_lds_dwordx4 v[190:191], off
	v_lshl_add_u64 v[190:191], v[222:223], 0, s[12:13]
	s_mov_b32 m0, s74
	s_nop 0
	global_load_lds_dwordx4 v[190:191], off
	s_waitcnt vmcnt(8) lgkmcnt(0)
	s_barrier
	v_mfma_f32_16x16x32_bf16 v[60:63], v[100:103], v[174:177], v[60:63]
	v_mfma_f32_16x16x32_bf16 v[56:59], v[124:127], v[174:177], v[56:59]
	v_mfma_f32_16x16x32_bf16 v[44:47], v[100:103], v[194:197], v[44:47]
	v_mfma_f32_16x16x32_bf16 v[40:43], v[124:127], v[194:197], v[40:43]
	v_mfma_f32_16x16x32_bf16 v[28:31], v[100:103], v[202:205], v[28:31]
	v_mfma_f32_16x16x32_bf16 v[24:27], v[124:127], v[202:205], v[24:27]
	v_mfma_f32_16x16x32_bf16 v[12:15], v[100:103], v[210:213], v[12:15]
	v_mfma_f32_16x16x32_bf16 v[8:11], v[124:127], v[210:213], v[8:11]
	v_mfma_f32_16x16x32_bf16 v[60:63], v[112:115], v[178:181], v[60:63]
	v_mfma_f32_16x16x32_bf16 v[56:59], v[136:139], v[178:181], v[56:59]
	v_mfma_f32_16x16x32_bf16 v[44:47], v[112:115], v[198:201], v[44:47]
	v_mfma_f32_16x16x32_bf16 v[40:43], v[136:139], v[198:201], v[40:43]
	v_mfma_f32_16x16x32_bf16 v[28:31], v[112:115], v[206:209], v[28:31]
	v_mfma_f32_16x16x32_bf16 v[24:27], v[136:139], v[206:209], v[24:27]
	v_mfma_f32_16x16x32_bf16 v[12:15], v[112:115], v[214:217], v[12:15]
	v_mfma_f32_16x16x32_bf16 v[8:11], v[136:139], v[214:217], v[8:11]
	v_mfma_f32_16x16x32_bf16 v[52:55], v[144:147], v[174:177], v[52:55]
	v_mfma_f32_16x16x32_bf16 v[48:51], v[152:155], v[174:177], v[48:51]
	v_mfma_f32_16x16x32_bf16 v[36:39], v[144:147], v[194:197], v[36:39]
	v_mfma_f32_16x16x32_bf16 v[32:35], v[152:155], v[194:197], v[32:35]
	v_mfma_f32_16x16x32_bf16 v[20:23], v[144:147], v[202:205], v[20:23]
	v_mfma_f32_16x16x32_bf16 v[16:19], v[152:155], v[202:205], v[16:19]
	v_mfma_f32_16x16x32_bf16 v[4:7], v[144:147], v[210:213], v[4:7]
	v_mfma_f32_16x16x32_bf16 v[0:3], v[152:155], v[210:213], v[0:3]
	v_mfma_f32_16x16x32_bf16 v[52:55], v[148:151], v[178:181], v[52:55]
	v_mfma_f32_16x16x32_bf16 v[48:51], v[170:173], v[178:181], v[48:51]
	v_mfma_f32_16x16x32_bf16 v[36:39], v[148:151], v[198:201], v[36:39]
	v_mfma_f32_16x16x32_bf16 v[32:35], v[170:173], v[198:201], v[32:35]
	v_mfma_f32_16x16x32_bf16 v[20:23], v[148:151], v[206:209], v[20:23]
	v_mfma_f32_16x16x32_bf16 v[16:19], v[170:173], v[206:209], v[16:19]
	v_mfma_f32_16x16x32_bf16 v[4:7], v[148:151], v[214:217], v[4:7]
	v_mfma_f32_16x16x32_bf16 v[0:3], v[170:173], v[214:217], v[0:3]
	s_barrier
	s_add_u32 s40, s40, 0x100
	s_addc_u32 s41, s41, 0
	s_add_u32 s48, s48, 0x100
	s_addc_u32 s49, s49, 0
	s_cmp_ge_u32 s51, s27
	s_mov_b32 s50, s51
	s_cbranch_scc1 .Lkpeel_600_exit
.LBB0_600:
	ds_read_b128 v[100:103], v186
	ds_read_b128 v[112:115], v186 offset:1024
	ds_read_b128 v[124:127], v186 offset:2048
	ds_read_b128 v[136:139], v186 offset:3072
	ds_read_b128 v[144:147], v187
	ds_read_b128 v[148:151], v187 offset:1024
	ds_read_b128 v[152:155], v187 offset:2048
	ds_read_b128 v[170:173], v187 offset:3072
	s_add_i32 s51, s50, 2
	s_add_u32 s42, s40, 0xfffc0080
	s_addc_u32 s43, s41, -1
	s_cmp_eq_u32 s33, s50
	s_cselect_b32 s53, s1, s43
	s_cselect_b32 s52, s5, s42
	s_cselect_b32 s43, s7, s49
	s_cselect_b32 s42, s25, s48
	v_lshl_add_u64 v[190:191], s[40:41], 0, v[164:165]
	s_add_i32 m0, s55, 0xc000
	ds_read_b128 v[174:177], v188
	ds_read_b128 v[178:181], v188 offset:1024
	ds_read_b128 v[194:197], v188 offset:2048
	ds_read_b128 v[198:201], v188 offset:3072
	ds_read_b128 v[202:205], v188 offset:4096
	ds_read_b128 v[206:209], v188 offset:5120
	ds_read_b128 v[210:213], v188 offset:6144
	ds_read_b128 v[214:217], v188 offset:7168
	global_load_lds_dwordx4 v[190:191], off
	v_lshl_add_u64 v[190:191], s[40:41], 0, v[166:167]
	s_add_i32 m0, s55, 0xe000
	s_nop 0
	global_load_lds_dwordx4 v[190:191], off
	s_waitcnt vmcnt(8) lgkmcnt(0)
	s_barrier
; #define PG8_STAGE(bufoff, gbase, voff) do { _Pragma("unroll") for (int _i = 0; _i < 2; ++_i) \
;         __builtin_amdgcn_global_load_lds((const unsigned*)((const char*)(gbase) + (voff)[_i]), (LAS unsigned*)(lds + (bufoff) + ldsw + _i * 8192), 16, 0, 0); } while (0)
; #define PG8_LDA(dst, b, h) do { _Pragma("unroll") for (int m = 0; m < 4; ++m) _Pragma("unroll") for (int k = 0; k < 2; ++k) dst[m][k] = *(const LAS bf16x8*)(lds + PG8_SA(b, h) + aoff + m * 2048 + k * 1024); } while (0)
; #define PG8_LDB(dst, b, h) do { _Pragma("unroll") for (int n = 0; n < 2; ++n) _Pragma("unroll") for (int k = 0; k < 2; ++k) dst[n][k] = *(const LAS bf16x8*)(lds + PG8_SB(b, h) + boff + n * 2048 + k * 1024); } while (0)
; #define PG8_MMA(ai, bj, At, Bt) do { __builtin_amdgcn_s_setprio(1); _Pragma("unroll") for (int m = 0; m < 4; ++m) _Pragma("unroll") for (int n = 0; n < 2; ++n) _Pragma("unroll") for (int k = 0; k < 2; ++k) \
;         acc[ai][bj][m][n] = __builtin_amdgcn_mfma_f32_16x16x32_bf16(Bt[n][k], At[m][k], acc[ai][bj][m][n], 0, 0, 0); __builtin_amdgcn_s_setprio(0); } while (0)
; #define PG8_WAIT_V(n) asm volatile("s_waitcnt vmcnt(" #n ")" ::: "memory")
; #define PG8_WAIT_L(n) asm volatile("s_waitcnt lgkmcnt(" #n ")" ::: "memory")
; #define PG8_BAR __builtin_amdgcn_s_barrier()
; #define PG8_SCHED __builtin_amdgcn_sched_barrier(0)
; template <class Epi, class Sched = StaticOrder, class EpiSub = NoSub, bool FAST = false>
; __device__ __forceinline__ void gemm_phase(LAS unsigned char* lds, const Gemm g, const Sched& S, const Epi& E, const EpiSub& ES = EpiSub()) {
;     ...
;             PG8_LDB(B0, 0, 0); PG8_LDB(B1, 0, 1); PG8_SCHED; PG8_LDA(At, 0, 0); PG8_STAGE(PG8_SA(1, 1), a1 + hstepA, voffA);
;             PG8_WAIT_V(8); PG8_WAIT_L(0); PG8_BAR; PG8_MMA(0, 0, At, B0); PG8_MMA(0, 1, At, B1); PG8_BAR; PG8_SCHED;
;             PG8_LDA(At, 0, 1); PG8_STAGE(PG8_SB(0, 0), b2, voffB); PG8_STAGE(PG8_SB(0, 1), b2 + hstepB, voffB); PG8_STAGE(PG8_SA(0, 0), a2, voffA);
;             PG8_WAIT_V(8); PG8_WAIT_L(0); PG8_BAR; PG8_MMA(1, 0, At, B0); PG8_MMA(1, 1, At, B1); PG8_BAR; PG8_SCHED;
	v_mfma_f32_16x16x32_bf16 v[140:143], v[100:103], v[174:177], v[140:143]
	v_mfma_f32_16x16x32_bf16 v[132:135], v[124:127], v[174:177], v[132:135]
	v_mfma_f32_16x16x32_bf16 v[116:119], v[100:103], v[194:197], v[116:119]
	v_mfma_f32_16x16x32_bf16 v[108:111], v[124:127], v[194:197], v[108:111]
	v_mfma_f32_16x16x32_bf16 v[92:95], v[100:103], v[202:205], v[92:95]
	v_mfma_f32_16x16x32_bf16 v[88:91], v[124:127], v[202:205], v[88:91]
	v_mfma_f32_16x16x32_bf16 v[76:79], v[100:103], v[210:213], v[76:79]
	v_mfma_f32_16x16x32_bf16 v[72:75], v[124:127], v[210:213], v[72:75]
	v_mfma_f32_16x16x32_bf16 v[140:143], v[112:115], v[178:181], v[140:143]
	v_mfma_f32_16x16x32_bf16 v[132:135], v[136:139], v[178:181], v[132:135]
	v_mfma_f32_16x16x32_bf16 v[116:119], v[112:115], v[198:201], v[116:119]
	v_mfma_f32_16x16x32_bf16 v[108:111], v[136:139], v[198:201], v[108:111]
	v_mfma_f32_16x16x32_bf16 v[92:95], v[112:115], v[206:209], v[92:95]
	v_mfma_f32_16x16x32_bf16 v[88:91], v[136:139], v[206:209], v[88:91]
	v_mfma_f32_16x16x32_bf16 v[76:79], v[112:115], v[214:217], v[76:79]
	v_mfma_f32_16x16x32_bf16 v[72:75], v[136:139], v[214:217], v[72:75]
	v_mfma_f32_16x16x32_bf16 v[128:131], v[144:147], v[174:177], v[128:131]
	v_mfma_f32_16x16x32_bf16 v[120:123], v[152:155], v[174:177], v[120:123]
	v_mfma_f32_16x16x32_bf16 v[104:107], v[144:147], v[194:197], v[104:107]
	v_mfma_f32_16x16x32_bf16 v[96:99], v[152:155], v[194:197], v[96:99]
	v_mfma_f32_16x16x32_bf16 v[84:87], v[144:147], v[202:205], v[84:87]
	v_mfma_f32_16x16x32_bf16 v[80:83], v[152:155], v[202:205], v[80:83]
	v_mfma_f32_16x16x32_bf16 v[68:71], v[144:147], v[210:213], v[68:71]
	v_mfma_f32_16x16x32_bf16 v[64:67], v[152:155], v[210:213], v[64:67]
	v_mfma_f32_16x16x32_bf16 v[128:131], v[148:151], v[178:181], v[128:131]
	v_mfma_f32_16x16x32_bf16 v[120:123], v[170:173], v[178:181], v[120:123]
	v_mfma_f32_16x16x32_bf16 v[104:107], v[148:151], v[198:201], v[104:107]
	v_mfma_f32_16x16x32_bf16 v[96:99], v[170:173], v[198:201], v[96:99]
	v_mfma_f32_16x16x32_bf16 v[84:87], v[148:151], v[206:209], v[84:87]
	v_mfma_f32_16x16x32_bf16 v[80:83], v[170:173], v[206:209], v[80:83]
	v_mfma_f32_16x16x32_bf16 v[68:71], v[148:151], v[214:217], v[68:71]
	v_mfma_f32_16x16x32_bf16 v[64:67], v[170:173], v[214:217], v[64:67]
	s_barrier
	s_add_i32 s50, s75, s54
	v_lshl_add_u64 v[190:191], s[42:43], 0, v[158:159]
	s_mov_b32 m0, s50
	ds_read_b128 v[174:177], v188 offset:16384
	ds_read_b128 v[178:181], v188 offset:17408
	ds_read_b128 v[194:197], v188 offset:18432
	ds_read_b128 v[198:201], v188 offset:19456
	ds_read_b128 v[202:205], v188 offset:20480
	ds_read_b128 v[206:209], v188 offset:21504
	ds_read_b128 v[210:213], v188 offset:22528
	ds_read_b128 v[214:217], v188 offset:23552
	global_load_lds_dwordx4 v[190:191], off
	s_add_i32 m0, s50, 0x2000
	s_add_u32 s70, s42, 0x40000
	v_lshl_add_u64 v[218:219], s[42:43], 0, v[162:163]
	s_addc_u32 s71, s43, 0
	s_add_i32 s50, s80, s54
	global_load_lds_dwordx4 v[218:219], off
	v_lshl_add_u64 v[220:221], s[70:71], 0, v[158:159]
	s_mov_b32 m0, s50
	v_lshl_add_u64 v[222:223], s[52:53], 0, v[160:161]
	global_load_lds_dwordx4 v[220:221], off
	v_lshl_add_u64 v[220:221], s[70:71], 0, v[162:163]
	s_add_i32 m0, s50, 0x2000
	s_nop 0
	global_load_lds_dwordx4 v[220:221], off
	v_lshl_add_u64 v[220:221], s[52:53], 0, v[156:157]
	s_mov_b32 m0, s55
	s_nop 0
	global_load_lds_dwordx4 v[220:221], off
	s_mov_b32 m0, s56
	s_nop 0
	global_load_lds_dwordx4 v[222:223], off
	s_waitcnt vmcnt(8) lgkmcnt(0)
	s_barrier
	v_mfma_f32_16x16x32_bf16 v[60:63], v[100:103], v[174:177], v[60:63]
	v_mfma_f32_16x16x32_bf16 v[56:59], v[124:127], v[174:177], v[56:59]
	v_mfma_f32_16x16x32_bf16 v[44:47], v[100:103], v[194:197], v[44:47]
	v_mfma_f32_16x16x32_bf16 v[40:43], v[124:127], v[194:197], v[40:43]
	v_mfma_f32_16x16x32_bf16 v[28:31], v[100:103], v[202:205], v[28:31]
	v_mfma_f32_16x16x32_bf16 v[24:27], v[124:127], v[202:205], v[24:27]
	v_mfma_f32_16x16x32_bf16 v[12:15], v[100:103], v[210:213], v[12:15]
	v_mfma_f32_16x16x32_bf16 v[8:11], v[124:127], v[210:213], v[8:11]
	v_mfma_f32_16x16x32_bf16 v[60:63], v[112:115], v[178:181], v[60:63]
	v_mfma_f32_16x16x32_bf16 v[56:59], v[136:139], v[178:181], v[56:59]
	v_mfma_f32_16x16x32_bf16 v[44:47], v[112:115], v[198:201], v[44:47]
	v_mfma_f32_16x16x32_bf16 v[40:43], v[136:139], v[198:201], v[40:43]
	v_mfma_f32_16x16x32_bf16 v[28:31], v[112:115], v[206:209], v[28:31]
	v_mfma_f32_16x16x32_bf16 v[24:27], v[136:139], v[206:209], v[24:27]
	v_mfma_f32_16x16x32_bf16 v[12:15], v[112:115], v[214:217], v[12:15]
	v_mfma_f32_16x16x32_bf16 v[8:11], v[136:139], v[214:217], v[8:11]
	v_mfma_f32_16x16x32_bf16 v[52:55], v[144:147], v[174:177], v[52:55]
	v_mfma_f32_16x16x32_bf16 v[48:51], v[152:155], v[174:177], v[48:51]
	v_mfma_f32_16x16x32_bf16 v[36:39], v[144:147], v[194:197], v[36:39]
	v_mfma_f32_16x16x32_bf16 v[32:35], v[152:155], v[194:197], v[32:35]
	v_mfma_f32_16x16x32_bf16 v[20:23], v[144:147], v[202:205], v[20:23]
	v_mfma_f32_16x16x32_bf16 v[16:19], v[152:155], v[202:205], v[16:19]
	v_mfma_f32_16x16x32_bf16 v[4:7], v[144:147], v[210:213], v[4:7]
	v_mfma_f32_16x16x32_bf16 v[0:3], v[152:155], v[210:213], v[0:3]
	v_mfma_f32_16x16x32_bf16 v[52:55], v[148:151], v[178:181], v[52:55]
	v_mfma_f32_16x16x32_bf16 v[48:51], v[170:173], v[178:181], v[48:51]
	v_mfma_f32_16x16x32_bf16 v[36:39], v[148:151], v[198:201], v[36:39]
	v_mfma_f32_16x16x32_bf16 v[32:35], v[170:173], v[198:201], v[32:35]
	v_mfma_f32_16x16x32_bf16 v[20:23], v[148:151], v[206:209], v[20:23]
	v_mfma_f32_16x16x32_bf16 v[16:19], v[170:173], v[206:209], v[16:19]
	v_mfma_f32_16x16x32_bf16 v[4:7], v[148:151], v[214:217], v[4:7]
	v_mfma_f32_16x16x32_bf16 v[0:3], v[170:173], v[214:217], v[0:3]
	s_barrier
; #define PG8_STAGE(bufoff, gbase, voff) do { _Pragma("unroll") for (int _i = 0; _i < 2; ++_i) \
;         __builtin_amdgcn_global_load_lds((const unsigned*)((const char*)(gbase) + (voff)[_i]), (LAS unsigned*)(lds + (bufoff) + ldsw + _i * 8192), 16, 0, 0); } while (0)
; #define PG8_LDA(dst, b, h) do { _Pragma("unroll") for (int m = 0; m < 4; ++m) _Pragma("unroll") for (int k = 0; k < 2; ++k) dst[m][k] = *(const LAS bf16x8*)(lds + PG8_SA(b, h) + aoff + m * 2048 + k * 1024); } while (0)
; #define PG8_LDB(dst, b, h) do { _Pragma("unroll") for (int n = 0; n < 2; ++n) _Pragma("unroll") for (int k = 0; k < 2; ++k) dst[n][k] = *(const LAS bf16x8*)(lds + PG8_SB(b, h) + boff + n * 2048 + k * 1024); } while (0)
; #define PG8_MMA(ai, bj, At, Bt) do { __builtin_amdgcn_s_setprio(1); _Pragma("unroll") for (int m = 0; m < 4; ++m) _Pragma("unroll") for (int n = 0; n < 2; ++n) _Pragma("unroll") for (int k = 0; k < 2; ++k) \
;         acc[ai][bj][m][n] = __builtin_amdgcn_mfma_f32_16x16x32_bf16(Bt[n][k], At[m][k], acc[ai][bj][m][n], 0, 0, 0); __builtin_amdgcn_s_setprio(0); } while (0)
; #define PG8_WAIT_V(n) asm volatile("s_waitcnt vmcnt(" #n ")" ::: "memory")
; #define PG8_WAIT_L(n) asm volatile("s_waitcnt lgkmcnt(" #n ")" ::: "memory")
; #define PG8_BAR __builtin_amdgcn_s_barrier()
; #define PG8_SCHED __builtin_amdgcn_sched_barrier(0)
; template <class Epi, class Sched = StaticOrder, class EpiSub = NoSub, bool FAST = false>
; __device__ __forceinline__ void gemm_phase(LAS unsigned char* lds, const Gemm g, const Sched& S, const Epi& E, const EpiSub& ES = EpiSub()) {
;     ...
;             PG8_LDB(B0, 1, 0); PG8_LDB(B1, 1, 1); PG8_SCHED; PG8_LDA(At, 1, 0); PG8_STAGE(PG8_SA(0, 1), a2 + hstepA, voffA);
;             PG8_WAIT_V(8); PG8_WAIT_L(0); PG8_BAR; PG8_MMA(0, 0, At, B0); PG8_MMA(0, 1, At, B1); PG8_BAR; PG8_SCHED;
;             PG8_LDA(At, 1, 1); PG8_STAGE(PG8_SB(1, 0), b3, voffB); PG8_STAGE(PG8_SB(1, 1), b3 + hstepB, voffB); PG8_STAGE(PG8_SA(1, 0), a3, voffA);
;             PG8_WAIT_V(8); PG8_WAIT_L(0); PG8_BAR; PG8_MMA(1, 0, At, B0); PG8_MMA(1, 1, At, B1); PG8_BAR; PG8_SCHED;
	s_add_i32 s50, 0, 0x18000
	s_add_i32 s70, 0, 0x1c000
	v_add_u32_e32 v136, s50, v183
	v_add_u32_e32 v170, s70, v183
	ds_read_b128 v[100:103], v136
	ds_read_b128 v[112:115], v136 offset:1024
	ds_read_b128 v[124:127], v136 offset:2048
	ds_read_b128 v[136:139], v136 offset:3072
	ds_read_b128 v[144:147], v170
	ds_read_b128 v[148:151], v170 offset:1024
	ds_read_b128 v[152:155], v170 offset:2048
	ds_read_b128 v[170:173], v170 offset:3072
	s_add_u32 s52, s52, 0x40000
	s_addc_u32 s53, s53, 0
	s_mov_b32 m0, s57
	v_lshl_add_u64 v[224:225], s[52:53], 0, v[156:157]
	ds_read_b128 v[174:177], v188 offset:32768
	ds_read_b128 v[178:181], v188 offset:33792
	ds_read_b128 v[194:197], v188 offset:34816
	ds_read_b128 v[198:201], v188 offset:35840
	ds_read_b128 v[202:205], v188 offset:36864
	ds_read_b128 v[206:209], v188 offset:37888
	ds_read_b128 v[210:213], v188 offset:38912
	ds_read_b128 v[214:217], v188 offset:39936
	global_load_lds_dwordx4 v[224:225], off
	v_lshl_add_u64 v[224:225], s[52:53], 0, v[160:161]
	s_mov_b32 m0, s58
	s_nop 0
	global_load_lds_dwordx4 v[224:225], off
	s_waitcnt vmcnt(8) lgkmcnt(0)
	s_barrier
	v_mfma_f32_16x16x32_bf16 v[140:143], v[100:103], v[174:177], v[140:143]
	v_mfma_f32_16x16x32_bf16 v[132:135], v[124:127], v[174:177], v[132:135]
	v_mfma_f32_16x16x32_bf16 v[116:119], v[100:103], v[194:197], v[116:119]
	v_mfma_f32_16x16x32_bf16 v[108:111], v[124:127], v[194:197], v[108:111]
	v_mfma_f32_16x16x32_bf16 v[92:95], v[100:103], v[202:205], v[92:95]
	v_mfma_f32_16x16x32_bf16 v[88:91], v[124:127], v[202:205], v[88:91]
	v_mfma_f32_16x16x32_bf16 v[76:79], v[100:103], v[210:213], v[76:79]
	v_mfma_f32_16x16x32_bf16 v[72:75], v[124:127], v[210:213], v[72:75]
	v_mfma_f32_16x16x32_bf16 v[140:143], v[112:115], v[178:181], v[140:143]
	v_mfma_f32_16x16x32_bf16 v[132:135], v[136:139], v[178:181], v[132:135]
	v_mfma_f32_16x16x32_bf16 v[116:119], v[112:115], v[198:201], v[116:119]
	v_mfma_f32_16x16x32_bf16 v[108:111], v[136:139], v[198:201], v[108:111]
	v_mfma_f32_16x16x32_bf16 v[92:95], v[112:115], v[206:209], v[92:95]
	v_mfma_f32_16x16x32_bf16 v[88:91], v[136:139], v[206:209], v[88:91]
	v_mfma_f32_16x16x32_bf16 v[76:79], v[112:115], v[214:217], v[76:79]
	v_mfma_f32_16x16x32_bf16 v[72:75], v[136:139], v[214:217], v[72:75]
	v_mfma_f32_16x16x32_bf16 v[128:131], v[144:147], v[174:177], v[128:131]
	v_mfma_f32_16x16x32_bf16 v[120:123], v[152:155], v[174:177], v[120:123]
	v_mfma_f32_16x16x32_bf16 v[104:107], v[144:147], v[194:197], v[104:107]
	v_mfma_f32_16x16x32_bf16 v[96:99], v[152:155], v[194:197], v[96:99]
	v_mfma_f32_16x16x32_bf16 v[84:87], v[144:147], v[202:205], v[84:87]
	v_mfma_f32_16x16x32_bf16 v[80:83], v[152:155], v[202:205], v[80:83]
	v_mfma_f32_16x16x32_bf16 v[68:71], v[144:147], v[210:213], v[68:71]
	v_mfma_f32_16x16x32_bf16 v[64:67], v[152:155], v[210:213], v[64:67]
	v_mfma_f32_16x16x32_bf16 v[128:131], v[148:151], v[178:181], v[128:131]
	v_mfma_f32_16x16x32_bf16 v[120:123], v[170:173], v[178:181], v[120:123]
	v_mfma_f32_16x16x32_bf16 v[104:107], v[148:151], v[198:201], v[104:107]
	v_mfma_f32_16x16x32_bf16 v[96:99], v[170:173], v[198:201], v[96:99]
	v_mfma_f32_16x16x32_bf16 v[84:87], v[148:151], v[206:209], v[84:87]
	v_mfma_f32_16x16x32_bf16 v[80:83], v[170:173], v[206:209], v[80:83]
	v_mfma_f32_16x16x32_bf16 v[68:71], v[148:151], v[214:217], v[68:71]
	v_mfma_f32_16x16x32_bf16 v[64:67], v[170:173], v[214:217], v[64:67]
	s_barrier
	s_add_i32 s50, s50, s54
	v_lshl_add_u64 v[190:191], v[190:191], 0, s[12:13]
	s_mov_b32 m0, s50
	ds_read_b128 v[174:177], v188 offset:49152
	ds_read_b128 v[178:181], v188 offset:50176
	ds_read_b128 v[194:197], v188 offset:51200
	ds_read_b128 v[198:201], v188 offset:52224
	ds_read_b128 v[202:205], v188 offset:53248
	ds_read_b128 v[206:209], v188 offset:54272
	ds_read_b128 v[210:213], v188 offset:55296
	ds_read_b128 v[214:217], v188 offset:56320
	global_load_lds_dwordx4 v[190:191], off
	s_add_i32 m0, s50, 0x2000
	s_add_u32 s42, s42, 0x40080
	v_lshl_add_u64 v[190:191], v[218:219], 0, s[12:13]
	s_addc_u32 s43, s43, 0
	s_add_i32 s50, s70, s54
	global_load_lds_dwordx4 v[190:191], off
	v_lshl_add_u64 v[190:191], s[42:43], 0, v[158:159]
	s_mov_b32 m0, s50
	s_nop 0
	global_load_lds_dwordx4 v[190:191], off
	v_lshl_add_u64 v[190:191], s[42:43], 0, v[162:163]
	s_add_i32 m0, s50, 0x2000
	s_nop 0
	global_load_lds_dwordx4 v[190:191], off
	v_lshl_add_u64 v[190:191], v[220:221], 0, s[12:13]
	s_mov_b32 m0, s69
	s_nop 0
	global_load_lds_dwordx4 v[190:191], off
	v_lshl_add_u64 v[190:191], v[222:223], 0, s[12:13]
	s_mov_b32 m0, s74
	s_nop 0
	global_load_lds_dwordx4 v[190:191], off
	s_waitcnt vmcnt(8) lgkmcnt(0)
	s_barrier
	v_mfma_f32_16x16x32_bf16 v[60:63], v[100:103], v[174:177], v[60:63]
	v_mfma_f32_16x16x32_bf16 v[56:59], v[124:127], v[174:177], v[56:59]
	v_mfma_f32_16x16x32_bf16 v[44:47], v[100:103], v[194:197], v[44:47]
	v_mfma_f32_16x16x32_bf16 v[40:43], v[124:127], v[194:197], v[40:43]
	v_mfma_f32_16x16x32_bf16 v[28:31], v[100:103], v[202:205], v[28:31]
	v_mfma_f32_16x16x32_bf16 v[24:27], v[124:127], v[202:205], v[24:27]
	v_mfma_f32_16x16x32_bf16 v[12:15], v[100:103], v[210:213], v[12:15]
	v_mfma_f32_16x16x32_bf16 v[8:11], v[124:127], v[210:213], v[8:11]
	v_mfma_f32_16x16x32_bf16 v[60:63], v[112:115], v[178:181], v[60:63]
	v_mfma_f32_16x16x32_bf16 v[56:59], v[136:139], v[178:181], v[56:59]
	v_mfma_f32_16x16x32_bf16 v[44:47], v[112:115], v[198:201], v[44:47]
	v_mfma_f32_16x16x32_bf16 v[40:43], v[136:139], v[198:201], v[40:43]
	v_mfma_f32_16x16x32_bf16 v[28:31], v[112:115], v[206:209], v[28:31]
	v_mfma_f32_16x16x32_bf16 v[24:27], v[136:139], v[206:209], v[24:27]
	v_mfma_f32_16x16x32_bf16 v[12:15], v[112:115], v[214:217], v[12:15]
	v_mfma_f32_16x16x32_bf16 v[8:11], v[136:139], v[214:217], v[8:11]
	v_mfma_f32_16x16x32_bf16 v[52:55], v[144:147], v[174:177], v[52:55]
	v_mfma_f32_16x16x32_bf16 v[48:51], v[152:155], v[174:177], v[48:51]
	v_mfma_f32_16x16x32_bf16 v[36:39], v[144:147], v[194:197], v[36:39]
	v_mfma_f32_16x16x32_bf16 v[32:35], v[152:155], v[194:197], v[32:35]
	v_mfma_f32_16x16x32_bf16 v[20:23], v[144:147], v[202:205], v[20:23]
	v_mfma_f32_16x16x32_bf16 v[16:19], v[152:155], v[202:205], v[16:19]
	v_mfma_f32_16x16x32_bf16 v[4:7], v[144:147], v[210:213], v[4:7]
	v_mfma_f32_16x16x32_bf16 v[0:3], v[152:155], v[210:213], v[0:3]
	v_mfma_f32_16x16x32_bf16 v[52:55], v[148:151], v[178:181], v[52:55]
	v_mfma_f32_16x16x32_bf16 v[48:51], v[170:173], v[178:181], v[48:51]
	v_mfma_f32_16x16x32_bf16 v[36:39], v[148:151], v[198:201], v[36:39]
	v_mfma_f32_16x16x32_bf16 v[32:35], v[170:173], v[198:201], v[32:35]
	v_mfma_f32_16x16x32_bf16 v[20:23], v[148:151], v[206:209], v[20:23]
	v_mfma_f32_16x16x32_bf16 v[16:19], v[170:173], v[206:209], v[16:19]
	v_mfma_f32_16x16x32_bf16 v[4:7], v[148:151], v[214:217], v[4:7]
	v_mfma_f32_16x16x32_bf16 v[0:3], v[170:173], v[214:217], v[0:3]
	s_barrier
	s_add_u32 s40, s40, 0x100
	s_addc_u32 s41, s41, 0
	s_add_u32 s48, s48, 0x100
	s_addc_u32 s49, s49, 0
	s_cmp_ge_u32 s51, s27
	s_mov_b32 s50, s51
	s_cbranch_scc0 .LBB0_600

; #define PG8_STAGE(bufoff, gbase, voff) do { _Pragma("unroll") for (int _i = 0; _i < 2; ++_i) \
;         __builtin_amdgcn_global_load_lds((const unsigned*)((const char*)(gbase) + (voff)[_i]), (LAS unsigned*)(lds + (bufoff) + ldsw + _i * 8192), 16, 0, 0); } while (0)
; #define PG8_LDA(dst, b, h) do { _Pragma("unroll") for (int m = 0; m < 4; ++m) _Pragma("unroll") for (int k = 0; k < 2; ++k) dst[m][k] = *(const LAS bf16x8*)(lds + PG8_SA(b, h) + aoff + m * 2048 + k * 1024); } while (0)
; #define PG8_LDB(dst, b, h) do { _Pragma("unroll") for (int n = 0; n < 2; ++n) _Pragma("unroll") for (int k = 0; k < 2; ++k) dst[n][k] = *(const LAS bf16x8*)(lds + PG8_SB(b, h) + boff + n * 2048 + k * 1024); } while (0)
; #define PG8_MMA(ai, bj, At, Bt) do { __builtin_amdgcn_s_setprio(1); _Pragma("unroll") for (int m = 0; m < 4; ++m) _Pragma("unroll") for (int n = 0; n < 2; ++n) _Pragma("unroll") for (int k = 0; k < 2; ++k) \
;         acc[ai][bj][m][n] = __builtin_amdgcn_mfma_f32_16x16x32_bf16(Bt[n][k], At[m][k], acc[ai][bj][m][n], 0, 0, 0); __builtin_amdgcn_s_setprio(0); } while (0)
; #define PG8_BAR __builtin_amdgcn_s_barrier()
; template <class Epi, class Sched = StaticOrder, class EpiSub = NoSub, bool FAST = false>
; __device__ __forceinline__ void gemm_phase(LAS unsigned char* lds, const Gemm g, const Sched& S, const Epi& E, const EpiSub& ES = EpiSub()) {
;     ...
;         const bool has_next = S.next(ui + 1, nxt);
;         const size_t nko = (has_next && nxt.kb >= 0) ? nxt.kb * ksubB : 0;
;         const char* nA = has_next ? (const char*)g.A + (size_t)nxt.pm * tstepA + (size_t)nxt.pn * g.acs + nko : cA; const char* nB = has_next ? (const char*)g.Bt + (size_t)nxt.pn * tstepB + nko : cB;
;         const int nt = cur.kb < 0 ? ntMain : ntSub;
;         for (int t = 0; t < nt; t += 2) {
;             const bool last = (t == nt - 2);
;             const char* a1 = cA + (size_t)(t + 1) * kstep;
;             const char* a2 = last ? nA : cA + (size_t)(t + 2) * kstep; const char* b2 = last ? nB : cB + (size_t)(t + 2) * kstep;
;             const char* a3 = a2 + kstep; const char* b3 = b2 + kstep;
;             if constexpr (FAST && PG8_SP2) {
;             PG8_LDB(B0, 0, 0); PG8_LDB(B1, 0, 1); PG8_SCHED; PG8_LDA(At, 0, 0); PG8_STAGE(PG8_SA(1, 1), a1 + hstepA, voffA);
;             PG8_WAIT_V(8); PG8_WAIT_L(0); PG8_BAR; PG8_MMA(0, 0, At, B0); PG8_MMA(0, 1, At, B1); PG8_BAR; PG8_SCHED;
.LBB0_631:
	s_cmp_gt_i32 s8, -1
	s_cselect_b64 s[26:27], -1, 0
	s_and_b64 s[26:27], s[24:25], s[26:27]
	s_lshl_b64 s[28:29], s[8:9], 10
	s_and_b64 s[26:27], s[26:27], exec
	s_cselect_b32 s31, s29, 0
	s_cselect_b32 s33, s28, 0
	s_ashr_i32 s23, s22, 31
	s_lshl_b64 s[26:27], s[22:23], 20
	v_readlane_b32 s28, v254, 36
	v_readlane_b32 s29, v254, 37
	s_add_u32 s1, s28, s26
	s_addc_u32 s5, s29, s27
	s_add_u32 s26, s1, s33
	s_addc_u32 s27, s5, s31
	s_and_b64 s[28:29], s[24:25], exec
	s_cselect_b32 s1, s27, s39
	s_cselect_b32 s5, s26, s38
	s_ashr_i32 s21, s20, 31
	s_lshl_b64 s[28:29], s[20:21], 20
	s_add_u32 s21, s2, s28
	s_addc_u32 s23, s3, s29
	s_add_u32 s28, s21, s33
	s_addc_u32 s29, s23, s31
	s_and_b64 s[36:37], s[24:25], exec
	s_cselect_b32 s21, s29, s41
	s_cselect_b32 s23, s28, s40
	s_cmp_gt_i32 s0, -1
	s_cselect_b64 s[36:37], -1, 0
	s_cmp_lt_i32 s0, 0
	s_cselect_b32 s31, 32, 8
	s_add_i32 s33, s31, -2
	s_add_u32 s38, s38, 0x80080
	s_addc_u32 s39, s39, 0
	s_add_u32 s48, s40, 0x100
	s_mov_b32 s42, 0
	s_addc_u32 s49, s41, 0
	ds_read_b128 v[104:107], v224
	ds_read_b128 v[108:111], v224 offset:1024
	ds_read_b128 v[120:123], v224 offset:2048
	ds_read_b128 v[124:127], v224 offset:3072
	ds_read_b128 v[136:139], v225
	ds_read_b128 v[140:143], v225 offset:1024
	ds_read_b128 v[152:155], v225 offset:2048
	ds_read_b128 v[156:159], v225 offset:3072
	s_add_i32 s50, s42, 2
	s_add_u32 s40, s38, 0xfff80080
	s_addc_u32 s41, s39, -1
	s_cmp_eq_u32 s33, s42
	s_cselect_b32 s42, s5, s40
	s_cselect_b32 s43, s1, s41
	s_cselect_b32 s41, s21, s49
	s_cselect_b32 s40, s23, s48
	v_lshl_add_u64 v[208:209], s[38:39], 0, v[202:203]
	s_add_i32 m0, s53, 0xc000
	ds_read_b128 v[160:163], v226
	ds_read_b128 v[164:167], v226 offset:1024
	ds_read_b128 v[168:171], v226 offset:2048
	ds_read_b128 v[172:175], v226 offset:3072
	ds_read_b128 v[176:179], v226 offset:4096
	ds_read_b128 v[180:183], v226 offset:5120
	ds_read_b128 v[184:187], v226 offset:6144
	ds_read_b128 v[188:191], v226 offset:7168
	global_load_lds_dwordx4 v[208:209], off
	v_lshl_add_u64 v[208:209], s[38:39], 0, v[204:205]
	s_add_i32 m0, s53, 0xe000
	s_nop 0
	global_load_lds_dwordx4 v[208:209], off
	s_waitcnt vmcnt(8) lgkmcnt(0)
	s_barrier
	v_mfma_f32_16x16x32_bf16 v[148:151], v[104:107], v[160:163], 0
	v_mfma_f32_16x16x32_bf16 v[144:147], v[120:123], v[160:163], 0
	v_mfma_f32_16x16x32_bf16 v[116:119], v[104:107], v[168:171], 0
	v_mfma_f32_16x16x32_bf16 v[112:115], v[120:123], v[168:171], 0
	v_mfma_f32_16x16x32_bf16 v[92:95], v[104:107], v[176:179], 0
	v_mfma_f32_16x16x32_bf16 v[88:91], v[120:123], v[176:179], 0
	v_mfma_f32_16x16x32_bf16 v[76:79], v[104:107], v[184:187], 0
	v_mfma_f32_16x16x32_bf16 v[72:75], v[120:123], v[184:187], 0
	v_mfma_f32_16x16x32_bf16 v[148:151], v[108:111], v[164:167], v[148:151]
	v_mfma_f32_16x16x32_bf16 v[144:147], v[124:127], v[164:167], v[144:147]
	v_mfma_f32_16x16x32_bf16 v[116:119], v[108:111], v[172:175], v[116:119]
	v_mfma_f32_16x16x32_bf16 v[112:115], v[124:127], v[172:175], v[112:115]
	v_mfma_f32_16x16x32_bf16 v[92:95], v[108:111], v[180:183], v[92:95]
	v_mfma_f32_16x16x32_bf16 v[88:91], v[124:127], v[180:183], v[88:91]
	v_mfma_f32_16x16x32_bf16 v[76:79], v[108:111], v[188:191], v[76:79]
	v_mfma_f32_16x16x32_bf16 v[72:75], v[124:127], v[188:191], v[72:75]
	v_mfma_f32_16x16x32_bf16 v[132:135], v[136:139], v[160:163], 0
	v_mfma_f32_16x16x32_bf16 v[128:131], v[152:155], v[160:163], 0
	v_mfma_f32_16x16x32_bf16 v[100:103], v[136:139], v[168:171], 0
	v_mfma_f32_16x16x32_bf16 v[96:99], v[152:155], v[168:171], 0
	v_mfma_f32_16x16x32_bf16 v[84:87], v[136:139], v[176:179], 0
	v_mfma_f32_16x16x32_bf16 v[80:83], v[152:155], v[176:179], 0
	v_mfma_f32_16x16x32_bf16 v[68:71], v[136:139], v[184:187], 0
	v_mfma_f32_16x16x32_bf16 v[64:67], v[152:155], v[184:187], 0
	v_mfma_f32_16x16x32_bf16 v[132:135], v[140:143], v[164:167], v[132:135]
	v_mfma_f32_16x16x32_bf16 v[128:131], v[156:159], v[164:167], v[128:131]
	v_mfma_f32_16x16x32_bf16 v[100:103], v[140:143], v[172:175], v[100:103]
	v_mfma_f32_16x16x32_bf16 v[96:99], v[156:159], v[172:175], v[96:99]
	v_mfma_f32_16x16x32_bf16 v[84:87], v[140:143], v[180:183], v[84:87]
	v_mfma_f32_16x16x32_bf16 v[80:83], v[156:159], v[180:183], v[80:83]
	v_mfma_f32_16x16x32_bf16 v[68:71], v[140:143], v[188:191], v[68:71]
	v_mfma_f32_16x16x32_bf16 v[64:67], v[156:159], v[188:191], v[64:67]
	s_barrier
	s_add_i32 s51, s75, s52
	v_lshl_add_u64 v[208:209], s[40:41], 0, v[196:197]
	s_mov_b32 m0, s51
	ds_read_b128 v[160:163], v226 offset:16384
	ds_read_b128 v[164:167], v226 offset:17408
	ds_read_b128 v[168:171], v226 offset:18432
	ds_read_b128 v[172:175], v226 offset:19456
	ds_read_b128 v[176:179], v226 offset:20480
	ds_read_b128 v[180:183], v226 offset:21504
	ds_read_b128 v[184:187], v226 offset:22528
	ds_read_b128 v[188:191], v226 offset:23552
	global_load_lds_dwordx4 v[208:209], off
	s_add_i32 m0, s51, 0x2000
	s_add_u32 s70, s40, 0x80000
	v_lshl_add_u64 v[210:211], s[40:41], 0, v[200:201]
	s_addc_u32 s71, s41, 0
	s_add_i32 s51, s78, s52
	global_load_lds_dwordx4 v[210:211], off
	v_lshl_add_u64 v[212:213], s[70:71], 0, v[196:197]
	s_mov_b32 m0, s51
	v_lshl_add_u64 v[214:215], s[42:43], 0, v[198:199]
	global_load_lds_dwordx4 v[212:213], off
	v_lshl_add_u64 v[212:213], s[70:71], 0, v[200:201]
	s_add_i32 m0, s51, 0x2000
	s_nop 0
	global_load_lds_dwordx4 v[212:213], off
	v_lshl_add_u64 v[212:213], s[42:43], 0, v[194:195]
	s_mov_b32 m0, s53
	s_nop 0
	global_load_lds_dwordx4 v[212:213], off
	s_mov_b32 m0, s54
	s_nop 0
	global_load_lds_dwordx4 v[214:215], off
	s_waitcnt vmcnt(8) lgkmcnt(0)
	s_barrier
; #define PG8_STAGE(bufoff, gbase, voff) do { _Pragma("unroll") for (int _i = 0; _i < 2; ++_i) \
;         __builtin_amdgcn_global_load_lds((const unsigned*)((const char*)(gbase) + (voff)[_i]), (LAS unsigned*)(lds + (bufoff) + ldsw + _i * 8192), 16, 0, 0); } while (0)
; #define PG8_LDA(dst, b, h) do { _Pragma("unroll") for (int m = 0; m < 4; ++m) _Pragma("unroll") for (int k = 0; k < 2; ++k) dst[m][k] = *(const LAS bf16x8*)(lds + PG8_SA(b, h) + aoff + m * 2048 + k * 1024); } while (0)
; #define PG8_LDB(dst, b, h) do { _Pragma("unroll") for (int n = 0; n < 2; ++n) _Pragma("unroll") for (int k = 0; k < 2; ++k) dst[n][k] = *(const LAS bf16x8*)(lds + PG8_SB(b, h) + boff + n * 2048 + k * 1024); } while (0)
; #define PG8_MMA(ai, bj, At, Bt) do { __builtin_amdgcn_s_setprio(1); _Pragma("unroll") for (int m = 0; m < 4; ++m) _Pragma("unroll") for (int n = 0; n < 2; ++n) _Pragma("unroll") for (int k = 0; k < 2; ++k) \
;         acc[ai][bj][m][n] = __builtin_amdgcn_mfma_f32_16x16x32_bf16(Bt[n][k], At[m][k], acc[ai][bj][m][n], 0, 0, 0); __builtin_amdgcn_s_setprio(0); } while (0)
; #define PG8_WAIT_V(n) asm volatile("s_waitcnt vmcnt(" #n ")" ::: "memory")
; #define PG8_WAIT_L(n) asm volatile("s_waitcnt lgkmcnt(" #n ")" ::: "memory")
; #define PG8_BAR __builtin_amdgcn_s_barrier()
; #define PG8_SCHED __builtin_amdgcn_sched_barrier(0)
; template <class Epi, class Sched = StaticOrder, class EpiSub = NoSub, bool FAST = false>
; __device__ __forceinline__ void gemm_phase(LAS unsigned char* lds, const Gemm g, const Sched& S, const Epi& E, const EpiSub& ES = EpiSub()) {
;     ...
;             PG8_WAIT_V(8); PG8_WAIT_L(0); PG8_BAR; PG8_MMA(0, 0, At, B0); PG8_MMA(0, 1, At, B1); PG8_BAR; PG8_SCHED;
;             PG8_LDA(At, 0, 1); PG8_STAGE(PG8_SB(0, 0), b2, voffB); PG8_STAGE(PG8_SB(0, 1), b2 + hstepB, voffB); PG8_STAGE(PG8_SA(0, 0), a2, voffA);
;             PG8_WAIT_V(8); PG8_WAIT_L(0); PG8_BAR; PG8_MMA(1, 0, At, B0); PG8_MMA(1, 1, At, B1); PG8_BAR; PG8_SCHED;
;             PG8_LDB(B0, 1, 0); PG8_LDB(B1, 1, 1); PG8_SCHED; PG8_LDA(At, 1, 0); PG8_STAGE(PG8_SA(0, 1), a2 + hstepA, voffA);
;             PG8_WAIT_V(8); PG8_WAIT_L(0); PG8_BAR; PG8_MMA(0, 0, At, B0); PG8_MMA(0, 1, At, B1); PG8_BAR; PG8_SCHED;
	v_mfma_f32_16x16x32_bf16 v[60:63], v[104:107], v[160:163], 0
	v_mfma_f32_16x16x32_bf16 v[56:59], v[120:123], v[160:163], 0
	v_mfma_f32_16x16x32_bf16 v[44:47], v[104:107], v[168:171], 0
	v_mfma_f32_16x16x32_bf16 v[40:43], v[120:123], v[168:171], 0
	v_mfma_f32_16x16x32_bf16 v[28:31], v[104:107], v[176:179], 0
	v_mfma_f32_16x16x32_bf16 v[24:27], v[120:123], v[176:179], 0
	v_mfma_f32_16x16x32_bf16 v[12:15], v[104:107], v[184:187], 0
	v_mfma_f32_16x16x32_bf16 v[8:11], v[120:123], v[184:187], 0
	v_mfma_f32_16x16x32_bf16 v[60:63], v[108:111], v[164:167], v[60:63]
	v_mfma_f32_16x16x32_bf16 v[56:59], v[124:127], v[164:167], v[56:59]
	v_mfma_f32_16x16x32_bf16 v[44:47], v[108:111], v[172:175], v[44:47]
	v_mfma_f32_16x16x32_bf16 v[40:43], v[124:127], v[172:175], v[40:43]
	v_mfma_f32_16x16x32_bf16 v[28:31], v[108:111], v[180:183], v[28:31]
	v_mfma_f32_16x16x32_bf16 v[24:27], v[124:127], v[180:183], v[24:27]
	v_mfma_f32_16x16x32_bf16 v[12:15], v[108:111], v[188:191], v[12:15]
	v_mfma_f32_16x16x32_bf16 v[8:11], v[124:127], v[188:191], v[8:11]
	v_mfma_f32_16x16x32_bf16 v[52:55], v[136:139], v[160:163], 0
	v_mfma_f32_16x16x32_bf16 v[48:51], v[152:155], v[160:163], 0
	v_mfma_f32_16x16x32_bf16 v[36:39], v[136:139], v[168:171], 0
	v_mfma_f32_16x16x32_bf16 v[32:35], v[152:155], v[168:171], 0
	v_mfma_f32_16x16x32_bf16 v[20:23], v[136:139], v[176:179], 0
	v_mfma_f32_16x16x32_bf16 v[16:19], v[152:155], v[176:179], 0
	v_mfma_f32_16x16x32_bf16 v[4:7], v[136:139], v[184:187], 0
	v_mfma_f32_16x16x32_bf16 v[0:3], v[152:155], v[184:187], 0
	v_mfma_f32_16x16x32_bf16 v[52:55], v[140:143], v[164:167], v[52:55]
	v_mfma_f32_16x16x32_bf16 v[48:51], v[156:159], v[164:167], v[48:51]
	v_mfma_f32_16x16x32_bf16 v[36:39], v[140:143], v[172:175], v[36:39]
	v_mfma_f32_16x16x32_bf16 v[32:35], v[156:159], v[172:175], v[32:35]
	v_mfma_f32_16x16x32_bf16 v[20:23], v[140:143], v[180:183], v[20:23]
	v_mfma_f32_16x16x32_bf16 v[16:19], v[156:159], v[180:183], v[16:19]
	v_mfma_f32_16x16x32_bf16 v[4:7], v[140:143], v[188:191], v[4:7]
	v_mfma_f32_16x16x32_bf16 v[0:3], v[156:159], v[188:191], v[0:3]
	s_barrier
	s_add_i32 s51, 0, 0x18000
	s_add_i32 s70, 0, 0x1c000
	v_add_u32_e32 v124, s51, v221
	v_add_u32_e32 v156, s70, v221
	ds_read_b128 v[104:107], v124
	ds_read_b128 v[108:111], v124 offset:1024
	ds_read_b128 v[120:123], v124 offset:2048
	ds_read_b128 v[124:127], v124 offset:3072
	ds_read_b128 v[136:139], v156
	ds_read_b128 v[140:143], v156 offset:1024
	ds_read_b128 v[152:155], v156 offset:2048
	ds_read_b128 v[156:159], v156 offset:3072
	s_add_u32 s42, s42, 0x80000
	s_addc_u32 s43, s43, 0
	s_mov_b32 m0, s55
	v_lshl_add_u64 v[216:217], s[42:43], 0, v[194:195]
	ds_read_b128 v[160:163], v226 offset:32768
	ds_read_b128 v[164:167], v226 offset:33792
	ds_read_b128 v[168:171], v226 offset:34816
	ds_read_b128 v[172:175], v226 offset:35840
	ds_read_b128 v[176:179], v226 offset:36864
	ds_read_b128 v[180:183], v226 offset:37888
	ds_read_b128 v[184:187], v226 offset:38912
	ds_read_b128 v[188:191], v226 offset:39936
	global_load_lds_dwordx4 v[216:217], off
	v_lshl_add_u64 v[216:217], s[42:43], 0, v[198:199]
	s_mov_b32 m0, s56
	s_nop 0
	global_load_lds_dwordx4 v[216:217], off
	s_waitcnt vmcnt(8) lgkmcnt(0)
	s_barrier
	v_mfma_f32_16x16x32_bf16 v[148:151], v[104:107], v[160:163], v[148:151]
	v_mfma_f32_16x16x32_bf16 v[144:147], v[120:123], v[160:163], v[144:147]
	v_mfma_f32_16x16x32_bf16 v[116:119], v[104:107], v[168:171], v[116:119]
	v_mfma_f32_16x16x32_bf16 v[112:115], v[120:123], v[168:171], v[112:115]
	v_mfma_f32_16x16x32_bf16 v[92:95], v[104:107], v[176:179], v[92:95]
	v_mfma_f32_16x16x32_bf16 v[88:91], v[120:123], v[176:179], v[88:91]
	v_mfma_f32_16x16x32_bf16 v[76:79], v[104:107], v[184:187], v[76:79]
	v_mfma_f32_16x16x32_bf16 v[72:75], v[120:123], v[184:187], v[72:75]
	v_mfma_f32_16x16x32_bf16 v[148:151], v[108:111], v[164:167], v[148:151]
	v_mfma_f32_16x16x32_bf16 v[144:147], v[124:127], v[164:167], v[144:147]
	v_mfma_f32_16x16x32_bf16 v[116:119], v[108:111], v[172:175], v[116:119]
	v_mfma_f32_16x16x32_bf16 v[112:115], v[124:127], v[172:175], v[112:115]
	v_mfma_f32_16x16x32_bf16 v[92:95], v[108:111], v[180:183], v[92:95]
	v_mfma_f32_16x16x32_bf16 v[88:91], v[124:127], v[180:183], v[88:91]
	v_mfma_f32_16x16x32_bf16 v[76:79], v[108:111], v[188:191], v[76:79]
	v_mfma_f32_16x16x32_bf16 v[72:75], v[124:127], v[188:191], v[72:75]
	v_mfma_f32_16x16x32_bf16 v[132:135], v[136:139], v[160:163], v[132:135]
	v_mfma_f32_16x16x32_bf16 v[128:131], v[152:155], v[160:163], v[128:131]
	v_mfma_f32_16x16x32_bf16 v[100:103], v[136:139], v[168:171], v[100:103]
	v_mfma_f32_16x16x32_bf16 v[96:99], v[152:155], v[168:171], v[96:99]
	v_mfma_f32_16x16x32_bf16 v[84:87], v[136:139], v[176:179], v[84:87]
	v_mfma_f32_16x16x32_bf16 v[80:83], v[152:155], v[176:179], v[80:83]
	v_mfma_f32_16x16x32_bf16 v[68:71], v[136:139], v[184:187], v[68:71]
	v_mfma_f32_16x16x32_bf16 v[64:67], v[152:155], v[184:187], v[64:67]
	v_mfma_f32_16x16x32_bf16 v[132:135], v[140:143], v[164:167], v[132:135]
	v_mfma_f32_16x16x32_bf16 v[128:131], v[156:159], v[164:167], v[128:131]
	v_mfma_f32_16x16x32_bf16 v[100:103], v[140:143], v[172:175], v[100:103]
	v_mfma_f32_16x16x32_bf16 v[96:99], v[156:159], v[172:175], v[96:99]
	v_mfma_f32_16x16x32_bf16 v[84:87], v[140:143], v[180:183], v[84:87]
	v_mfma_f32_16x16x32_bf16 v[80:83], v[156:159], v[180:183], v[80:83]
	v_mfma_f32_16x16x32_bf16 v[68:71], v[140:143], v[188:191], v[68:71]
	v_mfma_f32_16x16x32_bf16 v[64:67], v[156:159], v[188:191], v[64:67]
	s_barrier
; #define PG8_STAGE(bufoff, gbase, voff) do { _Pragma("unroll") for (int _i = 0; _i < 2; ++_i) \
;         __builtin_amdgcn_global_load_lds((const unsigned*)((const char*)(gbase) + (voff)[_i]), (LAS unsigned*)(lds + (bufoff) + ldsw + _i * 8192), 16, 0, 0); } while (0)
; #define PG8_LDA(dst, b, h) do { _Pragma("unroll") for (int m = 0; m < 4; ++m) _Pragma("unroll") for (int k = 0; k < 2; ++k) dst[m][k] = *(const LAS bf16x8*)(lds + PG8_SA(b, h) + aoff + m * 2048 + k * 1024); } while (0)
; #define PG8_LDB(dst, b, h) do { _Pragma("unroll") for (int n = 0; n < 2; ++n) _Pragma("unroll") for (int k = 0; k < 2; ++k) dst[n][k] = *(const LAS bf16x8*)(lds + PG8_SB(b, h) + boff + n * 2048 + k * 1024); } while (0)
; template <class Epi, class Sched = StaticOrder, class EpiSub = NoSub, bool FAST = false>
; __device__ __forceinline__ void gemm_phase(LAS unsigned char* lds, const Gemm g, const Sched& S, const Epi& E, const EpiSub& ES = EpiSub()) {
;     ...
;         for (int t = 0; t < nt; t += 2) {
;             const bool last = (t == nt - 2);
;             const char* a1 = cA + (size_t)(t + 1) * kstep;
;             const char* a2 = last ? nA : cA + (size_t)(t + 2) * kstep; const char* b2 = last ? nB : cB + (size_t)(t + 2) * kstep;
;             const char* a3 = a2 + kstep; const char* b3 = b2 + kstep;
;             if constexpr (FAST && PG8_SP2) {
;             PG8_LDB(B0, 0, 0); PG8_LDB(B1, 0, 1); PG8_SCHED; PG8_LDA(At, 0, 0); PG8_STAGE(PG8_SA(1, 1), a1 + hstepA, voffA);
;             PG8_WAIT_V(8); PG8_WAIT_L(0); PG8_BAR; PG8_MMA(0, 0, At, B0); PG8_MMA(0, 1, At, B1); PG8_BAR; PG8_SCHED;
;             PG8_LDA(At, 0, 1); PG8_STAGE(PG8_SB(0, 0), b2, voffB); PG8_STAGE(PG8_SB(0, 1), b2 + hstepB, voffB); PG8_STAGE(PG8_SA(0, 0), a2, voffA);
;             PG8_WAIT_V(8); PG8_WAIT_L(0); PG8_BAR; PG8_MMA(1, 0, At, B0); PG8_MMA(1, 1, At, B1); PG8_BAR; PG8_SCHED;
;             PG8_LDB(B0, 1, 0); PG8_LDB(B1, 1, 1); PG8_SCHED; PG8_LDA(At, 1, 0); PG8_STAGE(PG8_SA(0, 1), a2 + hstepA, voffA);
;             PG8_WAIT_V(8); PG8_WAIT_L(0); PG8_BAR; PG8_MMA(0, 0, At, B0); PG8_MMA(0, 1, At, B1); PG8_BAR; PG8_SCHED;
;             PG8_LDA(At, 1, 1); PG8_STAGE(PG8_SB(1, 0), b3, voffB); PG8_STAGE(PG8_SB(1, 1), b3 + hstepB, voffB); PG8_STAGE(PG8_SA(1, 0), a3, voffA);
;             PG8_WAIT_V(8); PG8_WAIT_L(0); PG8_BAR; PG8_MMA(1, 0, At, B0); PG8_MMA(1, 1, At, B1); PG8_BAR; PG8_SCHED;
	s_add_i32 s42, s51, s52
	v_lshl_add_u64 v[208:209], v[208:209], 0, s[12:13]
	s_mov_b32 m0, s42
	ds_read_b128 v[160:163], v226 offset:49152
	ds_read_b128 v[164:167], v226 offset:50176
	ds_read_b128 v[168:171], v226 offset:51200
	ds_read_b128 v[172:175], v226 offset:52224
	ds_read_b128 v[176:179], v226 offset:53248
	ds_read_b128 v[180:183], v226 offset:54272
	ds_read_b128 v[184:187], v226 offset:55296
	ds_read_b128 v[188:191], v226 offset:56320
	global_load_lds_dwordx4 v[208:209], off
	s_add_i32 m0, s42, 0x2000
	s_add_u32 s40, s40, 0x80080
	v_lshl_add_u64 v[208:209], v[210:211], 0, s[12:13]
	s_addc_u32 s41, s41, 0
	s_add_i32 s42, s70, s52
	global_load_lds_dwordx4 v[208:209], off
	v_lshl_add_u64 v[208:209], s[40:41], 0, v[196:197]
	s_mov_b32 m0, s42
	s_nop 0
	global_load_lds_dwordx4 v[208:209], off
	v_lshl_add_u64 v[208:209], s[40:41], 0, v[200:201]
	s_add_i32 m0, s42, 0x2000
	s_nop 0
	global_load_lds_dwordx4 v[208:209], off
	v_lshl_add_u64 v[208:209], v[212:213], 0, s[12:13]
	s_mov_b32 m0, s69
	s_nop 0
	global_load_lds_dwordx4 v[208:209], off
	v_lshl_add_u64 v[208:209], v[214:215], 0, s[12:13]
	s_mov_b32 m0, s74
	s_nop 0
	global_load_lds_dwordx4 v[208:209], off
	s_waitcnt vmcnt(8) lgkmcnt(0)
	s_barrier
	v_mfma_f32_16x16x32_bf16 v[60:63], v[104:107], v[160:163], v[60:63]
	v_mfma_f32_16x16x32_bf16 v[56:59], v[120:123], v[160:163], v[56:59]
	v_mfma_f32_16x16x32_bf16 v[44:47], v[104:107], v[168:171], v[44:47]
	v_mfma_f32_16x16x32_bf16 v[40:43], v[120:123], v[168:171], v[40:43]
	v_mfma_f32_16x16x32_bf16 v[28:31], v[104:107], v[176:179], v[28:31]
	v_mfma_f32_16x16x32_bf16 v[24:27], v[120:123], v[176:179], v[24:27]
	v_mfma_f32_16x16x32_bf16 v[12:15], v[104:107], v[184:187], v[12:15]
	v_mfma_f32_16x16x32_bf16 v[8:11], v[120:123], v[184:187], v[8:11]
	v_mfma_f32_16x16x32_bf16 v[60:63], v[108:111], v[164:167], v[60:63]
	v_mfma_f32_16x16x32_bf16 v[56:59], v[124:127], v[164:167], v[56:59]
	v_mfma_f32_16x16x32_bf16 v[44:47], v[108:111], v[172:175], v[44:47]
	v_mfma_f32_16x16x32_bf16 v[40:43], v[124:127], v[172:175], v[40:43]
	v_mfma_f32_16x16x32_bf16 v[28:31], v[108:111], v[180:183], v[28:31]
	v_mfma_f32_16x16x32_bf16 v[24:27], v[124:127], v[180:183], v[24:27]
	v_mfma_f32_16x16x32_bf16 v[12:15], v[108:111], v[188:191], v[12:15]
	v_mfma_f32_16x16x32_bf16 v[8:11], v[124:127], v[188:191], v[8:11]
	v_mfma_f32_16x16x32_bf16 v[52:55], v[136:139], v[160:163], v[52:55]
	v_mfma_f32_16x16x32_bf16 v[48:51], v[152:155], v[160:163], v[48:51]
	v_mfma_f32_16x16x32_bf16 v[36:39], v[136:139], v[168:171], v[36:39]
	v_mfma_f32_16x16x32_bf16 v[32:35], v[152:155], v[168:171], v[32:35]
	v_mfma_f32_16x16x32_bf16 v[20:23], v[136:139], v[176:179], v[20:23]
	v_mfma_f32_16x16x32_bf16 v[16:19], v[152:155], v[176:179], v[16:19]
	v_mfma_f32_16x16x32_bf16 v[4:7], v[136:139], v[184:187], v[4:7]
	v_mfma_f32_16x16x32_bf16 v[0:3], v[152:155], v[184:187], v[0:3]
	v_mfma_f32_16x16x32_bf16 v[52:55], v[140:143], v[164:167], v[52:55]
	v_mfma_f32_16x16x32_bf16 v[48:51], v[156:159], v[164:167], v[48:51]
	v_mfma_f32_16x16x32_bf16 v[36:39], v[140:143], v[172:175], v[36:39]
	v_mfma_f32_16x16x32_bf16 v[32:35], v[156:159], v[172:175], v[32:35]
	v_mfma_f32_16x16x32_bf16 v[20:23], v[140:143], v[180:183], v[20:23]
	v_mfma_f32_16x16x32_bf16 v[16:19], v[156:159], v[180:183], v[16:19]
	v_mfma_f32_16x16x32_bf16 v[4:7], v[140:143], v[188:191], v[4:7]
	v_mfma_f32_16x16x32_bf16 v[0:3], v[156:159], v[188:191], v[0:3]
	s_barrier
	s_add_u32 s38, s38, 0x100
	s_addc_u32 s39, s39, 0
	s_add_u32 s48, s48, 0x100
	s_addc_u32 s49, s49, 0
	s_cmp_ge_u32 s50, s31
	s_mov_b32 s42, s50
	s_cbranch_scc1 .Lkpeel_632_exit
.LBB0_632:
	ds_read_b128 v[104:107], v224
	ds_read_b128 v[108:111], v224 offset:1024
	ds_read_b128 v[120:123], v224 offset:2048
	ds_read_b128 v[124:127], v224 offset:3072
	ds_read_b128 v[136:139], v225
	ds_read_b128 v[140:143], v225 offset:1024
	ds_read_b128 v[152:155], v225 offset:2048
	ds_read_b128 v[156:159], v225 offset:3072
	s_add_i32 s50, s42, 2
	s_add_u32 s40, s38, 0xfff80080
	s_addc_u32 s41, s39, -1
	s_cmp_eq_u32 s33, s42
	s_cselect_b32 s42, s5, s40
	s_cselect_b32 s43, s1, s41
	s_cselect_b32 s41, s21, s49
	s_cselect_b32 s40, s23, s48
	v_lshl_add_u64 v[208:209], s[38:39], 0, v[202:203]
	s_add_i32 m0, s53, 0xc000
	ds_read_b128 v[160:163], v226
	ds_read_b128 v[164:167], v226 offset:1024
	ds_read_b128 v[168:171], v226 offset:2048
	ds_read_b128 v[172:175], v226 offset:3072
	ds_read_b128 v[176:179], v226 offset:4096
	ds_read_b128 v[180:183], v226 offset:5120
	ds_read_b128 v[184:187], v226 offset:6144
	ds_read_b128 v[188:191], v226 offset:7168
	global_load_lds_dwordx4 v[208:209], off
	v_lshl_add_u64 v[208:209], s[38:39], 0, v[204:205]
	s_add_i32 m0, s53, 0xe000
	s_nop 0
	global_load_lds_dwordx4 v[208:209], off
	s_waitcnt vmcnt(8) lgkmcnt(0)
	s_barrier
; #define PG8_STAGE(bufoff, gbase, voff) do { _Pragma("unroll") for (int _i = 0; _i < 2; ++_i) \
;         __builtin_amdgcn_global_load_lds((const unsigned*)((const char*)(gbase) + (voff)[_i]), (LAS unsigned*)(lds + (bufoff) + ldsw + _i * 8192), 16, 0, 0); } while (0)
; #define PG8_LDA(dst, b, h) do { _Pragma("unroll") for (int m = 0; m < 4; ++m) _Pragma("unroll") for (int k = 0; k < 2; ++k) dst[m][k] = *(const LAS bf16x8*)(lds + PG8_SA(b, h) + aoff + m * 2048 + k * 1024); } while (0)
; #define PG8_LDB(dst, b, h) do { _Pragma("unroll") for (int n = 0; n < 2; ++n) _Pragma("unroll") for (int k = 0; k < 2; ++k) dst[n][k] = *(const LAS bf16x8*)(lds + PG8_SB(b, h) + boff + n * 2048 + k * 1024); } while (0)
; #define PG8_MMA(ai, bj, At, Bt) do { __builtin_amdgcn_s_setprio(1); _Pragma("unroll") for (int m = 0; m < 4; ++m) _Pragma("unroll") for (int n = 0; n < 2; ++n) _Pragma("unroll") for (int k = 0; k < 2; ++k) \
;         acc[ai][bj][m][n] = __builtin_amdgcn_mfma_f32_16x16x32_bf16(Bt[n][k], At[m][k], acc[ai][bj][m][n], 0, 0, 0); __builtin_amdgcn_s_setprio(0); } while (0)
; #define PG8_WAIT_V(n) asm volatile("s_waitcnt vmcnt(" #n ")" ::: "memory")
; #define PG8_WAIT_L(n) asm volatile("s_waitcnt lgkmcnt(" #n ")" ::: "memory")
; #define PG8_BAR __builtin_amdgcn_s_barrier()
; #define PG8_SCHED __builtin_amdgcn_sched_barrier(0)
; template <class Epi, class Sched = StaticOrder, class EpiSub = NoSub, bool FAST = false>
; __device__ __forceinline__ void gemm_phase(LAS unsigned char* lds, const Gemm g, const Sched& S, const Epi& E, const EpiSub& ES = EpiSub()) {
;     ...
;             PG8_LDB(B0, 0, 0); PG8_LDB(B1, 0, 1); PG8_SCHED; PG8_LDA(At, 0, 0); PG8_STAGE(PG8_SA(1, 1), a1 + hstepA, voffA);
;             PG8_WAIT_V(8); PG8_WAIT_L(0); PG8_BAR; PG8_MMA(0, 0, At, B0); PG8_MMA(0, 1, At, B1); PG8_BAR; PG8_SCHED;
;             PG8_LDA(At, 0, 1); PG8_STAGE(PG8_SB(0, 0), b2, voffB); PG8_STAGE(PG8_SB(0, 1), b2 + hstepB, voffB); PG8_STAGE(PG8_SA(0, 0), a2, voffA);
;             PG8_WAIT_V(8); PG8_WAIT_L(0); PG8_BAR; PG8_MMA(1, 0, At, B0); PG8_MMA(1, 1, At, B1); PG8_BAR; PG8_SCHED;
	v_mfma_f32_16x16x32_bf16 v[148:151], v[104:107], v[160:163], v[148:151]
	v_mfma_f32_16x16x32_bf16 v[144:147], v[120:123], v[160:163], v[144:147]
	v_mfma_f32_16x16x32_bf16 v[116:119], v[104:107], v[168:171], v[116:119]
	v_mfma_f32_16x16x32_bf16 v[112:115], v[120:123], v[168:171], v[112:115]
	v_mfma_f32_16x16x32_bf16 v[92:95], v[104:107], v[176:179], v[92:95]
	v_mfma_f32_16x16x32_bf16 v[88:91], v[120:123], v[176:179], v[88:91]
	v_mfma_f32_16x16x32_bf16 v[76:79], v[104:107], v[184:187], v[76:79]
	v_mfma_f32_16x16x32_bf16 v[72:75], v[120:123], v[184:187], v[72:75]
	v_mfma_f32_16x16x32_bf16 v[148:151], v[108:111], v[164:167], v[148:151]
	v_mfma_f32_16x16x32_bf16 v[144:147], v[124:127], v[164:167], v[144:147]
	v_mfma_f32_16x16x32_bf16 v[116:119], v[108:111], v[172:175], v[116:119]
	v_mfma_f32_16x16x32_bf16 v[112:115], v[124:127], v[172:175], v[112:115]
	v_mfma_f32_16x16x32_bf16 v[92:95], v[108:111], v[180:183], v[92:95]
	v_mfma_f32_16x16x32_bf16 v[88:91], v[124:127], v[180:183], v[88:91]
	v_mfma_f32_16x16x32_bf16 v[76:79], v[108:111], v[188:191], v[76:79]
	v_mfma_f32_16x16x32_bf16 v[72:75], v[124:127], v[188:191], v[72:75]
	v_mfma_f32_16x16x32_bf16 v[132:135], v[136:139], v[160:163], v[132:135]
	v_mfma_f32_16x16x32_bf16 v[128:131], v[152:155], v[160:163], v[128:131]
	v_mfma_f32_16x16x32_bf16 v[100:103], v[136:139], v[168:171], v[100:103]
	v_mfma_f32_16x16x32_bf16 v[96:99], v[152:155], v[168:171], v[96:99]
	v_mfma_f32_16x16x32_bf16 v[84:87], v[136:139], v[176:179], v[84:87]
	v_mfma_f32_16x16x32_bf16 v[80:83], v[152:155], v[176:179], v[80:83]
	v_mfma_f32_16x16x32_bf16 v[68:71], v[136:139], v[184:187], v[68:71]
	v_mfma_f32_16x16x32_bf16 v[64:67], v[152:155], v[184:187], v[64:67]
	v_mfma_f32_16x16x32_bf16 v[132:135], v[140:143], v[164:167], v[132:135]
	v_mfma_f32_16x16x32_bf16 v[128:131], v[156:159], v[164:167], v[128:131]
	v_mfma_f32_16x16x32_bf16 v[100:103], v[140:143], v[172:175], v[100:103]
	v_mfma_f32_16x16x32_bf16 v[96:99], v[156:159], v[172:175], v[96:99]
	v_mfma_f32_16x16x32_bf16 v[84:87], v[140:143], v[180:183], v[84:87]
	v_mfma_f32_16x16x32_bf16 v[80:83], v[156:159], v[180:183], v[80:83]
	v_mfma_f32_16x16x32_bf16 v[68:71], v[140:143], v[188:191], v[68:71]
	v_mfma_f32_16x16x32_bf16 v[64:67], v[156:159], v[188:191], v[64:67]
	s_barrier
	s_add_i32 s51, s75, s52
	v_lshl_add_u64 v[208:209], s[40:41], 0, v[196:197]
	s_mov_b32 m0, s51
	ds_read_b128 v[160:163], v226 offset:16384
	ds_read_b128 v[164:167], v226 offset:17408
	ds_read_b128 v[168:171], v226 offset:18432
	ds_read_b128 v[172:175], v226 offset:19456
	ds_read_b128 v[176:179], v226 offset:20480
	ds_read_b128 v[180:183], v226 offset:21504
	ds_read_b128 v[184:187], v226 offset:22528
	ds_read_b128 v[188:191], v226 offset:23552
	global_load_lds_dwordx4 v[208:209], off
	s_add_i32 m0, s51, 0x2000
	s_add_u32 s70, s40, 0x80000
	v_lshl_add_u64 v[210:211], s[40:41], 0, v[200:201]
	s_addc_u32 s71, s41, 0
	s_add_i32 s51, s78, s52
	global_load_lds_dwordx4 v[210:211], off
	v_lshl_add_u64 v[212:213], s[70:71], 0, v[196:197]
	s_mov_b32 m0, s51
	v_lshl_add_u64 v[214:215], s[42:43], 0, v[198:199]
	global_load_lds_dwordx4 v[212:213], off
	v_lshl_add_u64 v[212:213], s[70:71], 0, v[200:201]
	s_add_i32 m0, s51, 0x2000
	s_nop 0
	global_load_lds_dwordx4 v[212:213], off
	v_lshl_add_u64 v[212:213], s[42:43], 0, v[194:195]
	s_mov_b32 m0, s53
	s_nop 0
	global_load_lds_dwordx4 v[212:213], off
	s_mov_b32 m0, s54
	s_nop 0
	global_load_lds_dwordx4 v[214:215], off
	s_waitcnt vmcnt(8) lgkmcnt(0)
	s_barrier
	v_mfma_f32_16x16x32_bf16 v[60:63], v[104:107], v[160:163], v[60:63]
	v_mfma_f32_16x16x32_bf16 v[56:59], v[120:123], v[160:163], v[56:59]
	v_mfma_f32_16x16x32_bf16 v[44:47], v[104:107], v[168:171], v[44:47]
	v_mfma_f32_16x16x32_bf16 v[40:43], v[120:123], v[168:171], v[40:43]
	v_mfma_f32_16x16x32_bf16 v[28:31], v[104:107], v[176:179], v[28:31]
	v_mfma_f32_16x16x32_bf16 v[24:27], v[120:123], v[176:179], v[24:27]
	v_mfma_f32_16x16x32_bf16 v[12:15], v[104:107], v[184:187], v[12:15]
	v_mfma_f32_16x16x32_bf16 v[8:11], v[120:123], v[184:187], v[8:11]
	v_mfma_f32_16x16x32_bf16 v[60:63], v[108:111], v[164:167], v[60:63]
	v_mfma_f32_16x16x32_bf16 v[56:59], v[124:127], v[164:167], v[56:59]
	v_mfma_f32_16x16x32_bf16 v[44:47], v[108:111], v[172:175], v[44:47]
	v_mfma_f32_16x16x32_bf16 v[40:43], v[124:127], v[172:175], v[40:43]
	v_mfma_f32_16x16x32_bf16 v[28:31], v[108:111], v[180:183], v[28:31]
	v_mfma_f32_16x16x32_bf16 v[24:27], v[124:127], v[180:183], v[24:27]
	v_mfma_f32_16x16x32_bf16 v[12:15], v[108:111], v[188:191], v[12:15]
	v_mfma_f32_16x16x32_bf16 v[8:11], v[124:127], v[188:191], v[8:11]
	v_mfma_f32_16x16x32_bf16 v[52:55], v[136:139], v[160:163], v[52:55]
	v_mfma_f32_16x16x32_bf16 v[48:51], v[152:155], v[160:163], v[48:51]
	v_mfma_f32_16x16x32_bf16 v[36:39], v[136:139], v[168:171], v[36:39]
	v_mfma_f32_16x16x32_bf16 v[32:35], v[152:155], v[168:171], v[32:35]
	v_mfma_f32_16x16x32_bf16 v[20:23], v[136:139], v[176:179], v[20:23]
	v_mfma_f32_16x16x32_bf16 v[16:19], v[152:155], v[176:179], v[16:19]
	v_mfma_f32_16x16x32_bf16 v[4:7], v[136:139], v[184:187], v[4:7]
	v_mfma_f32_16x16x32_bf16 v[0:3], v[152:155], v[184:187], v[0:3]
	v_mfma_f32_16x16x32_bf16 v[52:55], v[140:143], v[164:167], v[52:55]
	v_mfma_f32_16x16x32_bf16 v[48:51], v[156:159], v[164:167], v[48:51]
	v_mfma_f32_16x16x32_bf16 v[36:39], v[140:143], v[172:175], v[36:39]
	v_mfma_f32_16x16x32_bf16 v[32:35], v[156:159], v[172:175], v[32:35]
	v_mfma_f32_16x16x32_bf16 v[20:23], v[140:143], v[180:183], v[20:23]
	v_mfma_f32_16x16x32_bf16 v[16:19], v[156:159], v[180:183], v[16:19]
	v_mfma_f32_16x16x32_bf16 v[4:7], v[140:143], v[188:191], v[4:7]
	v_mfma_f32_16x16x32_bf16 v[0:3], v[156:159], v[188:191], v[0:3]
	s_barrier
; #define PG8_STAGE(bufoff, gbase, voff) do { _Pragma("unroll") for (int _i = 0; _i < 2; ++_i) \
;         __builtin_amdgcn_global_load_lds((const unsigned*)((const char*)(gbase) + (voff)[_i]), (LAS unsigned*)(lds + (bufoff) + ldsw + _i * 8192), 16, 0, 0); } while (0)
; #define PG8_LDA(dst, b, h) do { _Pragma("unroll") for (int m = 0; m < 4; ++m) _Pragma("unroll") for (int k = 0; k < 2; ++k) dst[m][k] = *(const LAS bf16x8*)(lds + PG8_SA(b, h) + aoff + m * 2048 + k * 1024); } while (0)
; #define PG8_LDB(dst, b, h) do { _Pragma("unroll") for (int n = 0; n < 2; ++n) _Pragma("unroll") for (int k = 0; k < 2; ++k) dst[n][k] = *(const LAS bf16x8*)(lds + PG8_SB(b, h) + boff + n * 2048 + k * 1024); } while (0)
; #define PG8_MMA(ai, bj, At, Bt) do { __builtin_amdgcn_s_setprio(1); _Pragma("unroll") for (int m = 0; m < 4; ++m) _Pragma("unroll") for (int n = 0; n < 2; ++n) _Pragma("unroll") for (int k = 0; k < 2; ++k) \
;         acc[ai][bj][m][n] = __builtin_amdgcn_mfma_f32_16x16x32_bf16(Bt[n][k], At[m][k], acc[ai][bj][m][n], 0, 0, 0); __builtin_amdgcn_s_setprio(0); } while (0)
; #define PG8_WAIT_V(n) asm volatile("s_waitcnt vmcnt(" #n ")" ::: "memory")
; #define PG8_WAIT_L(n) asm volatile("s_waitcnt lgkmcnt(" #n ")" ::: "memory")
; #define PG8_BAR __builtin_amdgcn_s_barrier()
; #define PG8_SCHED __builtin_amdgcn_sched_barrier(0)
; template <class Epi, class Sched = StaticOrder, class EpiSub = NoSub, bool FAST = false>
; __device__ __forceinline__ void gemm_phase(LAS unsigned char* lds, const Gemm g, const Sched& S, const Epi& E, const EpiSub& ES = EpiSub()) {
;     ...
;             PG8_LDB(B0, 1, 0); PG8_LDB(B1, 1, 1); PG8_SCHED; PG8_LDA(At, 1, 0); PG8_STAGE(PG8_SA(0, 1), a2 + hstepA, voffA);
;             PG8_WAIT_V(8); PG8_WAIT_L(0); PG8_BAR; PG8_MMA(0, 0, At, B0); PG8_MMA(0, 1, At, B1); PG8_BAR; PG8_SCHED;
;             PG8_LDA(At, 1, 1); PG8_STAGE(PG8_SB(1, 0), b3, voffB); PG8_STAGE(PG8_SB(1, 1), b3 + hstepB, voffB); PG8_STAGE(PG8_SA(1, 0), a3, voffA);
;             PG8_WAIT_V(8); PG8_WAIT_L(0); PG8_BAR; PG8_MMA(1, 0, At, B0); PG8_MMA(1, 1, At, B1); PG8_BAR; PG8_SCHED;
	s_add_i32 s51, 0, 0x18000
	s_add_i32 s70, 0, 0x1c000
	v_add_u32_e32 v124, s51, v221
	v_add_u32_e32 v156, s70, v221
	ds_read_b128 v[104:107], v124
	ds_read_b128 v[108:111], v124 offset:1024
	ds_read_b128 v[120:123], v124 offset:2048
	ds_read_b128 v[124:127], v124 offset:3072
	ds_read_b128 v[136:139], v156
	ds_read_b128 v[140:143], v156 offset:1024
	ds_read_b128 v[152:155], v156 offset:2048
	ds_read_b128 v[156:159], v156 offset:3072
	s_add_u32 s42, s42, 0x80000
	s_addc_u32 s43, s43, 0
	s_mov_b32 m0, s55
	v_lshl_add_u64 v[216:217], s[42:43], 0, v[194:195]
	ds_read_b128 v[160:163], v226 offset:32768
	ds_read_b128 v[164:167], v226 offset:33792
	ds_read_b128 v[168:171], v226 offset:34816
	ds_read_b128 v[172:175], v226 offset:35840
	ds_read_b128 v[176:179], v226 offset:36864
	ds_read_b128 v[180:183], v226 offset:37888
	ds_read_b128 v[184:187], v226 offset:38912
	ds_read_b128 v[188:191], v226 offset:39936
	global_load_lds_dwordx4 v[216:217], off
	v_lshl_add_u64 v[216:217], s[42:43], 0, v[198:199]
	s_mov_b32 m0, s56
	s_nop 0
	global_load_lds_dwordx4 v[216:217], off
	s_waitcnt vmcnt(8) lgkmcnt(0)
	s_barrier
	v_mfma_f32_16x16x32_bf16 v[148:151], v[104:107], v[160:163], v[148:151]
	v_mfma_f32_16x16x32_bf16 v[144:147], v[120:123], v[160:163], v[144:147]
	v_mfma_f32_16x16x32_bf16 v[116:119], v[104:107], v[168:171], v[116:119]
	v_mfma_f32_16x16x32_bf16 v[112:115], v[120:123], v[168:171], v[112:115]
	v_mfma_f32_16x16x32_bf16 v[92:95], v[104:107], v[176:179], v[92:95]
	v_mfma_f32_16x16x32_bf16 v[88:91], v[120:123], v[176:179], v[88:91]
	v_mfma_f32_16x16x32_bf16 v[76:79], v[104:107], v[184:187], v[76:79]
	v_mfma_f32_16x16x32_bf16 v[72:75], v[120:123], v[184:187], v[72:75]
	v_mfma_f32_16x16x32_bf16 v[148:151], v[108:111], v[164:167], v[148:151]
	v_mfma_f32_16x16x32_bf16 v[144:147], v[124:127], v[164:167], v[144:147]
	v_mfma_f32_16x16x32_bf16 v[116:119], v[108:111], v[172:175], v[116:119]
	v_mfma_f32_16x16x32_bf16 v[112:115], v[124:127], v[172:175], v[112:115]
	v_mfma_f32_16x16x32_bf16 v[92:95], v[108:111], v[180:183], v[92:95]
	v_mfma_f32_16x16x32_bf16 v[88:91], v[124:127], v[180:183], v[88:91]
	v_mfma_f32_16x16x32_bf16 v[76:79], v[108:111], v[188:191], v[76:79]
	v_mfma_f32_16x16x32_bf16 v[72:75], v[124:127], v[188:191], v[72:75]
	v_mfma_f32_16x16x32_bf16 v[132:135], v[136:139], v[160:163], v[132:135]
	v_mfma_f32_16x16x32_bf16 v[128:131], v[152:155], v[160:163], v[128:131]
	v_mfma_f32_16x16x32_bf16 v[100:103], v[136:139], v[168:171], v[100:103]
	v_mfma_f32_16x16x32_bf16 v[96:99], v[152:155], v[168:171], v[96:99]
	v_mfma_f32_16x16x32_bf16 v[84:87], v[136:139], v[176:179], v[84:87]
	v_mfma_f32_16x16x32_bf16 v[80:83], v[152:155], v[176:179], v[80:83]
	v_mfma_f32_16x16x32_bf16 v[68:71], v[136:139], v[184:187], v[68:71]
	v_mfma_f32_16x16x32_bf16 v[64:67], v[152:155], v[184:187], v[64:67]
	v_mfma_f32_16x16x32_bf16 v[132:135], v[140:143], v[164:167], v[132:135]
	v_mfma_f32_16x16x32_bf16 v[128:131], v[156:159], v[164:167], v[128:131]
	v_mfma_f32_16x16x32_bf16 v[100:103], v[140:143], v[172:175], v[100:103]
	v_mfma_f32_16x16x32_bf16 v[96:99], v[156:159], v[172:175], v[96:99]
	v_mfma_f32_16x16x32_bf16 v[84:87], v[140:143], v[180:183], v[84:87]
	v_mfma_f32_16x16x32_bf16 v[80:83], v[156:159], v[180:183], v[80:83]
	v_mfma_f32_16x16x32_bf16 v[68:71], v[140:143], v[188:191], v[68:71]
	v_mfma_f32_16x16x32_bf16 v[64:67], v[156:159], v[188:191], v[64:67]
	s_barrier
	s_add_i32 s42, s51, s52
	v_lshl_add_u64 v[208:209], v[208:209], 0, s[12:13]
	s_mov_b32 m0, s42
	ds_read_b128 v[160:163], v226 offset:49152
	ds_read_b128 v[164:167], v226 offset:50176
	ds_read_b128 v[168:171], v226 offset:51200
	ds_read_b128 v[172:175], v226 offset:52224
	ds_read_b128 v[176:179], v226 offset:53248
	ds_read_b128 v[180:183], v226 offset:54272
	ds_read_b128 v[184:187], v226 offset:55296
	ds_read_b128 v[188:191], v226 offset:56320
	global_load_lds_dwordx4 v[208:209], off
	s_add_i32 m0, s42, 0x2000
	s_add_u32 s40, s40, 0x80080
	v_lshl_add_u64 v[208:209], v[210:211], 0, s[12:13]
	s_addc_u32 s41, s41, 0
	s_add_i32 s42, s70, s52
	global_load_lds_dwordx4 v[208:209], off
	v_lshl_add_u64 v[208:209], s[40:41], 0, v[196:197]
	s_mov_b32 m0, s42
	s_nop 0
	global_load_lds_dwordx4 v[208:209], off
	v_lshl_add_u64 v[208:209], s[40:41], 0, v[200:201]
	s_add_i32 m0, s42, 0x2000
	s_nop 0
	global_load_lds_dwordx4 v[208:209], off
	v_lshl_add_u64 v[208:209], v[212:213], 0, s[12:13]
	s_mov_b32 m0, s69
	s_nop 0
	global_load_lds_dwordx4 v[208:209], off
	v_lshl_add_u64 v[208:209], v[214:215], 0, s[12:13]
	s_mov_b32 m0, s74
	s_nop 0
	global_load_lds_dwordx4 v[208:209], off
	s_waitcnt vmcnt(8) lgkmcnt(0)
	s_barrier
	v_mfma_f32_16x16x32_bf16 v[60:63], v[104:107], v[160:163], v[60:63]
	v_mfma_f32_16x16x32_bf16 v[56:59], v[120:123], v[160:163], v[56:59]
	v_mfma_f32_16x16x32_bf16 v[44:47], v[104:107], v[168:171], v[44:47]
	v_mfma_f32_16x16x32_bf16 v[40:43], v[120:123], v[168:171], v[40:43]
	v_mfma_f32_16x16x32_bf16 v[28:31], v[104:107], v[176:179], v[28:31]
	v_mfma_f32_16x16x32_bf16 v[24:27], v[120:123], v[176:179], v[24:27]
	v_mfma_f32_16x16x32_bf16 v[12:15], v[104:107], v[184:187], v[12:15]
	v_mfma_f32_16x16x32_bf16 v[8:11], v[120:123], v[184:187], v[8:11]
	v_mfma_f32_16x16x32_bf16 v[60:63], v[108:111], v[164:167], v[60:63]
	v_mfma_f32_16x16x32_bf16 v[56:59], v[124:127], v[164:167], v[56:59]
	v_mfma_f32_16x16x32_bf16 v[44:47], v[108:111], v[172:175], v[44:47]
	v_mfma_f32_16x16x32_bf16 v[40:43], v[124:127], v[172:175], v[40:43]
	v_mfma_f32_16x16x32_bf16 v[28:31], v[108:111], v[180:183], v[28:31]
	v_mfma_f32_16x16x32_bf16 v[24:27], v[124:127], v[180:183], v[24:27]
	v_mfma_f32_16x16x32_bf16 v[12:15], v[108:111], v[188:191], v[12:15]
	v_mfma_f32_16x16x32_bf16 v[8:11], v[124:127], v[188:191], v[8:11]
	v_mfma_f32_16x16x32_bf16 v[52:55], v[136:139], v[160:163], v[52:55]
	v_mfma_f32_16x16x32_bf16 v[48:51], v[152:155], v[160:163], v[48:51]
	v_mfma_f32_16x16x32_bf16 v[36:39], v[136:139], v[168:171], v[36:39]
	v_mfma_f32_16x16x32_bf16 v[32:35], v[152:155], v[168:171], v[32:35]
	v_mfma_f32_16x16x32_bf16 v[20:23], v[136:139], v[176:179], v[20:23]
	v_mfma_f32_16x16x32_bf16 v[16:19], v[152:155], v[176:179], v[16:19]
	v_mfma_f32_16x16x32_bf16 v[4:7], v[136:139], v[184:187], v[4:7]
	v_mfma_f32_16x16x32_bf16 v[0:3], v[152:155], v[184:187], v[0:3]
	v_mfma_f32_16x16x32_bf16 v[52:55], v[140:143], v[164:167], v[52:55]
	v_mfma_f32_16x16x32_bf16 v[48:51], v[156:159], v[164:167], v[48:51]
	v_mfma_f32_16x16x32_bf16 v[36:39], v[140:143], v[172:175], v[36:39]
	v_mfma_f32_16x16x32_bf16 v[32:35], v[156:159], v[172:175], v[32:35]
	v_mfma_f32_16x16x32_bf16 v[20:23], v[140:143], v[180:183], v[20:23]
	v_mfma_f32_16x16x32_bf16 v[16:19], v[156:159], v[180:183], v[16:19]
	v_mfma_f32_16x16x32_bf16 v[4:7], v[140:143], v[188:191], v[4:7]
	v_mfma_f32_16x16x32_bf16 v[0:3], v[156:159], v[188:191], v[0:3]
	s_barrier
	s_add_u32 s38, s38, 0x100
	s_addc_u32 s39, s39, 0
	s_add_u32 s48, s48, 0x100
	s_addc_u32 s49, s49, 0
	s_cmp_ge_u32 s50, s31
	s_mov_b32 s42, s50
	s_cbranch_scc0 .LBB0_632

; #define PG8_STAGE(bufoff, gbase, voff) do { _Pragma("unroll") for (int _i = 0; _i < 2; ++_i) \
;         __builtin_amdgcn_global_load_lds((const unsigned*)((const char*)(gbase) + (voff)[_i]), (LAS unsigned*)(lds + (bufoff) + ldsw + _i * 8192), 16, 0, 0); } while (0)
; #define PG8_LDA(dst, b, h) do { _Pragma("unroll") for (int m = 0; m < 4; ++m) _Pragma("unroll") for (int k = 0; k < 2; ++k) dst[m][k] = *(const LAS bf16x8*)(lds + PG8_SA(b, h) + aoff + m * 2048 + k * 1024); } while (0)
; #define PG8_LDB(dst, b, h) do { _Pragma("unroll") for (int n = 0; n < 2; ++n) _Pragma("unroll") for (int k = 0; k < 2; ++k) dst[n][k] = *(const LAS bf16x8*)(lds + PG8_SB(b, h) + boff + n * 2048 + k * 1024); } while (0)
; #define PG8_MMA(ai, bj, At, Bt) do { __builtin_amdgcn_s_setprio(1); _Pragma("unroll") for (int m = 0; m < 4; ++m) _Pragma("unroll") for (int n = 0; n < 2; ++n) _Pragma("unroll") for (int k = 0; k < 2; ++k) \
;         acc[ai][bj][m][n] = __builtin_amdgcn_mfma_f32_16x16x32_bf16(Bt[n][k], At[m][k], acc[ai][bj][m][n], 0, 0, 0); __builtin_amdgcn_s_setprio(0); } while (0)
; #define PG8_BAR __builtin_amdgcn_s_barrier()
; template <class Epi, class Sched = StaticOrder, class EpiSub = NoSub, bool FAST = false>
; __device__ __forceinline__ void gemm_phase(LAS unsigned char* lds, const Gemm g, const Sched& S, const Epi& E, const EpiSub& ES = EpiSub()) {
;     ...
;         const bool has_next = S.next(ui + 1, nxt);
;         const size_t nko = (has_next && nxt.kb >= 0) ? nxt.kb * ksubB : 0;
;         const char* nA = has_next ? (const char*)g.A + (size_t)nxt.pm * tstepA + (size_t)nxt.pn * g.acs + nko : cA; const char* nB = has_next ? (const char*)g.Bt + (size_t)nxt.pn * tstepB + nko : cB;
;         const int nt = cur.kb < 0 ? ntMain : ntSub;
;         for (int t = 0; t < nt; t += 2) {
;             const bool last = (t == nt - 2);
;             const char* a1 = cA + (size_t)(t + 1) * kstep;
;             const char* a2 = last ? nA : cA + (size_t)(t + 2) * kstep; const char* b2 = last ? nB : cB + (size_t)(t + 2) * kstep;
;             const char* a3 = a2 + kstep; const char* b3 = b2 + kstep;
;             if constexpr (FAST && PG8_SP2) {
;             PG8_LDB(B0, 0, 0); PG8_LDB(B1, 0, 1); PG8_SCHED; PG8_LDA(At, 0, 0); PG8_STAGE(PG8_SA(1, 1), a1 + hstepA, voffA);
;             PG8_WAIT_V(8); PG8_WAIT_L(0); PG8_BAR; PG8_MMA(0, 0, At, B0); PG8_MMA(0, 1, At, B1); PG8_BAR; PG8_SCHED;
.LBB0_768:
	s_cmp_gt_i32 s6, -1
	s_cselect_b64 s[24:25], -1, 0
	s_and_b64 s[24:25], s[22:23], s[24:25]
	s_lshl_b64 s[26:27], s[6:7], 9
	s_and_b64 s[24:25], s[24:25], exec
	s_cselect_b32 s29, s27, 0
	s_cselect_b32 s30, s26, 0
	s_ashr_i32 s21, s20, 31
	s_lshl_b64 s[24:25], s[20:21], 20
	s_add_u32 s1, s84, s24
	s_addc_u32 s5, s85, s25
	s_add_u32 s24, s1, s30
	s_addc_u32 s25, s5, s29
	s_and_b64 s[26:27], s[22:23], exec
	s_cselect_b32 s1, s25, s39
	s_cselect_b32 s5, s24, s38
	s_ashr_i32 s19, s18, 31
	s_lshl_b64 s[26:27], s[18:19], 20
	s_add_u32 s19, s2, s26
	s_addc_u32 s21, s3, s27
	s_add_u32 s26, s19, s30
	s_addc_u32 s27, s21, s29
	s_and_b64 s[30:31], s[22:23], exec
	s_cselect_b32 s19, s27, s41
	s_cselect_b32 s21, s26, s40
	s_cmp_gt_i32 s4, -1
	s_cselect_b64 s[30:31], -1, 0
	s_cmp_lt_i32 s4, 0
	s_cselect_b32 s29, 32, 4
	s_add_i32 s33, s29, -2
	s_add_u32 s38, s38, 0x80080
	s_addc_u32 s39, s39, 0
	s_add_u32 s70, s40, 0x100
	s_mov_b32 s42, 0
	s_addc_u32 s71, s41, 0
	ds_read_b128 v[96:99], v215
	ds_read_b128 v[100:103], v215 offset:1024
	ds_read_b128 v[112:115], v215 offset:2048
	ds_read_b128 v[116:119], v215 offset:3072
	ds_read_b128 v[144:147], v216
	ds_read_b128 v[148:151], v216 offset:1024
	ds_read_b128 v[152:155], v216 offset:2048
	ds_read_b128 v[156:159], v216 offset:3072
	s_add_i32 s72, s42, 2
	s_add_u32 s40, s38, 0xfff80080
	s_addc_u32 s41, s39, -1
	s_cmp_eq_u32 s33, s42
	s_cselect_b32 s42, s5, s40
	s_cselect_b32 s43, s1, s41
	s_cselect_b32 s41, s19, s71
	s_cselect_b32 s40, s21, s70
	v_lshl_add_u64 v[208:209], s[38:39], 0, v[194:195]
	s_add_i32 m0, s48, 0xc000
	ds_read_b128 v[160:163], v217
	ds_read_b128 v[164:167], v217 offset:1024
	ds_read_b128 v[168:171], v217 offset:2048
	ds_read_b128 v[172:175], v217 offset:3072
	ds_read_b128 v[176:179], v217 offset:4096
	ds_read_b128 v[180:183], v217 offset:5120
	ds_read_b128 v[200:203], v217 offset:6144
	ds_read_b128 v[204:207], v217 offset:7168
	global_load_lds_dwordx4 v[208:209], off
	v_lshl_add_u64 v[208:209], s[38:39], 0, v[196:197]
	s_add_i32 m0, s48, 0xe000
	s_nop 0
	global_load_lds_dwordx4 v[208:209], off
	s_waitcnt vmcnt(8) lgkmcnt(0)
	s_barrier
	v_mfma_f32_16x16x32_bf16 v[140:143], v[96:99], v[160:163], 0
	v_mfma_f32_16x16x32_bf16 v[136:139], v[112:115], v[160:163], 0
	v_mfma_f32_16x16x32_bf16 v[124:127], v[96:99], v[168:171], 0
	v_mfma_f32_16x16x32_bf16 v[120:123], v[112:115], v[168:171], 0
	v_mfma_f32_16x16x32_bf16 v[92:95], v[96:99], v[176:179], 0
	v_mfma_f32_16x16x32_bf16 v[88:91], v[112:115], v[176:179], 0
	v_mfma_f32_16x16x32_bf16 v[76:79], v[96:99], v[200:203], 0
	v_mfma_f32_16x16x32_bf16 v[72:75], v[112:115], v[200:203], 0
	v_mfma_f32_16x16x32_bf16 v[140:143], v[100:103], v[164:167], v[140:143]
	v_mfma_f32_16x16x32_bf16 v[136:139], v[116:119], v[164:167], v[136:139]
	v_mfma_f32_16x16x32_bf16 v[124:127], v[100:103], v[172:175], v[124:127]
	v_mfma_f32_16x16x32_bf16 v[120:123], v[116:119], v[172:175], v[120:123]
	v_mfma_f32_16x16x32_bf16 v[92:95], v[100:103], v[180:183], v[92:95]
	v_mfma_f32_16x16x32_bf16 v[88:91], v[116:119], v[180:183], v[88:91]
	v_mfma_f32_16x16x32_bf16 v[76:79], v[100:103], v[204:207], v[76:79]
	v_mfma_f32_16x16x32_bf16 v[72:75], v[116:119], v[204:207], v[72:75]
	v_mfma_f32_16x16x32_bf16 v[132:135], v[144:147], v[160:163], 0
	v_mfma_f32_16x16x32_bf16 v[128:131], v[152:155], v[160:163], 0
	v_mfma_f32_16x16x32_bf16 v[108:111], v[144:147], v[168:171], 0
	v_mfma_f32_16x16x32_bf16 v[104:107], v[152:155], v[168:171], 0
	v_mfma_f32_16x16x32_bf16 v[84:87], v[144:147], v[176:179], 0
	v_mfma_f32_16x16x32_bf16 v[80:83], v[152:155], v[176:179], 0
	v_mfma_f32_16x16x32_bf16 v[68:71], v[144:147], v[200:203], 0
	v_mfma_f32_16x16x32_bf16 v[64:67], v[152:155], v[200:203], 0
	v_mfma_f32_16x16x32_bf16 v[132:135], v[148:151], v[164:167], v[132:135]
	v_mfma_f32_16x16x32_bf16 v[128:131], v[156:159], v[164:167], v[128:131]
	v_mfma_f32_16x16x32_bf16 v[108:111], v[148:151], v[172:175], v[108:111]
	v_mfma_f32_16x16x32_bf16 v[104:107], v[156:159], v[172:175], v[104:107]
	v_mfma_f32_16x16x32_bf16 v[84:87], v[148:151], v[180:183], v[84:87]
	v_mfma_f32_16x16x32_bf16 v[80:83], v[156:159], v[180:183], v[80:83]
	v_mfma_f32_16x16x32_bf16 v[68:71], v[148:151], v[204:207], v[68:71]
	v_mfma_f32_16x16x32_bf16 v[64:67], v[156:159], v[204:207], v[64:67]
	s_barrier
	s_add_i32 s73, s58, s17
	v_lshl_add_u64 v[208:209], s[40:41], 0, v[186:187]
	s_mov_b32 m0, s73
	ds_read_b128 v[160:163], v217 offset:16384
	ds_read_b128 v[164:167], v217 offset:17408
	ds_read_b128 v[168:171], v217 offset:18432
	ds_read_b128 v[172:175], v217 offset:19456
	ds_read_b128 v[176:179], v217 offset:20480
	ds_read_b128 v[180:183], v217 offset:21504
	ds_read_b128 v[200:203], v217 offset:22528
	ds_read_b128 v[204:207], v217 offset:23552
	global_load_lds_dwordx4 v[208:209], off
	s_add_i32 m0, s73, 0x2000
	s_add_u32 s76, s40, 0x80000
	v_lshl_add_u64 v[210:211], s[40:41], 0, v[190:191]
	s_addc_u32 s77, s41, 0
	s_add_i32 s73, s59, s17
	global_load_lds_dwordx4 v[210:211], off
	v_lshl_add_u64 v[218:219], s[76:77], 0, v[186:187]
	s_mov_b32 m0, s73
	v_lshl_add_u64 v[220:221], s[42:43], 0, v[188:189]
	global_load_lds_dwordx4 v[218:219], off
	v_lshl_add_u64 v[218:219], s[76:77], 0, v[190:191]
	s_add_i32 m0, s73, 0x2000
	s_nop 0
	global_load_lds_dwordx4 v[218:219], off
	v_lshl_add_u64 v[218:219], s[42:43], 0, v[184:185]
	s_mov_b32 m0, s48
	s_nop 0
	global_load_lds_dwordx4 v[218:219], off
	s_mov_b32 m0, s49
	s_nop 0
	global_load_lds_dwordx4 v[220:221], off
	s_waitcnt vmcnt(8) lgkmcnt(0)
	s_barrier
; #define PG8_STAGE(bufoff, gbase, voff) do { _Pragma("unroll") for (int _i = 0; _i < 2; ++_i) \
;         __builtin_amdgcn_global_load_lds((const unsigned*)((const char*)(gbase) + (voff)[_i]), (LAS unsigned*)(lds + (bufoff) + ldsw + _i * 8192), 16, 0, 0); } while (0)
; #define PG8_LDA(dst, b, h) do { _Pragma("unroll") for (int m = 0; m < 4; ++m) _Pragma("unroll") for (int k = 0; k < 2; ++k) dst[m][k] = *(const LAS bf16x8*)(lds + PG8_SA(b, h) + aoff + m * 2048 + k * 1024); } while (0)
; #define PG8_LDB(dst, b, h) do { _Pragma("unroll") for (int n = 0; n < 2; ++n) _Pragma("unroll") for (int k = 0; k < 2; ++k) dst[n][k] = *(const LAS bf16x8*)(lds + PG8_SB(b, h) + boff + n * 2048 + k * 1024); } while (0)
; #define PG8_MMA(ai, bj, At, Bt) do { __builtin_amdgcn_s_setprio(1); _Pragma("unroll") for (int m = 0; m < 4; ++m) _Pragma("unroll") for (int n = 0; n < 2; ++n) _Pragma("unroll") for (int k = 0; k < 2; ++k) \
;         acc[ai][bj][m][n] = __builtin_amdgcn_mfma_f32_16x16x32_bf16(Bt[n][k], At[m][k], acc[ai][bj][m][n], 0, 0, 0); __builtin_amdgcn_s_setprio(0); } while (0)
; #define PG8_WAIT_V(n) asm volatile("s_waitcnt vmcnt(" #n ")" ::: "memory")
; #define PG8_WAIT_L(n) asm volatile("s_waitcnt lgkmcnt(" #n ")" ::: "memory")
; #define PG8_BAR __builtin_amdgcn_s_barrier()
; #define PG8_SCHED __builtin_amdgcn_sched_barrier(0)
; template <class Epi, class Sched = StaticOrder, class EpiSub = NoSub, bool FAST = false>
; __device__ __forceinline__ void gemm_phase(LAS unsigned char* lds, const Gemm g, const Sched& S, const Epi& E, const EpiSub& ES = EpiSub()) {
;     ...
;             PG8_WAIT_V(8); PG8_WAIT_L(0); PG8_BAR; PG8_MMA(0, 0, At, B0); PG8_MMA(0, 1, At, B1); PG8_BAR; PG8_SCHED;
;             PG8_LDA(At, 0, 1); PG8_STAGE(PG8_SB(0, 0), b2, voffB); PG8_STAGE(PG8_SB(0, 1), b2 + hstepB, voffB); PG8_STAGE(PG8_SA(0, 0), a2, voffA);
;             PG8_WAIT_V(8); PG8_WAIT_L(0); PG8_BAR; PG8_MMA(1, 0, At, B0); PG8_MMA(1, 1, At, B1); PG8_BAR; PG8_SCHED;
;             PG8_LDB(B0, 1, 0); PG8_LDB(B1, 1, 1); PG8_SCHED; PG8_LDA(At, 1, 0); PG8_STAGE(PG8_SA(0, 1), a2 + hstepA, voffA);
;             PG8_WAIT_V(8); PG8_WAIT_L(0); PG8_BAR; PG8_MMA(0, 0, At, B0); PG8_MMA(0, 1, At, B1); PG8_BAR; PG8_SCHED;
	v_mfma_f32_16x16x32_bf16 v[60:63], v[96:99], v[160:163], 0
	v_mfma_f32_16x16x32_bf16 v[56:59], v[112:115], v[160:163], 0
	v_mfma_f32_16x16x32_bf16 v[44:47], v[96:99], v[168:171], 0
	v_mfma_f32_16x16x32_bf16 v[40:43], v[112:115], v[168:171], 0
	v_mfma_f32_16x16x32_bf16 v[28:31], v[96:99], v[176:179], 0
	v_mfma_f32_16x16x32_bf16 v[24:27], v[112:115], v[176:179], 0
	v_mfma_f32_16x16x32_bf16 v[12:15], v[96:99], v[200:203], 0
	v_mfma_f32_16x16x32_bf16 v[8:11], v[112:115], v[200:203], 0
	v_mfma_f32_16x16x32_bf16 v[60:63], v[100:103], v[164:167], v[60:63]
	v_mfma_f32_16x16x32_bf16 v[56:59], v[116:119], v[164:167], v[56:59]
	v_mfma_f32_16x16x32_bf16 v[44:47], v[100:103], v[172:175], v[44:47]
	v_mfma_f32_16x16x32_bf16 v[40:43], v[116:119], v[172:175], v[40:43]
	v_mfma_f32_16x16x32_bf16 v[28:31], v[100:103], v[180:183], v[28:31]
	v_mfma_f32_16x16x32_bf16 v[24:27], v[116:119], v[180:183], v[24:27]
	v_mfma_f32_16x16x32_bf16 v[12:15], v[100:103], v[204:207], v[12:15]
	v_mfma_f32_16x16x32_bf16 v[8:11], v[116:119], v[204:207], v[8:11]
	v_mfma_f32_16x16x32_bf16 v[52:55], v[144:147], v[160:163], 0
	v_mfma_f32_16x16x32_bf16 v[48:51], v[152:155], v[160:163], 0
	v_mfma_f32_16x16x32_bf16 v[36:39], v[144:147], v[168:171], 0
	v_mfma_f32_16x16x32_bf16 v[32:35], v[152:155], v[168:171], 0
	v_mfma_f32_16x16x32_bf16 v[20:23], v[144:147], v[176:179], 0
	v_mfma_f32_16x16x32_bf16 v[16:19], v[152:155], v[176:179], 0
	v_mfma_f32_16x16x32_bf16 v[4:7], v[144:147], v[200:203], 0
	v_mfma_f32_16x16x32_bf16 v[0:3], v[152:155], v[200:203], 0
	v_mfma_f32_16x16x32_bf16 v[52:55], v[148:151], v[164:167], v[52:55]
	v_mfma_f32_16x16x32_bf16 v[48:51], v[156:159], v[164:167], v[48:51]
	v_mfma_f32_16x16x32_bf16 v[36:39], v[148:151], v[172:175], v[36:39]
	v_mfma_f32_16x16x32_bf16 v[32:35], v[156:159], v[172:175], v[32:35]
	v_mfma_f32_16x16x32_bf16 v[20:23], v[148:151], v[180:183], v[20:23]
	v_mfma_f32_16x16x32_bf16 v[16:19], v[156:159], v[180:183], v[16:19]
	v_mfma_f32_16x16x32_bf16 v[4:7], v[148:151], v[204:207], v[4:7]
	v_mfma_f32_16x16x32_bf16 v[0:3], v[156:159], v[204:207], v[0:3]
	s_barrier
	s_add_i32 s73, 0, 0x18000
	s_add_i32 s76, 0, 0x1c000
	v_add_u32_e32 v116, s73, v212
	v_add_u32_e32 v156, s76, v212
	ds_read_b128 v[96:99], v116
	ds_read_b128 v[100:103], v116 offset:1024
	ds_read_b128 v[112:115], v116 offset:2048
	ds_read_b128 v[116:119], v116 offset:3072
	ds_read_b128 v[144:147], v156
	ds_read_b128 v[148:151], v156 offset:1024
	ds_read_b128 v[152:155], v156 offset:2048
	ds_read_b128 v[156:159], v156 offset:3072
	s_add_u32 s42, s42, 0x80000
	s_addc_u32 s43, s43, 0
	s_mov_b32 m0, s50
	v_lshl_add_u64 v[222:223], s[42:43], 0, v[184:185]
	ds_read_b128 v[160:163], v217 offset:32768
	ds_read_b128 v[164:167], v217 offset:33792
	ds_read_b128 v[168:171], v217 offset:34816
	ds_read_b128 v[172:175], v217 offset:35840
	ds_read_b128 v[176:179], v217 offset:36864
	ds_read_b128 v[180:183], v217 offset:37888
	ds_read_b128 v[200:203], v217 offset:38912
	ds_read_b128 v[204:207], v217 offset:39936
	global_load_lds_dwordx4 v[222:223], off
	v_lshl_add_u64 v[222:223], s[42:43], 0, v[188:189]
	s_mov_b32 m0, s51
	s_nop 0
	global_load_lds_dwordx4 v[222:223], off
	s_waitcnt vmcnt(8) lgkmcnt(0)
	s_barrier
	v_mfma_f32_16x16x32_bf16 v[140:143], v[96:99], v[160:163], v[140:143]
	v_mfma_f32_16x16x32_bf16 v[136:139], v[112:115], v[160:163], v[136:139]
	v_mfma_f32_16x16x32_bf16 v[124:127], v[96:99], v[168:171], v[124:127]
	v_mfma_f32_16x16x32_bf16 v[120:123], v[112:115], v[168:171], v[120:123]
	v_mfma_f32_16x16x32_bf16 v[92:95], v[96:99], v[176:179], v[92:95]
	v_mfma_f32_16x16x32_bf16 v[88:91], v[112:115], v[176:179], v[88:91]
	v_mfma_f32_16x16x32_bf16 v[76:79], v[96:99], v[200:203], v[76:79]
	v_mfma_f32_16x16x32_bf16 v[72:75], v[112:115], v[200:203], v[72:75]
	v_mfma_f32_16x16x32_bf16 v[140:143], v[100:103], v[164:167], v[140:143]
	v_mfma_f32_16x16x32_bf16 v[136:139], v[116:119], v[164:167], v[136:139]
	v_mfma_f32_16x16x32_bf16 v[124:127], v[100:103], v[172:175], v[124:127]
	v_mfma_f32_16x16x32_bf16 v[120:123], v[116:119], v[172:175], v[120:123]
	v_mfma_f32_16x16x32_bf16 v[92:95], v[100:103], v[180:183], v[92:95]
	v_mfma_f32_16x16x32_bf16 v[88:91], v[116:119], v[180:183], v[88:91]
	v_mfma_f32_16x16x32_bf16 v[76:79], v[100:103], v[204:207], v[76:79]
	v_mfma_f32_16x16x32_bf16 v[72:75], v[116:119], v[204:207], v[72:75]
	v_mfma_f32_16x16x32_bf16 v[132:135], v[144:147], v[160:163], v[132:135]
	v_mfma_f32_16x16x32_bf16 v[128:131], v[152:155], v[160:163], v[128:131]
	v_mfma_f32_16x16x32_bf16 v[108:111], v[144:147], v[168:171], v[108:111]
	v_mfma_f32_16x16x32_bf16 v[104:107], v[152:155], v[168:171], v[104:107]
	v_mfma_f32_16x16x32_bf16 v[84:87], v[144:147], v[176:179], v[84:87]
	v_mfma_f32_16x16x32_bf16 v[80:83], v[152:155], v[176:179], v[80:83]
	v_mfma_f32_16x16x32_bf16 v[68:71], v[144:147], v[200:203], v[68:71]
	v_mfma_f32_16x16x32_bf16 v[64:67], v[152:155], v[200:203], v[64:67]
	v_mfma_f32_16x16x32_bf16 v[132:135], v[148:151], v[164:167], v[132:135]
	v_mfma_f32_16x16x32_bf16 v[128:131], v[156:159], v[164:167], v[128:131]
	v_mfma_f32_16x16x32_bf16 v[108:111], v[148:151], v[172:175], v[108:111]
	v_mfma_f32_16x16x32_bf16 v[104:107], v[156:159], v[172:175], v[104:107]
	v_mfma_f32_16x16x32_bf16 v[84:87], v[148:151], v[180:183], v[84:87]
	v_mfma_f32_16x16x32_bf16 v[80:83], v[156:159], v[180:183], v[80:83]
	v_mfma_f32_16x16x32_bf16 v[68:71], v[148:151], v[204:207], v[68:71]
	v_mfma_f32_16x16x32_bf16 v[64:67], v[156:159], v[204:207], v[64:67]
	s_barrier
; #define PG8_STAGE(bufoff, gbase, voff) do { _Pragma("unroll") for (int _i = 0; _i < 2; ++_i) \
;         __builtin_amdgcn_global_load_lds((const unsigned*)((const char*)(gbase) + (voff)[_i]), (LAS unsigned*)(lds + (bufoff) + ldsw + _i * 8192), 16, 0, 0); } while (0)
; #define PG8_LDA(dst, b, h) do { _Pragma("unroll") for (int m = 0; m < 4; ++m) _Pragma("unroll") for (int k = 0; k < 2; ++k) dst[m][k] = *(const LAS bf16x8*)(lds + PG8_SA(b, h) + aoff + m * 2048 + k * 1024); } while (0)
; #define PG8_LDB(dst, b, h) do { _Pragma("unroll") for (int n = 0; n < 2; ++n) _Pragma("unroll") for (int k = 0; k < 2; ++k) dst[n][k] = *(const LAS bf16x8*)(lds + PG8_SB(b, h) + boff + n * 2048 + k * 1024); } while (0)
; template <class Epi, class Sched = StaticOrder, class EpiSub = NoSub, bool FAST = false>
; __device__ __forceinline__ void gemm_phase(LAS unsigned char* lds, const Gemm g, const Sched& S, const Epi& E, const EpiSub& ES = EpiSub()) {
;     ...
;         for (int t = 0; t < nt; t += 2) {
;             const bool last = (t == nt - 2);
;             const char* a1 = cA + (size_t)(t + 1) * kstep;
;             const char* a2 = last ? nA : cA + (size_t)(t + 2) * kstep; const char* b2 = last ? nB : cB + (size_t)(t + 2) * kstep;
;             const char* a3 = a2 + kstep; const char* b3 = b2 + kstep;
;             if constexpr (FAST && PG8_SP2) {
;             PG8_LDB(B0, 0, 0); PG8_LDB(B1, 0, 1); PG8_SCHED; PG8_LDA(At, 0, 0); PG8_STAGE(PG8_SA(1, 1), a1 + hstepA, voffA);
;             PG8_WAIT_V(8); PG8_WAIT_L(0); PG8_BAR; PG8_MMA(0, 0, At, B0); PG8_MMA(0, 1, At, B1); PG8_BAR; PG8_SCHED;
;             PG8_LDA(At, 0, 1); PG8_STAGE(PG8_SB(0, 0), b2, voffB); PG8_STAGE(PG8_SB(0, 1), b2 + hstepB, voffB); PG8_STAGE(PG8_SA(0, 0), a2, voffA);
;             PG8_WAIT_V(8); PG8_WAIT_L(0); PG8_BAR; PG8_MMA(1, 0, At, B0); PG8_MMA(1, 1, At, B1); PG8_BAR; PG8_SCHED;
;             PG8_LDB(B0, 1, 0); PG8_LDB(B1, 1, 1); PG8_SCHED; PG8_LDA(At, 1, 0); PG8_STAGE(PG8_SA(0, 1), a2 + hstepA, voffA);
;             PG8_WAIT_V(8); PG8_WAIT_L(0); PG8_BAR; PG8_MMA(0, 0, At, B0); PG8_MMA(0, 1, At, B1); PG8_BAR; PG8_SCHED;
;             PG8_LDA(At, 1, 1); PG8_STAGE(PG8_SB(1, 0), b3, voffB); PG8_STAGE(PG8_SB(1, 1), b3 + hstepB, voffB); PG8_STAGE(PG8_SA(1, 0), a3, voffA);
;             PG8_WAIT_V(8); PG8_WAIT_L(0); PG8_BAR; PG8_MMA(1, 0, At, B0); PG8_MMA(1, 1, At, B1); PG8_BAR; PG8_SCHED;
	s_add_i32 s42, s73, s17
	v_lshl_add_u64 v[208:209], v[208:209], 0, s[12:13]
	s_mov_b32 m0, s42
	ds_read_b128 v[160:163], v217 offset:49152
	ds_read_b128 v[164:167], v217 offset:50176
	ds_read_b128 v[168:171], v217 offset:51200
	ds_read_b128 v[172:175], v217 offset:52224
	ds_read_b128 v[176:179], v217 offset:53248
	ds_read_b128 v[180:183], v217 offset:54272
	ds_read_b128 v[200:203], v217 offset:55296
	ds_read_b128 v[204:207], v217 offset:56320
	global_load_lds_dwordx4 v[208:209], off
	s_add_i32 m0, s42, 0x2000
	s_add_u32 s40, s40, 0x80080
	v_lshl_add_u64 v[208:209], v[210:211], 0, s[12:13]
	s_addc_u32 s41, s41, 0
	s_add_i32 s42, s76, s17
	global_load_lds_dwordx4 v[208:209], off
	v_lshl_add_u64 v[208:209], s[40:41], 0, v[186:187]
	s_mov_b32 m0, s42
	s_nop 0
	global_load_lds_dwordx4 v[208:209], off
	v_lshl_add_u64 v[208:209], s[40:41], 0, v[190:191]
	s_add_i32 m0, s42, 0x2000
	s_nop 0
	global_load_lds_dwordx4 v[208:209], off
	v_lshl_add_u64 v[208:209], v[218:219], 0, s[12:13]
	s_mov_b32 m0, s55
	s_nop 0
	global_load_lds_dwordx4 v[208:209], off
	v_lshl_add_u64 v[208:209], v[220:221], 0, s[12:13]
	s_mov_b32 m0, s56
	s_nop 0
	global_load_lds_dwordx4 v[208:209], off
	s_waitcnt vmcnt(8) lgkmcnt(0)
	s_barrier
	v_mfma_f32_16x16x32_bf16 v[60:63], v[96:99], v[160:163], v[60:63]
	v_mfma_f32_16x16x32_bf16 v[56:59], v[112:115], v[160:163], v[56:59]
	v_mfma_f32_16x16x32_bf16 v[44:47], v[96:99], v[168:171], v[44:47]
	v_mfma_f32_16x16x32_bf16 v[40:43], v[112:115], v[168:171], v[40:43]
	v_mfma_f32_16x16x32_bf16 v[28:31], v[96:99], v[176:179], v[28:31]
	v_mfma_f32_16x16x32_bf16 v[24:27], v[112:115], v[176:179], v[24:27]
	v_mfma_f32_16x16x32_bf16 v[12:15], v[96:99], v[200:203], v[12:15]
	v_mfma_f32_16x16x32_bf16 v[8:11], v[112:115], v[200:203], v[8:11]
	v_mfma_f32_16x16x32_bf16 v[60:63], v[100:103], v[164:167], v[60:63]
	v_mfma_f32_16x16x32_bf16 v[56:59], v[116:119], v[164:167], v[56:59]
	v_mfma_f32_16x16x32_bf16 v[44:47], v[100:103], v[172:175], v[44:47]
	v_mfma_f32_16x16x32_bf16 v[40:43], v[116:119], v[172:175], v[40:43]
	v_mfma_f32_16x16x32_bf16 v[28:31], v[100:103], v[180:183], v[28:31]
	v_mfma_f32_16x16x32_bf16 v[24:27], v[116:119], v[180:183], v[24:27]
	v_mfma_f32_16x16x32_bf16 v[12:15], v[100:103], v[204:207], v[12:15]
	v_mfma_f32_16x16x32_bf16 v[8:11], v[116:119], v[204:207], v[8:11]
	v_mfma_f32_16x16x32_bf16 v[52:55], v[144:147], v[160:163], v[52:55]
	v_mfma_f32_16x16x32_bf16 v[48:51], v[152:155], v[160:163], v[48:51]
	v_mfma_f32_16x16x32_bf16 v[36:39], v[144:147], v[168:171], v[36:39]
	v_mfma_f32_16x16x32_bf16 v[32:35], v[152:155], v[168:171], v[32:35]
	v_mfma_f32_16x16x32_bf16 v[20:23], v[144:147], v[176:179], v[20:23]
	v_mfma_f32_16x16x32_bf16 v[16:19], v[152:155], v[176:179], v[16:19]
	v_mfma_f32_16x16x32_bf16 v[4:7], v[144:147], v[200:203], v[4:7]
	v_mfma_f32_16x16x32_bf16 v[0:3], v[152:155], v[200:203], v[0:3]
	v_mfma_f32_16x16x32_bf16 v[52:55], v[148:151], v[164:167], v[52:55]
	v_mfma_f32_16x16x32_bf16 v[48:51], v[156:159], v[164:167], v[48:51]
	v_mfma_f32_16x16x32_bf16 v[36:39], v[148:151], v[172:175], v[36:39]
	v_mfma_f32_16x16x32_bf16 v[32:35], v[156:159], v[172:175], v[32:35]
	v_mfma_f32_16x16x32_bf16 v[20:23], v[148:151], v[180:183], v[20:23]
	v_mfma_f32_16x16x32_bf16 v[16:19], v[156:159], v[180:183], v[16:19]
	v_mfma_f32_16x16x32_bf16 v[4:7], v[148:151], v[204:207], v[4:7]
	v_mfma_f32_16x16x32_bf16 v[0:3], v[156:159], v[204:207], v[0:3]
	s_barrier
	s_add_u32 s38, s38, 0x100
	s_addc_u32 s39, s39, 0
	s_add_u32 s70, s70, 0x100
	s_addc_u32 s71, s71, 0
	s_cmp_ge_u32 s72, s29
	s_mov_b32 s42, s72
	s_cbranch_scc1 .Lkpeel_769_exit
.LBB0_769:
	ds_read_b128 v[96:99], v215
	ds_read_b128 v[100:103], v215 offset:1024
	ds_read_b128 v[112:115], v215 offset:2048
	ds_read_b128 v[116:119], v215 offset:3072
	ds_read_b128 v[144:147], v216
	ds_read_b128 v[148:151], v216 offset:1024
	ds_read_b128 v[152:155], v216 offset:2048
	ds_read_b128 v[156:159], v216 offset:3072
	s_add_i32 s72, s42, 2
	s_add_u32 s40, s38, 0xfff80080
	s_addc_u32 s41, s39, -1
	s_cmp_eq_u32 s33, s42
	s_cselect_b32 s42, s5, s40
	s_cselect_b32 s43, s1, s41
	s_cselect_b32 s41, s19, s71
	s_cselect_b32 s40, s21, s70
	v_lshl_add_u64 v[208:209], s[38:39], 0, v[194:195]
	s_add_i32 m0, s48, 0xc000
	ds_read_b128 v[160:163], v217
	ds_read_b128 v[164:167], v217 offset:1024
	ds_read_b128 v[168:171], v217 offset:2048
	ds_read_b128 v[172:175], v217 offset:3072
	ds_read_b128 v[176:179], v217 offset:4096
	ds_read_b128 v[180:183], v217 offset:5120
	ds_read_b128 v[200:203], v217 offset:6144
	ds_read_b128 v[204:207], v217 offset:7168
	global_load_lds_dwordx4 v[208:209], off
	v_lshl_add_u64 v[208:209], s[38:39], 0, v[196:197]
	s_add_i32 m0, s48, 0xe000
	s_nop 0
	global_load_lds_dwordx4 v[208:209], off
	s_waitcnt vmcnt(8) lgkmcnt(0)
	s_barrier
; #define PG8_STAGE(bufoff, gbase, voff) do { _Pragma("unroll") for (int _i = 0; _i < 2; ++_i) \
;         __builtin_amdgcn_global_load_lds((const unsigned*)((const char*)(gbase) + (voff)[_i]), (LAS unsigned*)(lds + (bufoff) + ldsw + _i * 8192), 16, 0, 0); } while (0)
; #define PG8_LDA(dst, b, h) do { _Pragma("unroll") for (int m = 0; m < 4; ++m) _Pragma("unroll") for (int k = 0; k < 2; ++k) dst[m][k] = *(const LAS bf16x8*)(lds + PG8_SA(b, h) + aoff + m * 2048 + k * 1024); } while (0)
; #define PG8_LDB(dst, b, h) do { _Pragma("unroll") for (int n = 0; n < 2; ++n) _Pragma("unroll") for (int k = 0; k < 2; ++k) dst[n][k] = *(const LAS bf16x8*)(lds + PG8_SB(b, h) + boff + n * 2048 + k * 1024); } while (0)
; #define PG8_MMA(ai, bj, At, Bt) do { __builtin_amdgcn_s_setprio(1); _Pragma("unroll") for (int m = 0; m < 4; ++m) _Pragma("unroll") for (int n = 0; n < 2; ++n) _Pragma("unroll") for (int k = 0; k < 2; ++k) \
;         acc[ai][bj][m][n] = __builtin_amdgcn_mfma_f32_16x16x32_bf16(Bt[n][k], At[m][k], acc[ai][bj][m][n], 0, 0, 0); __builtin_amdgcn_s_setprio(0); } while (0)
; #define PG8_WAIT_V(n) asm volatile("s_waitcnt vmcnt(" #n ")" ::: "memory")
; #define PG8_WAIT_L(n) asm volatile("s_waitcnt lgkmcnt(" #n ")" ::: "memory")
; #define PG8_BAR __builtin_amdgcn_s_barrier()
; #define PG8_SCHED __builtin_amdgcn_sched_barrier(0)
; template <class Epi, class Sched = StaticOrder, class EpiSub = NoSub, bool FAST = false>
; __device__ __forceinline__ void gemm_phase(LAS unsigned char* lds, const Gemm g, const Sched& S, const Epi& E, const EpiSub& ES = EpiSub()) {
;     ...
;             PG8_LDB(B0, 0, 0); PG8_LDB(B1, 0, 1); PG8_SCHED; PG8_LDA(At, 0, 0); PG8_STAGE(PG8_SA(1, 1), a1 + hstepA, voffA);
;             PG8_WAIT_V(8); PG8_WAIT_L(0); PG8_BAR; PG8_MMA(0, 0, At, B0); PG8_MMA(0, 1, At, B1); PG8_BAR; PG8_SCHED;
;             PG8_LDA(At, 0, 1); PG8_STAGE(PG8_SB(0, 0), b2, voffB); PG8_STAGE(PG8_SB(0, 1), b2 + hstepB, voffB); PG8_STAGE(PG8_SA(0, 0), a2, voffA);
;             PG8_WAIT_V(8); PG8_WAIT_L(0); PG8_BAR; PG8_MMA(1, 0, At, B0); PG8_MMA(1, 1, At, B1); PG8_BAR; PG8_SCHED;
	v_mfma_f32_16x16x32_bf16 v[140:143], v[96:99], v[160:163], v[140:143]
	v_mfma_f32_16x16x32_bf16 v[136:139], v[112:115], v[160:163], v[136:139]
	v_mfma_f32_16x16x32_bf16 v[124:127], v[96:99], v[168:171], v[124:127]
	v_mfma_f32_16x16x32_bf16 v[120:123], v[112:115], v[168:171], v[120:123]
	v_mfma_f32_16x16x32_bf16 v[92:95], v[96:99], v[176:179], v[92:95]
	v_mfma_f32_16x16x32_bf16 v[88:91], v[112:115], v[176:179], v[88:91]
	v_mfma_f32_16x16x32_bf16 v[76:79], v[96:99], v[200:203], v[76:79]
	v_mfma_f32_16x16x32_bf16 v[72:75], v[112:115], v[200:203], v[72:75]
	v_mfma_f32_16x16x32_bf16 v[140:143], v[100:103], v[164:167], v[140:143]
	v_mfma_f32_16x16x32_bf16 v[136:139], v[116:119], v[164:167], v[136:139]
	v_mfma_f32_16x16x32_bf16 v[124:127], v[100:103], v[172:175], v[124:127]
	v_mfma_f32_16x16x32_bf16 v[120:123], v[116:119], v[172:175], v[120:123]
	v_mfma_f32_16x16x32_bf16 v[92:95], v[100:103], v[180:183], v[92:95]
	v_mfma_f32_16x16x32_bf16 v[88:91], v[116:119], v[180:183], v[88:91]
	v_mfma_f32_16x16x32_bf16 v[76:79], v[100:103], v[204:207], v[76:79]
	v_mfma_f32_16x16x32_bf16 v[72:75], v[116:119], v[204:207], v[72:75]
	v_mfma_f32_16x16x32_bf16 v[132:135], v[144:147], v[160:163], v[132:135]
	v_mfma_f32_16x16x32_bf16 v[128:131], v[152:155], v[160:163], v[128:131]
	v_mfma_f32_16x16x32_bf16 v[108:111], v[144:147], v[168:171], v[108:111]
	v_mfma_f32_16x16x32_bf16 v[104:107], v[152:155], v[168:171], v[104:107]
	v_mfma_f32_16x16x32_bf16 v[84:87], v[144:147], v[176:179], v[84:87]
	v_mfma_f32_16x16x32_bf16 v[80:83], v[152:155], v[176:179], v[80:83]
	v_mfma_f32_16x16x32_bf16 v[68:71], v[144:147], v[200:203], v[68:71]
	v_mfma_f32_16x16x32_bf16 v[64:67], v[152:155], v[200:203], v[64:67]
	v_mfma_f32_16x16x32_bf16 v[132:135], v[148:151], v[164:167], v[132:135]
	v_mfma_f32_16x16x32_bf16 v[128:131], v[156:159], v[164:167], v[128:131]
	v_mfma_f32_16x16x32_bf16 v[108:111], v[148:151], v[172:175], v[108:111]
	v_mfma_f32_16x16x32_bf16 v[104:107], v[156:159], v[172:175], v[104:107]
	v_mfma_f32_16x16x32_bf16 v[84:87], v[148:151], v[180:183], v[84:87]
	v_mfma_f32_16x16x32_bf16 v[80:83], v[156:159], v[180:183], v[80:83]
	v_mfma_f32_16x16x32_bf16 v[68:71], v[148:151], v[204:207], v[68:71]
	v_mfma_f32_16x16x32_bf16 v[64:67], v[156:159], v[204:207], v[64:67]
	s_barrier
	s_add_i32 s73, s58, s17
	v_lshl_add_u64 v[208:209], s[40:41], 0, v[186:187]
	s_mov_b32 m0, s73
	ds_read_b128 v[160:163], v217 offset:16384
	ds_read_b128 v[164:167], v217 offset:17408
	ds_read_b128 v[168:171], v217 offset:18432
	ds_read_b128 v[172:175], v217 offset:19456
	ds_read_b128 v[176:179], v217 offset:20480
	ds_read_b128 v[180:183], v217 offset:21504
	ds_read_b128 v[200:203], v217 offset:22528
	ds_read_b128 v[204:207], v217 offset:23552
	global_load_lds_dwordx4 v[208:209], off
	s_add_i32 m0, s73, 0x2000
	s_add_u32 s76, s40, 0x80000
	v_lshl_add_u64 v[210:211], s[40:41], 0, v[190:191]
	s_addc_u32 s77, s41, 0
	s_add_i32 s73, s59, s17
	global_load_lds_dwordx4 v[210:211], off
	v_lshl_add_u64 v[218:219], s[76:77], 0, v[186:187]
	s_mov_b32 m0, s73
	v_lshl_add_u64 v[220:221], s[42:43], 0, v[188:189]
	global_load_lds_dwordx4 v[218:219], off
	v_lshl_add_u64 v[218:219], s[76:77], 0, v[190:191]
	s_add_i32 m0, s73, 0x2000
	s_nop 0
	global_load_lds_dwordx4 v[218:219], off
	v_lshl_add_u64 v[218:219], s[42:43], 0, v[184:185]
	s_mov_b32 m0, s48
	s_nop 0
	global_load_lds_dwordx4 v[218:219], off
	s_mov_b32 m0, s49
	s_nop 0
	global_load_lds_dwordx4 v[220:221], off
	s_waitcnt vmcnt(8) lgkmcnt(0)
	s_barrier
	v_mfma_f32_16x16x32_bf16 v[60:63], v[96:99], v[160:163], v[60:63]
	v_mfma_f32_16x16x32_bf16 v[56:59], v[112:115], v[160:163], v[56:59]
	v_mfma_f32_16x16x32_bf16 v[44:47], v[96:99], v[168:171], v[44:47]
	v_mfma_f32_16x16x32_bf16 v[40:43], v[112:115], v[168:171], v[40:43]
	v_mfma_f32_16x16x32_bf16 v[28:31], v[96:99], v[176:179], v[28:31]
	v_mfma_f32_16x16x32_bf16 v[24:27], v[112:115], v[176:179], v[24:27]
	v_mfma_f32_16x16x32_bf16 v[12:15], v[96:99], v[200:203], v[12:15]
	v_mfma_f32_16x16x32_bf16 v[8:11], v[112:115], v[200:203], v[8:11]
	v_mfma_f32_16x16x32_bf16 v[60:63], v[100:103], v[164:167], v[60:63]
	v_mfma_f32_16x16x32_bf16 v[56:59], v[116:119], v[164:167], v[56:59]
	v_mfma_f32_16x16x32_bf16 v[44:47], v[100:103], v[172:175], v[44:47]
	v_mfma_f32_16x16x32_bf16 v[40:43], v[116:119], v[172:175], v[40:43]
	v_mfma_f32_16x16x32_bf16 v[28:31], v[100:103], v[180:183], v[28:31]
	v_mfma_f32_16x16x32_bf16 v[24:27], v[116:119], v[180:183], v[24:27]
	v_mfma_f32_16x16x32_bf16 v[12:15], v[100:103], v[204:207], v[12:15]
	v_mfma_f32_16x16x32_bf16 v[8:11], v[116:119], v[204:207], v[8:11]
	v_mfma_f32_16x16x32_bf16 v[52:55], v[144:147], v[160:163], v[52:55]
	v_mfma_f32_16x16x32_bf16 v[48:51], v[152:155], v[160:163], v[48:51]
	v_mfma_f32_16x16x32_bf16 v[36:39], v[144:147], v[168:171], v[36:39]
	v_mfma_f32_16x16x32_bf16 v[32:35], v[152:155], v[168:171], v[32:35]
	v_mfma_f32_16x16x32_bf16 v[20:23], v[144:147], v[176:179], v[20:23]
	v_mfma_f32_16x16x32_bf16 v[16:19], v[152:155], v[176:179], v[16:19]
	v_mfma_f32_16x16x32_bf16 v[4:7], v[144:147], v[200:203], v[4:7]
	v_mfma_f32_16x16x32_bf16 v[0:3], v[152:155], v[200:203], v[0:3]
	v_mfma_f32_16x16x32_bf16 v[52:55], v[148:151], v[164:167], v[52:55]
	v_mfma_f32_16x16x32_bf16 v[48:51], v[156:159], v[164:167], v[48:51]
	v_mfma_f32_16x16x32_bf16 v[36:39], v[148:151], v[172:175], v[36:39]
	v_mfma_f32_16x16x32_bf16 v[32:35], v[156:159], v[172:175], v[32:35]
	v_mfma_f32_16x16x32_bf16 v[20:23], v[148:151], v[180:183], v[20:23]
	v_mfma_f32_16x16x32_bf16 v[16:19], v[156:159], v[180:183], v[16:19]
	v_mfma_f32_16x16x32_bf16 v[4:7], v[148:151], v[204:207], v[4:7]
	v_mfma_f32_16x16x32_bf16 v[0:3], v[156:159], v[204:207], v[0:3]
	s_barrier
; #define PG8_STAGE(bufoff, gbase, voff) do { _Pragma("unroll") for (int _i = 0; _i < 2; ++_i) \
;         __builtin_amdgcn_global_load_lds((const unsigned*)((const char*)(gbase) + (voff)[_i]), (LAS unsigned*)(lds + (bufoff) + ldsw + _i * 8192), 16, 0, 0); } while (0)
; #define PG8_LDA(dst, b, h) do { _Pragma("unroll") for (int m = 0; m < 4; ++m) _Pragma("unroll") for (int k = 0; k < 2; ++k) dst[m][k] = *(const LAS bf16x8*)(lds + PG8_SA(b, h) + aoff + m * 2048 + k * 1024); } while (0)
; #define PG8_LDB(dst, b, h) do { _Pragma("unroll") for (int n = 0; n < 2; ++n) _Pragma("unroll") for (int k = 0; k < 2; ++k) dst[n][k] = *(const LAS bf16x8*)(lds + PG8_SB(b, h) + boff + n * 2048 + k * 1024); } while (0)
; #define PG8_MMA(ai, bj, At, Bt) do { __builtin_amdgcn_s_setprio(1); _Pragma("unroll") for (int m = 0; m < 4; ++m) _Pragma("unroll") for (int n = 0; n < 2; ++n) _Pragma("unroll") for (int k = 0; k < 2; ++k) \
;         acc[ai][bj][m][n] = __builtin_amdgcn_mfma_f32_16x16x32_bf16(Bt[n][k], At[m][k], acc[ai][bj][m][n], 0, 0, 0); __builtin_amdgcn_s_setprio(0); } while (0)
; #define PG8_WAIT_V(n) asm volatile("s_waitcnt vmcnt(" #n ")" ::: "memory")
; #define PG8_WAIT_L(n) asm volatile("s_waitcnt lgkmcnt(" #n ")" ::: "memory")
; #define PG8_BAR __builtin_amdgcn_s_barrier()
; #define PG8_SCHED __builtin_amdgcn_sched_barrier(0)
; template <class Epi, class Sched = StaticOrder, class EpiSub = NoSub, bool FAST = false>
; __device__ __forceinline__ void gemm_phase(LAS unsigned char* lds, const Gemm g, const Sched& S, const Epi& E, const EpiSub& ES = EpiSub()) {
;     ...
;             PG8_LDB(B0, 1, 0); PG8_LDB(B1, 1, 1); PG8_SCHED; PG8_LDA(At, 1, 0); PG8_STAGE(PG8_SA(0, 1), a2 + hstepA, voffA);
;             PG8_WAIT_V(8); PG8_WAIT_L(0); PG8_BAR; PG8_MMA(0, 0, At, B0); PG8_MMA(0, 1, At, B1); PG8_BAR; PG8_SCHED;
;             PG8_LDA(At, 1, 1); PG8_STAGE(PG8_SB(1, 0), b3, voffB); PG8_STAGE(PG8_SB(1, 1), b3 + hstepB, voffB); PG8_STAGE(PG8_SA(1, 0), a3, voffA);
;             PG8_WAIT_V(8); PG8_WAIT_L(0); PG8_BAR; PG8_MMA(1, 0, At, B0); PG8_MMA(1, 1, At, B1); PG8_BAR; PG8_SCHED;
	s_add_i32 s73, 0, 0x18000
	s_add_i32 s76, 0, 0x1c000
	v_add_u32_e32 v116, s73, v212
	v_add_u32_e32 v156, s76, v212
	ds_read_b128 v[96:99], v116
	ds_read_b128 v[100:103], v116 offset:1024
	ds_read_b128 v[112:115], v116 offset:2048
	ds_read_b128 v[116:119], v116 offset:3072
	ds_read_b128 v[144:147], v156
	ds_read_b128 v[148:151], v156 offset:1024
	ds_read_b128 v[152:155], v156 offset:2048
	ds_read_b128 v[156:159], v156 offset:3072
	s_add_u32 s42, s42, 0x80000
	s_addc_u32 s43, s43, 0
	s_mov_b32 m0, s50
	v_lshl_add_u64 v[222:223], s[42:43], 0, v[184:185]
	ds_read_b128 v[160:163], v217 offset:32768
	ds_read_b128 v[164:167], v217 offset:33792
	ds_read_b128 v[168:171], v217 offset:34816
	ds_read_b128 v[172:175], v217 offset:35840
	ds_read_b128 v[176:179], v217 offset:36864
	ds_read_b128 v[180:183], v217 offset:37888
	ds_read_b128 v[200:203], v217 offset:38912
	ds_read_b128 v[204:207], v217 offset:39936
	global_load_lds_dwordx4 v[222:223], off
	v_lshl_add_u64 v[222:223], s[42:43], 0, v[188:189]
	s_mov_b32 m0, s51
	s_nop 0
	global_load_lds_dwordx4 v[222:223], off
	s_waitcnt vmcnt(8) lgkmcnt(0)
	s_barrier
	v_mfma_f32_16x16x32_bf16 v[140:143], v[96:99], v[160:163], v[140:143]
	v_mfma_f32_16x16x32_bf16 v[136:139], v[112:115], v[160:163], v[136:139]
	v_mfma_f32_16x16x32_bf16 v[124:127], v[96:99], v[168:171], v[124:127]
	v_mfma_f32_16x16x32_bf16 v[120:123], v[112:115], v[168:171], v[120:123]
	v_mfma_f32_16x16x32_bf16 v[92:95], v[96:99], v[176:179], v[92:95]
	v_mfma_f32_16x16x32_bf16 v[88:91], v[112:115], v[176:179], v[88:91]
	v_mfma_f32_16x16x32_bf16 v[76:79], v[96:99], v[200:203], v[76:79]
	v_mfma_f32_16x16x32_bf16 v[72:75], v[112:115], v[200:203], v[72:75]
	v_mfma_f32_16x16x32_bf16 v[140:143], v[100:103], v[164:167], v[140:143]
	v_mfma_f32_16x16x32_bf16 v[136:139], v[116:119], v[164:167], v[136:139]
	v_mfma_f32_16x16x32_bf16 v[124:127], v[100:103], v[172:175], v[124:127]
	v_mfma_f32_16x16x32_bf16 v[120:123], v[116:119], v[172:175], v[120:123]
	v_mfma_f32_16x16x32_bf16 v[92:95], v[100:103], v[180:183], v[92:95]
	v_mfma_f32_16x16x32_bf16 v[88:91], v[116:119], v[180:183], v[88:91]
	v_mfma_f32_16x16x32_bf16 v[76:79], v[100:103], v[204:207], v[76:79]
	v_mfma_f32_16x16x32_bf16 v[72:75], v[116:119], v[204:207], v[72:75]
	v_mfma_f32_16x16x32_bf16 v[132:135], v[144:147], v[160:163], v[132:135]
	v_mfma_f32_16x16x32_bf16 v[128:131], v[152:155], v[160:163], v[128:131]
	v_mfma_f32_16x16x32_bf16 v[108:111], v[144:147], v[168:171], v[108:111]
	v_mfma_f32_16x16x32_bf16 v[104:107], v[152:155], v[168:171], v[104:107]
	v_mfma_f32_16x16x32_bf16 v[84:87], v[144:147], v[176:179], v[84:87]
	v_mfma_f32_16x16x32_bf16 v[80:83], v[152:155], v[176:179], v[80:83]
	v_mfma_f32_16x16x32_bf16 v[68:71], v[144:147], v[200:203], v[68:71]
	v_mfma_f32_16x16x32_bf16 v[64:67], v[152:155], v[200:203], v[64:67]
	v_mfma_f32_16x16x32_bf16 v[132:135], v[148:151], v[164:167], v[132:135]
	v_mfma_f32_16x16x32_bf16 v[128:131], v[156:159], v[164:167], v[128:131]
	v_mfma_f32_16x16x32_bf16 v[108:111], v[148:151], v[172:175], v[108:111]
	v_mfma_f32_16x16x32_bf16 v[104:107], v[156:159], v[172:175], v[104:107]
	v_mfma_f32_16x16x32_bf16 v[84:87], v[148:151], v[180:183], v[84:87]
	v_mfma_f32_16x16x32_bf16 v[80:83], v[156:159], v[180:183], v[80:83]
	v_mfma_f32_16x16x32_bf16 v[68:71], v[148:151], v[204:207], v[68:71]
	v_mfma_f32_16x16x32_bf16 v[64:67], v[156:159], v[204:207], v[64:67]
	s_barrier
	s_add_i32 s42, s73, s17
	v_lshl_add_u64 v[208:209], v[208:209], 0, s[12:13]
	s_mov_b32 m0, s42
	ds_read_b128 v[160:163], v217 offset:49152
	ds_read_b128 v[164:167], v217 offset:50176
	ds_read_b128 v[168:171], v217 offset:51200
	ds_read_b128 v[172:175], v217 offset:52224
	ds_read_b128 v[176:179], v217 offset:53248
	ds_read_b128 v[180:183], v217 offset:54272
	ds_read_b128 v[200:203], v217 offset:55296
	ds_read_b128 v[204:207], v217 offset:56320
	global_load_lds_dwordx4 v[208:209], off
	s_add_i32 m0, s42, 0x2000
	s_add_u32 s40, s40, 0x80080
	v_lshl_add_u64 v[208:209], v[210:211], 0, s[12:13]
	s_addc_u32 s41, s41, 0
	s_add_i32 s42, s76, s17
	global_load_lds_dwordx4 v[208:209], off
	v_lshl_add_u64 v[208:209], s[40:41], 0, v[186:187]
	s_mov_b32 m0, s42
	s_nop 0
	global_load_lds_dwordx4 v[208:209], off
	v_lshl_add_u64 v[208:209], s[40:41], 0, v[190:191]
	s_add_i32 m0, s42, 0x2000
	s_nop 0
	global_load_lds_dwordx4 v[208:209], off
	v_lshl_add_u64 v[208:209], v[218:219], 0, s[12:13]
	s_mov_b32 m0, s55
	s_nop 0
	global_load_lds_dwordx4 v[208:209], off
	v_lshl_add_u64 v[208:209], v[220:221], 0, s[12:13]
	s_mov_b32 m0, s56
	s_nop 0
	global_load_lds_dwordx4 v[208:209], off
	s_waitcnt vmcnt(8) lgkmcnt(0)
	s_barrier
	v_mfma_f32_16x16x32_bf16 v[60:63], v[96:99], v[160:163], v[60:63]
	v_mfma_f32_16x16x32_bf16 v[56:59], v[112:115], v[160:163], v[56:59]
	v_mfma_f32_16x16x32_bf16 v[44:47], v[96:99], v[168:171], v[44:47]
	v_mfma_f32_16x16x32_bf16 v[40:43], v[112:115], v[168:171], v[40:43]
	v_mfma_f32_16x16x32_bf16 v[28:31], v[96:99], v[176:179], v[28:31]
	v_mfma_f32_16x16x32_bf16 v[24:27], v[112:115], v[176:179], v[24:27]
	v_mfma_f32_16x16x32_bf16 v[12:15], v[96:99], v[200:203], v[12:15]
	v_mfma_f32_16x16x32_bf16 v[8:11], v[112:115], v[200:203], v[8:11]
	v_mfma_f32_16x16x32_bf16 v[60:63], v[100:103], v[164:167], v[60:63]
	v_mfma_f32_16x16x32_bf16 v[56:59], v[116:119], v[164:167], v[56:59]
	v_mfma_f32_16x16x32_bf16 v[44:47], v[100:103], v[172:175], v[44:47]
	v_mfma_f32_16x16x32_bf16 v[40:43], v[116:119], v[172:175], v[40:43]
	v_mfma_f32_16x16x32_bf16 v[28:31], v[100:103], v[180:183], v[28:31]
	v_mfma_f32_16x16x32_bf16 v[24:27], v[116:119], v[180:183], v[24:27]
	v_mfma_f32_16x16x32_bf16 v[12:15], v[100:103], v[204:207], v[12:15]
	v_mfma_f32_16x16x32_bf16 v[8:11], v[116:119], v[204:207], v[8:11]
	v_mfma_f32_16x16x32_bf16 v[52:55], v[144:147], v[160:163], v[52:55]
	v_mfma_f32_16x16x32_bf16 v[48:51], v[152:155], v[160:163], v[48:51]
	v_mfma_f32_16x16x32_bf16 v[36:39], v[144:147], v[168:171], v[36:39]
	v_mfma_f32_16x16x32_bf16 v[32:35], v[152:155], v[168:171], v[32:35]
	v_mfma_f32_16x16x32_bf16 v[20:23], v[144:147], v[176:179], v[20:23]
	v_mfma_f32_16x16x32_bf16 v[16:19], v[152:155], v[176:179], v[16:19]
	v_mfma_f32_16x16x32_bf16 v[4:7], v[144:147], v[200:203], v[4:7]
	v_mfma_f32_16x16x32_bf16 v[0:3], v[152:155], v[200:203], v[0:3]
	v_mfma_f32_16x16x32_bf16 v[52:55], v[148:151], v[164:167], v[52:55]
	v_mfma_f32_16x16x32_bf16 v[48:51], v[156:159], v[164:167], v[48:51]
	v_mfma_f32_16x16x32_bf16 v[36:39], v[148:151], v[172:175], v[36:39]
	v_mfma_f32_16x16x32_bf16 v[32:35], v[156:159], v[172:175], v[32:35]
	v_mfma_f32_16x16x32_bf16 v[20:23], v[148:151], v[180:183], v[20:23]
	v_mfma_f32_16x16x32_bf16 v[16:19], v[156:159], v[180:183], v[16:19]
	v_mfma_f32_16x16x32_bf16 v[4:7], v[148:151], v[204:207], v[4:7]
	v_mfma_f32_16x16x32_bf16 v[0:3], v[156:159], v[204:207], v[0:3]
	s_barrier
	s_add_u32 s38, s38, 0x100
	s_addc_u32 s39, s39, 0
	s_add_u32 s70, s70, 0x100
	s_addc_u32 s71, s71, 0
	s_cmp_ge_u32 s72, s29
	s_mov_b32 s42, s72
	s_cbranch_scc0 .LBB0_769

; #define PG8_STAGE(bufoff, gbase, voff) do { _Pragma("unroll") for (int _i = 0; _i < 2; ++_i) \
;         __builtin_amdgcn_global_load_lds((const unsigned*)((const char*)(gbase) + (voff)[_i]), (LAS unsigned*)(lds + (bufoff) + ldsw + _i * 8192), 16, 0, 0); } while (0)
; #define PG8_LDA(dst, b, h) do { _Pragma("unroll") for (int m = 0; m < 4; ++m) _Pragma("unroll") for (int k = 0; k < 2; ++k) dst[m][k] = *(const LAS bf16x8*)(lds + PG8_SA(b, h) + aoff + m * 2048 + k * 1024); } while (0)
; #define PG8_LDB(dst, b, h) do { _Pragma("unroll") for (int n = 0; n < 2; ++n) _Pragma("unroll") for (int k = 0; k < 2; ++k) dst[n][k] = *(const LAS bf16x8*)(lds + PG8_SB(b, h) + boff + n * 2048 + k * 1024); } while (0)
; #define PG8_MMA(ai, bj, At, Bt) do { __builtin_amdgcn_s_setprio(1); _Pragma("unroll") for (int m = 0; m < 4; ++m) _Pragma("unroll") for (int n = 0; n < 2; ++n) _Pragma("unroll") for (int k = 0; k < 2; ++k) \
;         acc[ai][bj][m][n] = __builtin_amdgcn_mfma_f32_16x16x32_bf16(Bt[n][k], At[m][k], acc[ai][bj][m][n], 0, 0, 0); __builtin_amdgcn_s_setprio(0); } while (0)
; #define PG8_BAR __builtin_amdgcn_s_barrier()
; template <class Epi, class Sched = StaticOrder, class EpiSub = NoSub, bool FAST = false>
; __device__ __forceinline__ void gemm_phase(LAS unsigned char* lds, const Gemm g, const Sched& S, const Epi& E, const EpiSub& ES = EpiSub()) {
;     ...
;         const bool has_next = S.next(ui + 1, nxt);
;         const size_t nko = (has_next && nxt.kb >= 0) ? nxt.kb * ksubB : 0;
;         const char* nA = has_next ? (const char*)g.A + (size_t)nxt.pm * tstepA + (size_t)nxt.pn * g.acs + nko : cA; const char* nB = has_next ? (const char*)g.Bt + (size_t)nxt.pn * tstepB + nko : cB;
;         const int nt = cur.kb < 0 ? ntMain : ntSub;
;         for (int t = 0; t < nt; t += 2) {
;             const bool last = (t == nt - 2);
;             const char* a1 = cA + (size_t)(t + 1) * kstep;
;             const char* a2 = last ? nA : cA + (size_t)(t + 2) * kstep; const char* b2 = last ? nB : cB + (size_t)(t + 2) * kstep;
;             const char* a3 = a2 + kstep; const char* b3 = b2 + kstep;
;             if constexpr (FAST && PG8_SP2) {
;             PG8_LDB(B0, 0, 0); PG8_LDB(B1, 0, 1); PG8_SCHED; PG8_LDA(At, 0, 0); PG8_STAGE(PG8_SA(1, 1), a1 + hstepA, voffA);
;             PG8_WAIT_V(8); PG8_WAIT_L(0); PG8_BAR; PG8_MMA(0, 0, At, B0); PG8_MMA(0, 1, At, B1); PG8_BAR; PG8_SCHED;
.LBB0_984:
	s_ashr_i32 s15, s14, 31
	s_lshl_b64 s[16:17], s[14:15], 20
	v_readlane_b32 s18, v254, 36
	v_readlane_b32 s19, v254, 37
	s_add_u32 s16, s18, s16
	s_addc_u32 s17, s19, s17
	s_and_b64 s[18:19], s[0:1], exec
	s_cselect_b32 s15, s17, s23
	s_cselect_b32 s45, s16, s22
	s_ashr_i32 s13, s12, 31
	s_lshl_b64 s[18:19], s[12:13], 20
	s_add_u32 s18, s2, s18
	s_addc_u32 s19, s3, s19
	s_and_b64 s[26:27], s[0:1], exec
	s_cselect_b32 s13, s19, s25
	s_cselect_b32 s46, s18, s24
	s_add_u32 s22, s22, 0x80080
	s_addc_u32 s23, s23, 0
	s_add_u32 s47, s24, 0x100
	s_addc_u32 s48, s25, 0
	s_mov_b32 s49, -2
	ds_read_b128 v[150:153], v147
	ds_read_b128 v[154:157], v147 offset:1024
	ds_read_b128 v[158:161], v147 offset:2048
	ds_read_b128 v[162:165], v147 offset:3072
	ds_read_b128 v[166:169], v148
	ds_read_b128 v[170:173], v148 offset:1024
	ds_read_b128 v[174:177], v148 offset:2048
	ds_read_b128 v[178:181], v148 offset:3072
	s_add_u32 s24, s22, 0xfff80080
	s_addc_u32 s25, s23, -1
	s_cmp_eq_u32 s49, 28
	s_cselect_b32 s27, s15, s25
	s_cselect_b32 s26, s45, s24
	s_cselect_b32 s25, s13, s48
	s_cselect_b32 s24, s46, s47
	v_lshl_add_u64 v[190:191], s[22:23], 0, v[136:137]
	s_add_i32 m0, s21, 0xc000
	ds_read_b128 v[182:185], v149
	ds_read_b128 v[186:189], v149 offset:1024
	ds_read_b128 v[194:197], v149 offset:2048
	ds_read_b128 v[198:201], v149 offset:3072
	ds_read_b128 v[202:205], v149 offset:4096
	ds_read_b128 v[206:209], v149 offset:5120
	ds_read_b128 v[210:213], v149 offset:6144
	ds_read_b128 v[214:217], v149 offset:7168
	global_load_lds_dwordx4 v[190:191], off
	v_lshl_add_u64 v[190:191], s[22:23], 0, v[138:139]
	s_add_i32 m0, s21, 0xe000
	s_nop 0
	global_load_lds_dwordx4 v[190:191], off
	s_waitcnt vmcnt(8) lgkmcnt(0)
	s_barrier
	v_mfma_f32_16x16x32_bf16 v[124:127], v[150:153], v[182:185], 0
	v_mfma_f32_16x16x32_bf16 v[116:119], v[158:161], v[182:185], 0
	v_mfma_f32_16x16x32_bf16 v[108:111], v[150:153], v[194:197], 0
	v_mfma_f32_16x16x32_bf16 v[100:103], v[158:161], v[194:197], 0
	v_mfma_f32_16x16x32_bf16 v[92:95], v[150:153], v[202:205], 0
	v_mfma_f32_16x16x32_bf16 v[84:87], v[158:161], v[202:205], 0
	v_mfma_f32_16x16x32_bf16 v[76:79], v[150:153], v[210:213], 0
	v_mfma_f32_16x16x32_bf16 v[68:71], v[158:161], v[210:213], 0
	v_mfma_f32_16x16x32_bf16 v[124:127], v[154:157], v[186:189], v[124:127]
	v_mfma_f32_16x16x32_bf16 v[116:119], v[162:165], v[186:189], v[116:119]
	v_mfma_f32_16x16x32_bf16 v[108:111], v[154:157], v[198:201], v[108:111]
	v_mfma_f32_16x16x32_bf16 v[100:103], v[162:165], v[198:201], v[100:103]
	v_mfma_f32_16x16x32_bf16 v[92:95], v[154:157], v[206:209], v[92:95]
	v_mfma_f32_16x16x32_bf16 v[84:87], v[162:165], v[206:209], v[84:87]
	v_mfma_f32_16x16x32_bf16 v[76:79], v[154:157], v[214:217], v[76:79]
	v_mfma_f32_16x16x32_bf16 v[68:71], v[162:165], v[214:217], v[68:71]
	v_mfma_f32_16x16x32_bf16 v[120:123], v[166:169], v[182:185], 0
	v_mfma_f32_16x16x32_bf16 v[112:115], v[174:177], v[182:185], 0
	v_mfma_f32_16x16x32_bf16 v[104:107], v[166:169], v[194:197], 0
	v_mfma_f32_16x16x32_bf16 v[96:99], v[174:177], v[194:197], 0
	v_mfma_f32_16x16x32_bf16 v[88:91], v[166:169], v[202:205], 0
	v_mfma_f32_16x16x32_bf16 v[80:83], v[174:177], v[202:205], 0
	v_mfma_f32_16x16x32_bf16 v[72:75], v[166:169], v[210:213], 0
	v_mfma_f32_16x16x32_bf16 v[64:67], v[174:177], v[210:213], 0
	v_mfma_f32_16x16x32_bf16 v[120:123], v[170:173], v[186:189], v[120:123]
	v_mfma_f32_16x16x32_bf16 v[112:115], v[178:181], v[186:189], v[112:115]
	v_mfma_f32_16x16x32_bf16 v[104:107], v[170:173], v[198:201], v[104:107]
	v_mfma_f32_16x16x32_bf16 v[96:99], v[178:181], v[198:201], v[96:99]
	v_mfma_f32_16x16x32_bf16 v[88:91], v[170:173], v[206:209], v[88:91]
	v_mfma_f32_16x16x32_bf16 v[80:83], v[178:181], v[206:209], v[80:83]
	v_mfma_f32_16x16x32_bf16 v[72:75], v[170:173], v[214:217], v[72:75]
	v_mfma_f32_16x16x32_bf16 v[64:67], v[178:181], v[214:217], v[64:67]
	s_barrier
	s_add_i32 s50, s42, s28
	v_lshl_add_u64 v[190:191], s[24:25], 0, v[130:131]
	s_mov_b32 m0, s50
	ds_read_b128 v[182:185], v149 offset:16384
	ds_read_b128 v[186:189], v149 offset:17408
	ds_read_b128 v[194:197], v149 offset:18432
	ds_read_b128 v[198:201], v149 offset:19456
	ds_read_b128 v[202:205], v149 offset:20480
	ds_read_b128 v[206:209], v149 offset:21504
	ds_read_b128 v[210:213], v149 offset:22528
	ds_read_b128 v[214:217], v149 offset:23552
	global_load_lds_dwordx4 v[190:191], off
	s_add_i32 m0, s50, 0x2000
	s_add_u32 s50, s24, 0x80000
	v_lshl_add_u64 v[218:219], s[24:25], 0, v[134:135]
	s_addc_u32 s51, s25, 0
	s_add_i32 s52, s43, s28
	global_load_lds_dwordx4 v[218:219], off
	v_lshl_add_u64 v[220:221], s[50:51], 0, v[130:131]
	s_mov_b32 m0, s52
	v_lshl_add_u64 v[222:223], s[26:27], 0, v[132:133]
	global_load_lds_dwordx4 v[220:221], off
	v_lshl_add_u64 v[220:221], s[50:51], 0, v[134:135]
	s_add_i32 m0, s52, 0x2000
	s_nop 0
	global_load_lds_dwordx4 v[220:221], off
	v_lshl_add_u64 v[220:221], s[26:27], 0, v[128:129]
	s_mov_b32 m0, s21
	s_nop 0
	global_load_lds_dwordx4 v[220:221], off
	s_mov_b32 m0, s31
	s_nop 0
	global_load_lds_dwordx4 v[222:223], off
	s_waitcnt vmcnt(8) lgkmcnt(0)
	s_barrier
; #define PG8_STAGE(bufoff, gbase, voff) do { _Pragma("unroll") for (int _i = 0; _i < 2; ++_i) \
;         __builtin_amdgcn_global_load_lds((const unsigned*)((const char*)(gbase) + (voff)[_i]), (LAS unsigned*)(lds + (bufoff) + ldsw + _i * 8192), 16, 0, 0); } while (0)
; #define PG8_LDA(dst, b, h) do { _Pragma("unroll") for (int m = 0; m < 4; ++m) _Pragma("unroll") for (int k = 0; k < 2; ++k) dst[m][k] = *(const LAS bf16x8*)(lds + PG8_SA(b, h) + aoff + m * 2048 + k * 1024); } while (0)
; #define PG8_LDB(dst, b, h) do { _Pragma("unroll") for (int n = 0; n < 2; ++n) _Pragma("unroll") for (int k = 0; k < 2; ++k) dst[n][k] = *(const LAS bf16x8*)(lds + PG8_SB(b, h) + boff + n * 2048 + k * 1024); } while (0)
; #define PG8_MMA(ai, bj, At, Bt) do { __builtin_amdgcn_s_setprio(1); _Pragma("unroll") for (int m = 0; m < 4; ++m) _Pragma("unroll") for (int n = 0; n < 2; ++n) _Pragma("unroll") for (int k = 0; k < 2; ++k) \
;         acc[ai][bj][m][n] = __builtin_amdgcn_mfma_f32_16x16x32_bf16(Bt[n][k], At[m][k], acc[ai][bj][m][n], 0, 0, 0); __builtin_amdgcn_s_setprio(0); } while (0)
; #define PG8_WAIT_V(n) asm volatile("s_waitcnt vmcnt(" #n ")" ::: "memory")
; #define PG8_WAIT_L(n) asm volatile("s_waitcnt lgkmcnt(" #n ")" ::: "memory")
; #define PG8_BAR __builtin_amdgcn_s_barrier()
; #define PG8_SCHED __builtin_amdgcn_sched_barrier(0)
; template <class Epi, class Sched = StaticOrder, class EpiSub = NoSub, bool FAST = false>
; __device__ __forceinline__ void gemm_phase(LAS unsigned char* lds, const Gemm g, const Sched& S, const Epi& E, const EpiSub& ES = EpiSub()) {
;     ...
;             PG8_WAIT_V(8); PG8_WAIT_L(0); PG8_BAR; PG8_MMA(0, 0, At, B0); PG8_MMA(0, 1, At, B1); PG8_BAR; PG8_SCHED;
;             PG8_LDA(At, 0, 1); PG8_STAGE(PG8_SB(0, 0), b2, voffB); PG8_STAGE(PG8_SB(0, 1), b2 + hstepB, voffB); PG8_STAGE(PG8_SA(0, 0), a2, voffA);
;             PG8_WAIT_V(8); PG8_WAIT_L(0); PG8_BAR; PG8_MMA(1, 0, At, B0); PG8_MMA(1, 1, At, B1); PG8_BAR; PG8_SCHED;
;             PG8_LDB(B0, 1, 0); PG8_LDB(B1, 1, 1); PG8_SCHED; PG8_LDA(At, 1, 0); PG8_STAGE(PG8_SA(0, 1), a2 + hstepA, voffA);
;             PG8_WAIT_V(8); PG8_WAIT_L(0); PG8_BAR; PG8_MMA(0, 0, At, B0); PG8_MMA(0, 1, At, B1); PG8_BAR; PG8_SCHED;
	v_mfma_f32_16x16x32_bf16 v[60:63], v[150:153], v[182:185], 0
	v_mfma_f32_16x16x32_bf16 v[52:55], v[158:161], v[182:185], 0
	v_mfma_f32_16x16x32_bf16 v[44:47], v[150:153], v[194:197], 0
	v_mfma_f32_16x16x32_bf16 v[36:39], v[158:161], v[194:197], 0
	v_mfma_f32_16x16x32_bf16 v[28:31], v[150:153], v[202:205], 0
	v_mfma_f32_16x16x32_bf16 v[20:23], v[158:161], v[202:205], 0
	v_mfma_f32_16x16x32_bf16 v[12:15], v[150:153], v[210:213], 0
	v_mfma_f32_16x16x32_bf16 v[4:7], v[158:161], v[210:213], 0
	v_mfma_f32_16x16x32_bf16 v[60:63], v[154:157], v[186:189], v[60:63]
	v_mfma_f32_16x16x32_bf16 v[52:55], v[162:165], v[186:189], v[52:55]
	v_mfma_f32_16x16x32_bf16 v[44:47], v[154:157], v[198:201], v[44:47]
	v_mfma_f32_16x16x32_bf16 v[36:39], v[162:165], v[198:201], v[36:39]
	v_mfma_f32_16x16x32_bf16 v[28:31], v[154:157], v[206:209], v[28:31]
	v_mfma_f32_16x16x32_bf16 v[20:23], v[162:165], v[206:209], v[20:23]
	v_mfma_f32_16x16x32_bf16 v[12:15], v[154:157], v[214:217], v[12:15]
	v_mfma_f32_16x16x32_bf16 v[4:7], v[162:165], v[214:217], v[4:7]
	v_mfma_f32_16x16x32_bf16 v[56:59], v[166:169], v[182:185], 0
	v_mfma_f32_16x16x32_bf16 v[48:51], v[174:177], v[182:185], 0
	v_mfma_f32_16x16x32_bf16 v[40:43], v[166:169], v[194:197], 0
	v_mfma_f32_16x16x32_bf16 v[32:35], v[174:177], v[194:197], 0
	v_mfma_f32_16x16x32_bf16 v[24:27], v[166:169], v[202:205], 0
	v_mfma_f32_16x16x32_bf16 v[16:19], v[174:177], v[202:205], 0
	v_mfma_f32_16x16x32_bf16 v[8:11], v[166:169], v[210:213], 0
	v_mfma_f32_16x16x32_bf16 v[0:3], v[174:177], v[210:213], 0
	v_mfma_f32_16x16x32_bf16 v[56:59], v[170:173], v[186:189], v[56:59]
	v_mfma_f32_16x16x32_bf16 v[48:51], v[178:181], v[186:189], v[48:51]
	v_mfma_f32_16x16x32_bf16 v[40:43], v[170:173], v[198:201], v[40:43]
	v_mfma_f32_16x16x32_bf16 v[32:35], v[178:181], v[198:201], v[32:35]
	v_mfma_f32_16x16x32_bf16 v[24:27], v[170:173], v[206:209], v[24:27]
	v_mfma_f32_16x16x32_bf16 v[16:19], v[178:181], v[206:209], v[16:19]
	v_mfma_f32_16x16x32_bf16 v[8:11], v[170:173], v[214:217], v[8:11]
	v_mfma_f32_16x16x32_bf16 v[0:3], v[178:181], v[214:217], v[0:3]
	s_barrier
	s_add_i32 s50, 0, 0x18000
	s_add_i32 s51, 0, 0x1c000
	v_add_u32_e32 v162, s50, v145
	v_add_u32_e32 v178, s51, v145
	ds_read_b128 v[150:153], v162
	ds_read_b128 v[154:157], v162 offset:1024
	ds_read_b128 v[158:161], v162 offset:2048
	ds_read_b128 v[162:165], v162 offset:3072
	ds_read_b128 v[166:169], v178
	ds_read_b128 v[170:173], v178 offset:1024
	ds_read_b128 v[174:177], v178 offset:2048
	ds_read_b128 v[178:181], v178 offset:3072
	s_add_u32 s26, s26, 0x80000
	s_addc_u32 s27, s27, 0
	s_mov_b32 m0, s36
	v_lshl_add_u64 v[224:225], s[26:27], 0, v[128:129]
	ds_read_b128 v[182:185], v149 offset:32768
	ds_read_b128 v[186:189], v149 offset:33792
	ds_read_b128 v[194:197], v149 offset:34816
	ds_read_b128 v[198:201], v149 offset:35840
	ds_read_b128 v[202:205], v149 offset:36864
	ds_read_b128 v[206:209], v149 offset:37888
	ds_read_b128 v[210:213], v149 offset:38912
	ds_read_b128 v[214:217], v149 offset:39936
	global_load_lds_dwordx4 v[224:225], off
	v_lshl_add_u64 v[224:225], s[26:27], 0, v[132:133]
	s_mov_b32 m0, s37
	s_nop 0
	global_load_lds_dwordx4 v[224:225], off
	s_waitcnt vmcnt(8) lgkmcnt(0)
	s_barrier
	v_mfma_f32_16x16x32_bf16 v[124:127], v[150:153], v[182:185], v[124:127]
	v_mfma_f32_16x16x32_bf16 v[116:119], v[158:161], v[182:185], v[116:119]
	v_mfma_f32_16x16x32_bf16 v[108:111], v[150:153], v[194:197], v[108:111]
	v_mfma_f32_16x16x32_bf16 v[100:103], v[158:161], v[194:197], v[100:103]
	v_mfma_f32_16x16x32_bf16 v[92:95], v[150:153], v[202:205], v[92:95]
	v_mfma_f32_16x16x32_bf16 v[84:87], v[158:161], v[202:205], v[84:87]
	v_mfma_f32_16x16x32_bf16 v[76:79], v[150:153], v[210:213], v[76:79]
	v_mfma_f32_16x16x32_bf16 v[68:71], v[158:161], v[210:213], v[68:71]
	v_mfma_f32_16x16x32_bf16 v[124:127], v[154:157], v[186:189], v[124:127]
	v_mfma_f32_16x16x32_bf16 v[116:119], v[162:165], v[186:189], v[116:119]
	v_mfma_f32_16x16x32_bf16 v[108:111], v[154:157], v[198:201], v[108:111]
	v_mfma_f32_16x16x32_bf16 v[100:103], v[162:165], v[198:201], v[100:103]
	v_mfma_f32_16x16x32_bf16 v[92:95], v[154:157], v[206:209], v[92:95]
	v_mfma_f32_16x16x32_bf16 v[84:87], v[162:165], v[206:209], v[84:87]
	v_mfma_f32_16x16x32_bf16 v[76:79], v[154:157], v[214:217], v[76:79]
	v_mfma_f32_16x16x32_bf16 v[68:71], v[162:165], v[214:217], v[68:71]
	v_mfma_f32_16x16x32_bf16 v[120:123], v[166:169], v[182:185], v[120:123]
	v_mfma_f32_16x16x32_bf16 v[112:115], v[174:177], v[182:185], v[112:115]
	v_mfma_f32_16x16x32_bf16 v[104:107], v[166:169], v[194:197], v[104:107]
	v_mfma_f32_16x16x32_bf16 v[96:99], v[174:177], v[194:197], v[96:99]
	v_mfma_f32_16x16x32_bf16 v[88:91], v[166:169], v[202:205], v[88:91]
	v_mfma_f32_16x16x32_bf16 v[80:83], v[174:177], v[202:205], v[80:83]
	v_mfma_f32_16x16x32_bf16 v[72:75], v[166:169], v[210:213], v[72:75]
	v_mfma_f32_16x16x32_bf16 v[64:67], v[174:177], v[210:213], v[64:67]
	v_mfma_f32_16x16x32_bf16 v[120:123], v[170:173], v[186:189], v[120:123]
	v_mfma_f32_16x16x32_bf16 v[112:115], v[178:181], v[186:189], v[112:115]
	v_mfma_f32_16x16x32_bf16 v[104:107], v[170:173], v[198:201], v[104:107]
	v_mfma_f32_16x16x32_bf16 v[96:99], v[178:181], v[198:201], v[96:99]
	v_mfma_f32_16x16x32_bf16 v[88:91], v[170:173], v[206:209], v[88:91]
	v_mfma_f32_16x16x32_bf16 v[80:83], v[178:181], v[206:209], v[80:83]
	v_mfma_f32_16x16x32_bf16 v[72:75], v[170:173], v[214:217], v[72:75]
	v_mfma_f32_16x16x32_bf16 v[64:67], v[178:181], v[214:217], v[64:67]
	s_barrier
; #define PG8_STAGE(bufoff, gbase, voff) do { _Pragma("unroll") for (int _i = 0; _i < 2; ++_i) \
;         __builtin_amdgcn_global_load_lds((const unsigned*)((const char*)(gbase) + (voff)[_i]), (LAS unsigned*)(lds + (bufoff) + ldsw + _i * 8192), 16, 0, 0); } while (0)
; #define PG8_LDA(dst, b, h) do { _Pragma("unroll") for (int m = 0; m < 4; ++m) _Pragma("unroll") for (int k = 0; k < 2; ++k) dst[m][k] = *(const LAS bf16x8*)(lds + PG8_SA(b, h) + aoff + m * 2048 + k * 1024); } while (0)
; #define PG8_LDB(dst, b, h) do { _Pragma("unroll") for (int n = 0; n < 2; ++n) _Pragma("unroll") for (int k = 0; k < 2; ++k) dst[n][k] = *(const LAS bf16x8*)(lds + PG8_SB(b, h) + boff + n * 2048 + k * 1024); } while (0)
; template <class Epi, class Sched = StaticOrder, class EpiSub = NoSub, bool FAST = false>
; __device__ __forceinline__ void gemm_phase(LAS unsigned char* lds, const Gemm g, const Sched& S, const Epi& E, const EpiSub& ES = EpiSub()) {
;     ...
;         for (int t = 0; t < nt; t += 2) {
;             const bool last = (t == nt - 2);
;             const char* a1 = cA + (size_t)(t + 1) * kstep;
;             const char* a2 = last ? nA : cA + (size_t)(t + 2) * kstep; const char* b2 = last ? nB : cB + (size_t)(t + 2) * kstep;
;             const char* a3 = a2 + kstep; const char* b3 = b2 + kstep;
;             if constexpr (FAST && PG8_SP2) {
;             PG8_LDB(B0, 0, 0); PG8_LDB(B1, 0, 1); PG8_SCHED; PG8_LDA(At, 0, 0); PG8_STAGE(PG8_SA(1, 1), a1 + hstepA, voffA);
;             PG8_WAIT_V(8); PG8_WAIT_L(0); PG8_BAR; PG8_MMA(0, 0, At, B0); PG8_MMA(0, 1, At, B1); PG8_BAR; PG8_SCHED;
;             PG8_LDA(At, 0, 1); PG8_STAGE(PG8_SB(0, 0), b2, voffB); PG8_STAGE(PG8_SB(0, 1), b2 + hstepB, voffB); PG8_STAGE(PG8_SA(0, 0), a2, voffA);
;             PG8_WAIT_V(8); PG8_WAIT_L(0); PG8_BAR; PG8_MMA(1, 0, At, B0); PG8_MMA(1, 1, At, B1); PG8_BAR; PG8_SCHED;
;             PG8_LDB(B0, 1, 0); PG8_LDB(B1, 1, 1); PG8_SCHED; PG8_LDA(At, 1, 0); PG8_STAGE(PG8_SA(0, 1), a2 + hstepA, voffA);
;             PG8_WAIT_V(8); PG8_WAIT_L(0); PG8_BAR; PG8_MMA(0, 0, At, B0); PG8_MMA(0, 1, At, B1); PG8_BAR; PG8_SCHED;
;             PG8_LDA(At, 1, 1); PG8_STAGE(PG8_SB(1, 0), b3, voffB); PG8_STAGE(PG8_SB(1, 1), b3 + hstepB, voffB); PG8_STAGE(PG8_SA(1, 0), a3, voffA);
;             PG8_WAIT_V(8); PG8_WAIT_L(0); PG8_BAR; PG8_MMA(1, 0, At, B0); PG8_MMA(1, 1, At, B1); PG8_BAR; PG8_SCHED;
	s_add_i32 s26, s50, s28
	v_lshl_add_u64 v[190:191], v[190:191], 0, s[8:9]
	s_mov_b32 m0, s26
	ds_read_b128 v[182:185], v149 offset:49152
	ds_read_b128 v[186:189], v149 offset:50176
	ds_read_b128 v[194:197], v149 offset:51200
	ds_read_b128 v[198:201], v149 offset:52224
	ds_read_b128 v[202:205], v149 offset:53248
	ds_read_b128 v[206:209], v149 offset:54272
	ds_read_b128 v[210:213], v149 offset:55296
	ds_read_b128 v[214:217], v149 offset:56320
	global_load_lds_dwordx4 v[190:191], off
	s_add_i32 m0, s26, 0x2000
	s_add_u32 s24, s24, 0x80080
	v_lshl_add_u64 v[190:191], v[218:219], 0, s[8:9]
	s_addc_u32 s25, s25, 0
	s_add_i32 s26, s51, s28
	global_load_lds_dwordx4 v[190:191], off
	v_lshl_add_u64 v[190:191], s[24:25], 0, v[130:131]
	s_mov_b32 m0, s26
	s_nop 0
	global_load_lds_dwordx4 v[190:191], off
	v_lshl_add_u64 v[190:191], s[24:25], 0, v[134:135]
	s_add_i32 m0, s26, 0x2000
	s_nop 0
	global_load_lds_dwordx4 v[190:191], off
	v_lshl_add_u64 v[190:191], v[220:221], 0, s[8:9]
	s_mov_b32 m0, s40
	s_nop 0
	global_load_lds_dwordx4 v[190:191], off
	v_lshl_add_u64 v[190:191], v[222:223], 0, s[8:9]
	s_mov_b32 m0, s41
	s_nop 0
	global_load_lds_dwordx4 v[190:191], off
	s_waitcnt vmcnt(8) lgkmcnt(0)
	s_barrier
	v_mfma_f32_16x16x32_bf16 v[60:63], v[150:153], v[182:185], v[60:63]
	v_mfma_f32_16x16x32_bf16 v[52:55], v[158:161], v[182:185], v[52:55]
	v_mfma_f32_16x16x32_bf16 v[44:47], v[150:153], v[194:197], v[44:47]
	v_mfma_f32_16x16x32_bf16 v[36:39], v[158:161], v[194:197], v[36:39]
	v_mfma_f32_16x16x32_bf16 v[28:31], v[150:153], v[202:205], v[28:31]
	v_mfma_f32_16x16x32_bf16 v[20:23], v[158:161], v[202:205], v[20:23]
	v_mfma_f32_16x16x32_bf16 v[12:15], v[150:153], v[210:213], v[12:15]
	v_mfma_f32_16x16x32_bf16 v[4:7], v[158:161], v[210:213], v[4:7]
	v_mfma_f32_16x16x32_bf16 v[60:63], v[154:157], v[186:189], v[60:63]
	v_mfma_f32_16x16x32_bf16 v[52:55], v[162:165], v[186:189], v[52:55]
	v_mfma_f32_16x16x32_bf16 v[44:47], v[154:157], v[198:201], v[44:47]
	v_mfma_f32_16x16x32_bf16 v[36:39], v[162:165], v[198:201], v[36:39]
	v_mfma_f32_16x16x32_bf16 v[28:31], v[154:157], v[206:209], v[28:31]
	v_mfma_f32_16x16x32_bf16 v[20:23], v[162:165], v[206:209], v[20:23]
	v_mfma_f32_16x16x32_bf16 v[12:15], v[154:157], v[214:217], v[12:15]
	v_mfma_f32_16x16x32_bf16 v[4:7], v[162:165], v[214:217], v[4:7]
	v_mfma_f32_16x16x32_bf16 v[56:59], v[166:169], v[182:185], v[56:59]
	v_mfma_f32_16x16x32_bf16 v[48:51], v[174:177], v[182:185], v[48:51]
	v_mfma_f32_16x16x32_bf16 v[40:43], v[166:169], v[194:197], v[40:43]
	v_mfma_f32_16x16x32_bf16 v[32:35], v[174:177], v[194:197], v[32:35]
	v_mfma_f32_16x16x32_bf16 v[24:27], v[166:169], v[202:205], v[24:27]
	v_mfma_f32_16x16x32_bf16 v[16:19], v[174:177], v[202:205], v[16:19]
	v_mfma_f32_16x16x32_bf16 v[8:11], v[166:169], v[210:213], v[8:11]
	v_mfma_f32_16x16x32_bf16 v[0:3], v[174:177], v[210:213], v[0:3]
	v_mfma_f32_16x16x32_bf16 v[56:59], v[170:173], v[186:189], v[56:59]
	v_mfma_f32_16x16x32_bf16 v[48:51], v[178:181], v[186:189], v[48:51]
	v_mfma_f32_16x16x32_bf16 v[40:43], v[170:173], v[198:201], v[40:43]
	v_mfma_f32_16x16x32_bf16 v[32:35], v[178:181], v[198:201], v[32:35]
	v_mfma_f32_16x16x32_bf16 v[24:27], v[170:173], v[206:209], v[24:27]
	v_mfma_f32_16x16x32_bf16 v[16:19], v[178:181], v[206:209], v[16:19]
	v_mfma_f32_16x16x32_bf16 v[8:11], v[170:173], v[214:217], v[8:11]
	v_mfma_f32_16x16x32_bf16 v[0:3], v[178:181], v[214:217], v[0:3]
	s_barrier
	s_add_i32 s49, s49, 2
	s_add_u32 s22, s22, 0x100
	s_addc_u32 s23, s23, 0
	s_add_u32 s47, s47, 0x100
	s_addc_u32 s48, s48, 0
	s_cmp_gt_u32 s49, 29
	s_cbranch_scc1 .Lkpeel_985_exit
.LBB0_985:
	ds_read_b128 v[150:153], v147
	ds_read_b128 v[154:157], v147 offset:1024
	ds_read_b128 v[158:161], v147 offset:2048
	ds_read_b128 v[162:165], v147 offset:3072
	ds_read_b128 v[166:169], v148
	ds_read_b128 v[170:173], v148 offset:1024
	ds_read_b128 v[174:177], v148 offset:2048
	ds_read_b128 v[178:181], v148 offset:3072
	s_add_u32 s24, s22, 0xfff80080
	s_addc_u32 s25, s23, -1
	s_cmp_eq_u32 s49, 28
	s_cselect_b32 s27, s15, s25
	s_cselect_b32 s26, s45, s24
	s_cselect_b32 s25, s13, s48
	s_cselect_b32 s24, s46, s47
	v_lshl_add_u64 v[190:191], s[22:23], 0, v[136:137]
	s_add_i32 m0, s21, 0xc000
	ds_read_b128 v[182:185], v149
	ds_read_b128 v[186:189], v149 offset:1024
	ds_read_b128 v[194:197], v149 offset:2048
	ds_read_b128 v[198:201], v149 offset:3072
	ds_read_b128 v[202:205], v149 offset:4096
	ds_read_b128 v[206:209], v149 offset:5120
	ds_read_b128 v[210:213], v149 offset:6144
	ds_read_b128 v[214:217], v149 offset:7168
	global_load_lds_dwordx4 v[190:191], off
	v_lshl_add_u64 v[190:191], s[22:23], 0, v[138:139]
	s_add_i32 m0, s21, 0xe000
	s_nop 0
	global_load_lds_dwordx4 v[190:191], off
	s_waitcnt vmcnt(8) lgkmcnt(0)
	s_barrier
; #define PG8_STAGE(bufoff, gbase, voff) do { _Pragma("unroll") for (int _i = 0; _i < 2; ++_i) \
;         __builtin_amdgcn_global_load_lds((const unsigned*)((const char*)(gbase) + (voff)[_i]), (LAS unsigned*)(lds + (bufoff) + ldsw + _i * 8192), 16, 0, 0); } while (0)
; #define PG8_LDA(dst, b, h) do { _Pragma("unroll") for (int m = 0; m < 4; ++m) _Pragma("unroll") for (int k = 0; k < 2; ++k) dst[m][k] = *(const LAS bf16x8*)(lds + PG8_SA(b, h) + aoff + m * 2048 + k * 1024); } while (0)
; #define PG8_LDB(dst, b, h) do { _Pragma("unroll") for (int n = 0; n < 2; ++n) _Pragma("unroll") for (int k = 0; k < 2; ++k) dst[n][k] = *(const LAS bf16x8*)(lds + PG8_SB(b, h) + boff + n * 2048 + k * 1024); } while (0)
; #define PG8_MMA(ai, bj, At, Bt) do { __builtin_amdgcn_s_setprio(1); _Pragma("unroll") for (int m = 0; m < 4; ++m) _Pragma("unroll") for (int n = 0; n < 2; ++n) _Pragma("unroll") for (int k = 0; k < 2; ++k) \
;         acc[ai][bj][m][n] = __builtin_amdgcn_mfma_f32_16x16x32_bf16(Bt[n][k], At[m][k], acc[ai][bj][m][n], 0, 0, 0); __builtin_amdgcn_s_setprio(0); } while (0)
; #define PG8_WAIT_V(n) asm volatile("s_waitcnt vmcnt(" #n ")" ::: "memory")
; #define PG8_WAIT_L(n) asm volatile("s_waitcnt lgkmcnt(" #n ")" ::: "memory")
; #define PG8_BAR __builtin_amdgcn_s_barrier()
; #define PG8_SCHED __builtin_amdgcn_sched_barrier(0)
; template <class Epi, class Sched = StaticOrder, class EpiSub = NoSub, bool FAST = false>
; __device__ __forceinline__ void gemm_phase(LAS unsigned char* lds, const Gemm g, const Sched& S, const Epi& E, const EpiSub& ES = EpiSub()) {
;     ...
;             PG8_LDB(B0, 0, 0); PG8_LDB(B1, 0, 1); PG8_SCHED; PG8_LDA(At, 0, 0); PG8_STAGE(PG8_SA(1, 1), a1 + hstepA, voffA);
;             PG8_WAIT_V(8); PG8_WAIT_L(0); PG8_BAR; PG8_MMA(0, 0, At, B0); PG8_MMA(0, 1, At, B1); PG8_BAR; PG8_SCHED;
;             PG8_LDA(At, 0, 1); PG8_STAGE(PG8_SB(0, 0), b2, voffB); PG8_STAGE(PG8_SB(0, 1), b2 + hstepB, voffB); PG8_STAGE(PG8_SA(0, 0), a2, voffA);
;             PG8_WAIT_V(8); PG8_WAIT_L(0); PG8_BAR; PG8_MMA(1, 0, At, B0); PG8_MMA(1, 1, At, B1); PG8_BAR; PG8_SCHED;
	v_mfma_f32_16x16x32_bf16 v[124:127], v[150:153], v[182:185], v[124:127]
	v_mfma_f32_16x16x32_bf16 v[116:119], v[158:161], v[182:185], v[116:119]
	v_mfma_f32_16x16x32_bf16 v[108:111], v[150:153], v[194:197], v[108:111]
	v_mfma_f32_16x16x32_bf16 v[100:103], v[158:161], v[194:197], v[100:103]
	v_mfma_f32_16x16x32_bf16 v[92:95], v[150:153], v[202:205], v[92:95]
	v_mfma_f32_16x16x32_bf16 v[84:87], v[158:161], v[202:205], v[84:87]
	v_mfma_f32_16x16x32_bf16 v[76:79], v[150:153], v[210:213], v[76:79]
	v_mfma_f32_16x16x32_bf16 v[68:71], v[158:161], v[210:213], v[68:71]
	v_mfma_f32_16x16x32_bf16 v[124:127], v[154:157], v[186:189], v[124:127]
	v_mfma_f32_16x16x32_bf16 v[116:119], v[162:165], v[186:189], v[116:119]
	v_mfma_f32_16x16x32_bf16 v[108:111], v[154:157], v[198:201], v[108:111]
	v_mfma_f32_16x16x32_bf16 v[100:103], v[162:165], v[198:201], v[100:103]
	v_mfma_f32_16x16x32_bf16 v[92:95], v[154:157], v[206:209], v[92:95]
	v_mfma_f32_16x16x32_bf16 v[84:87], v[162:165], v[206:209], v[84:87]
	v_mfma_f32_16x16x32_bf16 v[76:79], v[154:157], v[214:217], v[76:79]
	v_mfma_f32_16x16x32_bf16 v[68:71], v[162:165], v[214:217], v[68:71]
	v_mfma_f32_16x16x32_bf16 v[120:123], v[166:169], v[182:185], v[120:123]
	v_mfma_f32_16x16x32_bf16 v[112:115], v[174:177], v[182:185], v[112:115]
	v_mfma_f32_16x16x32_bf16 v[104:107], v[166:169], v[194:197], v[104:107]
	v_mfma_f32_16x16x32_bf16 v[96:99], v[174:177], v[194:197], v[96:99]
	v_mfma_f32_16x16x32_bf16 v[88:91], v[166:169], v[202:205], v[88:91]
	v_mfma_f32_16x16x32_bf16 v[80:83], v[174:177], v[202:205], v[80:83]
	v_mfma_f32_16x16x32_bf16 v[72:75], v[166:169], v[210:213], v[72:75]
	v_mfma_f32_16x16x32_bf16 v[64:67], v[174:177], v[210:213], v[64:67]
	v_mfma_f32_16x16x32_bf16 v[120:123], v[170:173], v[186:189], v[120:123]
	v_mfma_f32_16x16x32_bf16 v[112:115], v[178:181], v[186:189], v[112:115]
	v_mfma_f32_16x16x32_bf16 v[104:107], v[170:173], v[198:201], v[104:107]
	v_mfma_f32_16x16x32_bf16 v[96:99], v[178:181], v[198:201], v[96:99]
	v_mfma_f32_16x16x32_bf16 v[88:91], v[170:173], v[206:209], v[88:91]
	v_mfma_f32_16x16x32_bf16 v[80:83], v[178:181], v[206:209], v[80:83]
	v_mfma_f32_16x16x32_bf16 v[72:75], v[170:173], v[214:217], v[72:75]
	v_mfma_f32_16x16x32_bf16 v[64:67], v[178:181], v[214:217], v[64:67]
	s_barrier
	s_add_i32 s50, s42, s28
	v_lshl_add_u64 v[190:191], s[24:25], 0, v[130:131]
	s_mov_b32 m0, s50
	ds_read_b128 v[182:185], v149 offset:16384
	ds_read_b128 v[186:189], v149 offset:17408
	ds_read_b128 v[194:197], v149 offset:18432
	ds_read_b128 v[198:201], v149 offset:19456
	ds_read_b128 v[202:205], v149 offset:20480
	ds_read_b128 v[206:209], v149 offset:21504
	ds_read_b128 v[210:213], v149 offset:22528
	ds_read_b128 v[214:217], v149 offset:23552
	global_load_lds_dwordx4 v[190:191], off
	s_add_i32 m0, s50, 0x2000
	s_add_u32 s50, s24, 0x80000
	v_lshl_add_u64 v[218:219], s[24:25], 0, v[134:135]
	s_addc_u32 s51, s25, 0
	s_add_i32 s52, s43, s28
	global_load_lds_dwordx4 v[218:219], off
	v_lshl_add_u64 v[220:221], s[50:51], 0, v[130:131]
	s_mov_b32 m0, s52
	v_lshl_add_u64 v[222:223], s[26:27], 0, v[132:133]
	global_load_lds_dwordx4 v[220:221], off
	v_lshl_add_u64 v[220:221], s[50:51], 0, v[134:135]
	s_add_i32 m0, s52, 0x2000
	s_nop 0
	global_load_lds_dwordx4 v[220:221], off
	v_lshl_add_u64 v[220:221], s[26:27], 0, v[128:129]
	s_mov_b32 m0, s21
	s_nop 0
	global_load_lds_dwordx4 v[220:221], off
	s_mov_b32 m0, s31
	s_nop 0
	global_load_lds_dwordx4 v[222:223], off
	s_waitcnt vmcnt(8) lgkmcnt(0)
	s_barrier
	v_mfma_f32_16x16x32_bf16 v[60:63], v[150:153], v[182:185], v[60:63]
	v_mfma_f32_16x16x32_bf16 v[52:55], v[158:161], v[182:185], v[52:55]
	v_mfma_f32_16x16x32_bf16 v[44:47], v[150:153], v[194:197], v[44:47]
	v_mfma_f32_16x16x32_bf16 v[36:39], v[158:161], v[194:197], v[36:39]
	v_mfma_f32_16x16x32_bf16 v[28:31], v[150:153], v[202:205], v[28:31]
	v_mfma_f32_16x16x32_bf16 v[20:23], v[158:161], v[202:205], v[20:23]
	v_mfma_f32_16x16x32_bf16 v[12:15], v[150:153], v[210:213], v[12:15]
	v_mfma_f32_16x16x32_bf16 v[4:7], v[158:161], v[210:213], v[4:7]
	v_mfma_f32_16x16x32_bf16 v[60:63], v[154:157], v[186:189], v[60:63]
	v_mfma_f32_16x16x32_bf16 v[52:55], v[162:165], v[186:189], v[52:55]
	v_mfma_f32_16x16x32_bf16 v[44:47], v[154:157], v[198:201], v[44:47]
	v_mfma_f32_16x16x32_bf16 v[36:39], v[162:165], v[198:201], v[36:39]
	v_mfma_f32_16x16x32_bf16 v[28:31], v[154:157], v[206:209], v[28:31]
	v_mfma_f32_16x16x32_bf16 v[20:23], v[162:165], v[206:209], v[20:23]
	v_mfma_f32_16x16x32_bf16 v[12:15], v[154:157], v[214:217], v[12:15]
	v_mfma_f32_16x16x32_bf16 v[4:7], v[162:165], v[214:217], v[4:7]
	v_mfma_f32_16x16x32_bf16 v[56:59], v[166:169], v[182:185], v[56:59]
	v_mfma_f32_16x16x32_bf16 v[48:51], v[174:177], v[182:185], v[48:51]
	v_mfma_f32_16x16x32_bf16 v[40:43], v[166:169], v[194:197], v[40:43]
	v_mfma_f32_16x16x32_bf16 v[32:35], v[174:177], v[194:197], v[32:35]
	v_mfma_f32_16x16x32_bf16 v[24:27], v[166:169], v[202:205], v[24:27]
	v_mfma_f32_16x16x32_bf16 v[16:19], v[174:177], v[202:205], v[16:19]
	v_mfma_f32_16x16x32_bf16 v[8:11], v[166:169], v[210:213], v[8:11]
	v_mfma_f32_16x16x32_bf16 v[0:3], v[174:177], v[210:213], v[0:3]
	v_mfma_f32_16x16x32_bf16 v[56:59], v[170:173], v[186:189], v[56:59]
	v_mfma_f32_16x16x32_bf16 v[48:51], v[178:181], v[186:189], v[48:51]
	v_mfma_f32_16x16x32_bf16 v[40:43], v[170:173], v[198:201], v[40:43]
	v_mfma_f32_16x16x32_bf16 v[32:35], v[178:181], v[198:201], v[32:35]
	v_mfma_f32_16x16x32_bf16 v[24:27], v[170:173], v[206:209], v[24:27]
	v_mfma_f32_16x16x32_bf16 v[16:19], v[178:181], v[206:209], v[16:19]
	v_mfma_f32_16x16x32_bf16 v[8:11], v[170:173], v[214:217], v[8:11]
	v_mfma_f32_16x16x32_bf16 v[0:3], v[178:181], v[214:217], v[0:3]
	s_barrier
; #define PG8_STAGE(bufoff, gbase, voff) do { _Pragma("unroll") for (int _i = 0; _i < 2; ++_i) \
;         __builtin_amdgcn_global_load_lds((const unsigned*)((const char*)(gbase) + (voff)[_i]), (LAS unsigned*)(lds + (bufoff) + ldsw + _i * 8192), 16, 0, 0); } while (0)
; #define PG8_LDA(dst, b, h) do { _Pragma("unroll") for (int m = 0; m < 4; ++m) _Pragma("unroll") for (int k = 0; k < 2; ++k) dst[m][k] = *(const LAS bf16x8*)(lds + PG8_SA(b, h) + aoff + m * 2048 + k * 1024); } while (0)
; #define PG8_LDB(dst, b, h) do { _Pragma("unroll") for (int n = 0; n < 2; ++n) _Pragma("unroll") for (int k = 0; k < 2; ++k) dst[n][k] = *(const LAS bf16x8*)(lds + PG8_SB(b, h) + boff + n * 2048 + k * 1024); } while (0)
; #define PG8_MMA(ai, bj, At, Bt) do { __builtin_amdgcn_s_setprio(1); _Pragma("unroll") for (int m = 0; m < 4; ++m) _Pragma("unroll") for (int n = 0; n < 2; ++n) _Pragma("unroll") for (int k = 0; k < 2; ++k) \
;         acc[ai][bj][m][n] = __builtin_amdgcn_mfma_f32_16x16x32_bf16(Bt[n][k], At[m][k], acc[ai][bj][m][n], 0, 0, 0); __builtin_amdgcn_s_setprio(0); } while (0)
; #define PG8_WAIT_V(n) asm volatile("s_waitcnt vmcnt(" #n ")" ::: "memory")
; #define PG8_WAIT_L(n) asm volatile("s_waitcnt lgkmcnt(" #n ")" ::: "memory")
; #define PG8_BAR __builtin_amdgcn_s_barrier()
; #define PG8_SCHED __builtin_amdgcn_sched_barrier(0)
; template <class Epi, class Sched = StaticOrder, class EpiSub = NoSub, bool FAST = false>
; __device__ __forceinline__ void gemm_phase(LAS unsigned char* lds, const Gemm g, const Sched& S, const Epi& E, const EpiSub& ES = EpiSub()) {
;     ...
;             PG8_LDB(B0, 1, 0); PG8_LDB(B1, 1, 1); PG8_SCHED; PG8_LDA(At, 1, 0); PG8_STAGE(PG8_SA(0, 1), a2 + hstepA, voffA);
;             PG8_WAIT_V(8); PG8_WAIT_L(0); PG8_BAR; PG8_MMA(0, 0, At, B0); PG8_MMA(0, 1, At, B1); PG8_BAR; PG8_SCHED;
;             PG8_LDA(At, 1, 1); PG8_STAGE(PG8_SB(1, 0), b3, voffB); PG8_STAGE(PG8_SB(1, 1), b3 + hstepB, voffB); PG8_STAGE(PG8_SA(1, 0), a3, voffA);
;             PG8_WAIT_V(8); PG8_WAIT_L(0); PG8_BAR; PG8_MMA(1, 0, At, B0); PG8_MMA(1, 1, At, B1); PG8_BAR; PG8_SCHED;
	s_add_i32 s50, 0, 0x18000
	s_add_i32 s51, 0, 0x1c000
	v_add_u32_e32 v162, s50, v145
	v_add_u32_e32 v178, s51, v145
	ds_read_b128 v[150:153], v162
	ds_read_b128 v[154:157], v162 offset:1024
	ds_read_b128 v[158:161], v162 offset:2048
	ds_read_b128 v[162:165], v162 offset:3072
	ds_read_b128 v[166:169], v178
	ds_read_b128 v[170:173], v178 offset:1024
	ds_read_b128 v[174:177], v178 offset:2048
	ds_read_b128 v[178:181], v178 offset:3072
	s_add_u32 s26, s26, 0x80000
	s_addc_u32 s27, s27, 0
	s_mov_b32 m0, s36
	v_lshl_add_u64 v[224:225], s[26:27], 0, v[128:129]
	ds_read_b128 v[182:185], v149 offset:32768
	ds_read_b128 v[186:189], v149 offset:33792
	ds_read_b128 v[194:197], v149 offset:34816
	ds_read_b128 v[198:201], v149 offset:35840
	ds_read_b128 v[202:205], v149 offset:36864
	ds_read_b128 v[206:209], v149 offset:37888
	ds_read_b128 v[210:213], v149 offset:38912
	ds_read_b128 v[214:217], v149 offset:39936
	global_load_lds_dwordx4 v[224:225], off
	v_lshl_add_u64 v[224:225], s[26:27], 0, v[132:133]
	s_mov_b32 m0, s37
	s_nop 0
	global_load_lds_dwordx4 v[224:225], off
	s_waitcnt vmcnt(8) lgkmcnt(0)
	s_barrier
	v_mfma_f32_16x16x32_bf16 v[124:127], v[150:153], v[182:185], v[124:127]
	v_mfma_f32_16x16x32_bf16 v[116:119], v[158:161], v[182:185], v[116:119]
	v_mfma_f32_16x16x32_bf16 v[108:111], v[150:153], v[194:197], v[108:111]
	v_mfma_f32_16x16x32_bf16 v[100:103], v[158:161], v[194:197], v[100:103]
	v_mfma_f32_16x16x32_bf16 v[92:95], v[150:153], v[202:205], v[92:95]
	v_mfma_f32_16x16x32_bf16 v[84:87], v[158:161], v[202:205], v[84:87]
	v_mfma_f32_16x16x32_bf16 v[76:79], v[150:153], v[210:213], v[76:79]
	v_mfma_f32_16x16x32_bf16 v[68:71], v[158:161], v[210:213], v[68:71]
	v_mfma_f32_16x16x32_bf16 v[124:127], v[154:157], v[186:189], v[124:127]
	v_mfma_f32_16x16x32_bf16 v[116:119], v[162:165], v[186:189], v[116:119]
	v_mfma_f32_16x16x32_bf16 v[108:111], v[154:157], v[198:201], v[108:111]
	v_mfma_f32_16x16x32_bf16 v[100:103], v[162:165], v[198:201], v[100:103]
	v_mfma_f32_16x16x32_bf16 v[92:95], v[154:157], v[206:209], v[92:95]
	v_mfma_f32_16x16x32_bf16 v[84:87], v[162:165], v[206:209], v[84:87]
	v_mfma_f32_16x16x32_bf16 v[76:79], v[154:157], v[214:217], v[76:79]
	v_mfma_f32_16x16x32_bf16 v[68:71], v[162:165], v[214:217], v[68:71]
	v_mfma_f32_16x16x32_bf16 v[120:123], v[166:169], v[182:185], v[120:123]
	v_mfma_f32_16x16x32_bf16 v[112:115], v[174:177], v[182:185], v[112:115]
	v_mfma_f32_16x16x32_bf16 v[104:107], v[166:169], v[194:197], v[104:107]
	v_mfma_f32_16x16x32_bf16 v[96:99], v[174:177], v[194:197], v[96:99]
	v_mfma_f32_16x16x32_bf16 v[88:91], v[166:169], v[202:205], v[88:91]
	v_mfma_f32_16x16x32_bf16 v[80:83], v[174:177], v[202:205], v[80:83]
	v_mfma_f32_16x16x32_bf16 v[72:75], v[166:169], v[210:213], v[72:75]
	v_mfma_f32_16x16x32_bf16 v[64:67], v[174:177], v[210:213], v[64:67]
	v_mfma_f32_16x16x32_bf16 v[120:123], v[170:173], v[186:189], v[120:123]
	v_mfma_f32_16x16x32_bf16 v[112:115], v[178:181], v[186:189], v[112:115]
	v_mfma_f32_16x16x32_bf16 v[104:107], v[170:173], v[198:201], v[104:107]
	v_mfma_f32_16x16x32_bf16 v[96:99], v[178:181], v[198:201], v[96:99]
	v_mfma_f32_16x16x32_bf16 v[88:91], v[170:173], v[206:209], v[88:91]
	v_mfma_f32_16x16x32_bf16 v[80:83], v[178:181], v[206:209], v[80:83]
	v_mfma_f32_16x16x32_bf16 v[72:75], v[170:173], v[214:217], v[72:75]
	v_mfma_f32_16x16x32_bf16 v[64:67], v[178:181], v[214:217], v[64:67]
	s_barrier
	s_add_i32 s26, s50, s28
	v_lshl_add_u64 v[190:191], v[190:191], 0, s[8:9]
	s_mov_b32 m0, s26
	ds_read_b128 v[182:185], v149 offset:49152
	ds_read_b128 v[186:189], v149 offset:50176
	ds_read_b128 v[194:197], v149 offset:51200
	ds_read_b128 v[198:201], v149 offset:52224
	ds_read_b128 v[202:205], v149 offset:53248
	ds_read_b128 v[206:209], v149 offset:54272
	ds_read_b128 v[210:213], v149 offset:55296
	ds_read_b128 v[214:217], v149 offset:56320
	global_load_lds_dwordx4 v[190:191], off
	s_add_i32 m0, s26, 0x2000
	s_add_u32 s24, s24, 0x80080
	v_lshl_add_u64 v[190:191], v[218:219], 0, s[8:9]
	s_addc_u32 s25, s25, 0
	s_add_i32 s26, s51, s28
	global_load_lds_dwordx4 v[190:191], off
	v_lshl_add_u64 v[190:191], s[24:25], 0, v[130:131]
	s_mov_b32 m0, s26
	s_nop 0
	global_load_lds_dwordx4 v[190:191], off
	v_lshl_add_u64 v[190:191], s[24:25], 0, v[134:135]
	s_add_i32 m0, s26, 0x2000
	s_nop 0
	global_load_lds_dwordx4 v[190:191], off
	v_lshl_add_u64 v[190:191], v[220:221], 0, s[8:9]
	s_mov_b32 m0, s40
	s_nop 0
	global_load_lds_dwordx4 v[190:191], off
	v_lshl_add_u64 v[190:191], v[222:223], 0, s[8:9]
	s_mov_b32 m0, s41
	s_nop 0
	global_load_lds_dwordx4 v[190:191], off
	s_waitcnt vmcnt(8) lgkmcnt(0)
	s_barrier
	v_mfma_f32_16x16x32_bf16 v[60:63], v[150:153], v[182:185], v[60:63]
	v_mfma_f32_16x16x32_bf16 v[52:55], v[158:161], v[182:185], v[52:55]
	v_mfma_f32_16x16x32_bf16 v[44:47], v[150:153], v[194:197], v[44:47]
	v_mfma_f32_16x16x32_bf16 v[36:39], v[158:161], v[194:197], v[36:39]
	v_mfma_f32_16x16x32_bf16 v[28:31], v[150:153], v[202:205], v[28:31]
	v_mfma_f32_16x16x32_bf16 v[20:23], v[158:161], v[202:205], v[20:23]
	v_mfma_f32_16x16x32_bf16 v[12:15], v[150:153], v[210:213], v[12:15]
	v_mfma_f32_16x16x32_bf16 v[4:7], v[158:161], v[210:213], v[4:7]
	v_mfma_f32_16x16x32_bf16 v[60:63], v[154:157], v[186:189], v[60:63]
	v_mfma_f32_16x16x32_bf16 v[52:55], v[162:165], v[186:189], v[52:55]
	v_mfma_f32_16x16x32_bf16 v[44:47], v[154:157], v[198:201], v[44:47]
	v_mfma_f32_16x16x32_bf16 v[36:39], v[162:165], v[198:201], v[36:39]
	v_mfma_f32_16x16x32_bf16 v[28:31], v[154:157], v[206:209], v[28:31]
	v_mfma_f32_16x16x32_bf16 v[20:23], v[162:165], v[206:209], v[20:23]
	v_mfma_f32_16x16x32_bf16 v[12:15], v[154:157], v[214:217], v[12:15]
	v_mfma_f32_16x16x32_bf16 v[4:7], v[162:165], v[214:217], v[4:7]
	v_mfma_f32_16x16x32_bf16 v[56:59], v[166:169], v[182:185], v[56:59]
	v_mfma_f32_16x16x32_bf16 v[48:51], v[174:177], v[182:185], v[48:51]
	v_mfma_f32_16x16x32_bf16 v[40:43], v[166:169], v[194:197], v[40:43]
	v_mfma_f32_16x16x32_bf16 v[32:35], v[174:177], v[194:197], v[32:35]
	v_mfma_f32_16x16x32_bf16 v[24:27], v[166:169], v[202:205], v[24:27]
	v_mfma_f32_16x16x32_bf16 v[16:19], v[174:177], v[202:205], v[16:19]
	v_mfma_f32_16x16x32_bf16 v[8:11], v[166:169], v[210:213], v[8:11]
	v_mfma_f32_16x16x32_bf16 v[0:3], v[174:177], v[210:213], v[0:3]
	v_mfma_f32_16x16x32_bf16 v[56:59], v[170:173], v[186:189], v[56:59]
	v_mfma_f32_16x16x32_bf16 v[48:51], v[178:181], v[186:189], v[48:51]
	v_mfma_f32_16x16x32_bf16 v[40:43], v[170:173], v[198:201], v[40:43]
	v_mfma_f32_16x16x32_bf16 v[32:35], v[178:181], v[198:201], v[32:35]
	v_mfma_f32_16x16x32_bf16 v[24:27], v[170:173], v[206:209], v[24:27]
	v_mfma_f32_16x16x32_bf16 v[16:19], v[178:181], v[206:209], v[16:19]
	v_mfma_f32_16x16x32_bf16 v[8:11], v[170:173], v[214:217], v[8:11]
	v_mfma_f32_16x16x32_bf16 v[0:3], v[178:181], v[214:217], v[0:3]
	s_barrier
	s_add_i32 s49, s49, 2
	s_add_u32 s22, s22, 0x100
	s_addc_u32 s23, s23, 0
	s_add_u32 s47, s47, 0x100
	s_addc_u32 s48, s48, 0
	s_cmp_gt_u32 s49, 29
	s_cbranch_scc0 .LBB0_985

; #define PG8_STAGE(bufoff, gbase, voff) do { _Pragma("unroll") for (int _i = 0; _i < 2; ++_i) \
;         __builtin_amdgcn_global_load_lds((const unsigned*)((const char*)(gbase) + (voff)[_i]), (LAS unsigned*)(lds + (bufoff) + ldsw + _i * 8192), 16, 0, 0); } while (0)
; #define PG8_LDA(dst, b, h) do { _Pragma("unroll") for (int m = 0; m < 4; ++m) _Pragma("unroll") for (int k = 0; k < 2; ++k) dst[m][k] = *(const LAS bf16x8*)(lds + PG8_SA(b, h) + aoff + m * 2048 + k * 1024); } while (0)
; #define PG8_LDB(dst, b, h) do { _Pragma("unroll") for (int n = 0; n < 2; ++n) _Pragma("unroll") for (int k = 0; k < 2; ++k) dst[n][k] = *(const LAS bf16x8*)(lds + PG8_SB(b, h) + boff + n * 2048 + k * 1024); } while (0)
; #define PG8_MMA(ai, bj, At, Bt) do { __builtin_amdgcn_s_setprio(1); _Pragma("unroll") for (int m = 0; m < 4; ++m) _Pragma("unroll") for (int n = 0; n < 2; ++n) _Pragma("unroll") for (int k = 0; k < 2; ++k) \
;         acc[ai][bj][m][n] = __builtin_amdgcn_mfma_f32_16x16x32_bf16(Bt[n][k], At[m][k], acc[ai][bj][m][n], 0, 0, 0); __builtin_amdgcn_s_setprio(0); } while (0)
; #define PG8_WAIT_V(n) asm volatile("s_waitcnt vmcnt(" #n ")" ::: "memory")
; template <class Epi, class Sched = StaticOrder, class EpiSub = NoSub, bool FAST = false>
; __device__ __forceinline__ void gemm_phase(LAS unsigned char* lds, const Gemm g, const Sched& S, const Epi& E, const EpiSub& ES = EpiSub()) {
;     ...
;         const size_t nko = (has_next && nxt.kb >= 0) ? nxt.kb * ksubB : 0;
;         const char* nA = has_next ? (const char*)g.A + (size_t)nxt.pm * tstepA + (size_t)nxt.pn * g.acs + nko : cA; const char* nB = has_next ? (const char*)g.Bt + (size_t)nxt.pn * tstepB + nko : cB;
;         const int nt = cur.kb < 0 ? ntMain : ntSub;
;         for (int t = 0; t < nt; t += 2) {
;             const bool last = (t == nt - 2);
;             const char* a1 = cA + (size_t)(t + 1) * kstep;
;             const char* a2 = last ? nA : cA + (size_t)(t + 2) * kstep; const char* b2 = last ? nB : cB + (size_t)(t + 2) * kstep;
;             const char* a3 = a2 + kstep; const char* b3 = b2 + kstep;
;             if constexpr (FAST && PG8_SP2) {
;             PG8_LDB(B0, 0, 0); PG8_LDB(B1, 0, 1); PG8_SCHED; PG8_LDA(At, 0, 0); PG8_STAGE(PG8_SA(1, 1), a1 + hstepA, voffA);
;             PG8_WAIT_V(8); PG8_WAIT_L(0); PG8_BAR; PG8_MMA(0, 0, At, B0); PG8_MMA(0, 1, At, B1); PG8_BAR; PG8_SCHED;
.LBB0_1078:
	s_cmp_gt_i32 s8, -1
	s_cselect_b64 s[4:5], -1, 0
	s_cmp_lt_i32 s8, 0
	s_cselect_b32 s70, 0x58, 22
	s_add_i32 s71, s70, -2
	s_add_u32 s42, s42, 0x160080
	s_addc_u32 s43, s43, 0
	s_add_u32 s83, s44, 0x100
	s_mov_b32 s46, 0
	s_addc_u32 s84, s45, 0
	ds_read_b128 v[96:99], v201
	ds_read_b128 v[100:103], v201 offset:1024
	ds_read_b128 v[108:111], v201 offset:2048
	ds_read_b128 v[116:119], v201 offset:3072
	ds_read_b128 v[144:147], v202
	ds_read_b128 v[148:151], v202 offset:1024
	ds_read_b128 v[152:155], v202 offset:2048
	ds_read_b128 v[156:159], v202 offset:3072
	s_add_i32 s85, s46, 2
	s_add_u32 s44, s42, 0xffea0080
	s_addc_u32 s45, s43, -1
	s_cmp_eq_u32 s71, s46
	s_cselect_b32 s46, s38, s44
	s_cselect_b32 s47, s39, s45
	s_cselect_b32 s45, s41, s84
	s_cselect_b32 s44, s40, s83
	v_lshl_add_u64 v[190:191], s[42:43], 0, v[176:177]
	s_add_i32 m0, s48, 0xc000
	ds_read_b128 v[160:163], v203
	ds_read_b128 v[164:167], v203 offset:1024
	ds_read_b128 v[182:185], v203 offset:2048
	ds_read_b128 v[186:189], v203 offset:3072
	ds_read_b128 v[194:197], v203 offset:4096
	ds_read_b128 v[204:207], v203 offset:5120
	ds_read_b128 v[208:211], v203 offset:6144
	ds_read_b128 v[212:215], v203 offset:7168
	global_load_lds_dwordx4 v[190:191], off
	v_lshl_add_u64 v[190:191], s[42:43], 0, v[178:179]
	s_add_i32 m0, s48, 0xe000
	s_nop 0
	global_load_lds_dwordx4 v[190:191], off
	s_waitcnt vmcnt(8) lgkmcnt(0)
	s_barrier
	v_mfma_f32_16x16x32_bf16 v[140:143], v[96:99], v[160:163], 0
	v_mfma_f32_16x16x32_bf16 v[136:139], v[108:111], v[160:163], 0
	v_mfma_f32_16x16x32_bf16 v[124:127], v[96:99], v[182:185], 0
	v_mfma_f32_16x16x32_bf16 v[120:123], v[108:111], v[182:185], 0
	v_mfma_f32_16x16x32_bf16 v[92:95], v[96:99], v[194:197], 0
	v_mfma_f32_16x16x32_bf16 v[88:91], v[108:111], v[194:197], 0
	v_mfma_f32_16x16x32_bf16 v[76:79], v[96:99], v[208:211], 0
	v_mfma_f32_16x16x32_bf16 v[72:75], v[108:111], v[208:211], 0
	v_mfma_f32_16x16x32_bf16 v[140:143], v[100:103], v[164:167], v[140:143]
	v_mfma_f32_16x16x32_bf16 v[136:139], v[116:119], v[164:167], v[136:139]
	v_mfma_f32_16x16x32_bf16 v[124:127], v[100:103], v[186:189], v[124:127]
	v_mfma_f32_16x16x32_bf16 v[120:123], v[116:119], v[186:189], v[120:123]
	v_mfma_f32_16x16x32_bf16 v[92:95], v[100:103], v[204:207], v[92:95]
	v_mfma_f32_16x16x32_bf16 v[88:91], v[116:119], v[204:207], v[88:91]
	v_mfma_f32_16x16x32_bf16 v[76:79], v[100:103], v[212:215], v[76:79]
	v_mfma_f32_16x16x32_bf16 v[72:75], v[116:119], v[212:215], v[72:75]
	v_mfma_f32_16x16x32_bf16 v[132:135], v[144:147], v[160:163], 0
	v_mfma_f32_16x16x32_bf16 v[128:131], v[152:155], v[160:163], 0
	v_mfma_f32_16x16x32_bf16 v[112:115], v[144:147], v[182:185], 0
	v_mfma_f32_16x16x32_bf16 v[104:107], v[152:155], v[182:185], 0
	v_mfma_f32_16x16x32_bf16 v[84:87], v[144:147], v[194:197], 0
	v_mfma_f32_16x16x32_bf16 v[80:83], v[152:155], v[194:197], 0
	v_mfma_f32_16x16x32_bf16 v[68:71], v[144:147], v[208:211], 0
	v_mfma_f32_16x16x32_bf16 v[64:67], v[152:155], v[208:211], 0
	v_mfma_f32_16x16x32_bf16 v[132:135], v[148:151], v[164:167], v[132:135]
	v_mfma_f32_16x16x32_bf16 v[128:131], v[156:159], v[164:167], v[128:131]
	v_mfma_f32_16x16x32_bf16 v[112:115], v[148:151], v[186:189], v[112:115]
	v_mfma_f32_16x16x32_bf16 v[104:107], v[156:159], v[186:189], v[104:107]
	v_mfma_f32_16x16x32_bf16 v[84:87], v[148:151], v[204:207], v[84:87]
	v_mfma_f32_16x16x32_bf16 v[80:83], v[156:159], v[204:207], v[80:83]
	v_mfma_f32_16x16x32_bf16 v[68:71], v[148:151], v[212:215], v[68:71]
	v_mfma_f32_16x16x32_bf16 v[64:67], v[156:159], v[212:215], v[64:67]
	s_barrier
	s_add_i32 s86, s58, s27
	v_lshl_add_u64 v[190:191], s[44:45], 0, v[170:171]
	s_mov_b32 m0, s86
	ds_read_b128 v[160:163], v203 offset:16384
	ds_read_b128 v[164:167], v203 offset:17408
	ds_read_b128 v[182:185], v203 offset:18432
	ds_read_b128 v[186:189], v203 offset:19456
	ds_read_b128 v[194:197], v203 offset:20480
	ds_read_b128 v[204:207], v203 offset:21504
	ds_read_b128 v[208:211], v203 offset:22528
	ds_read_b128 v[212:215], v203 offset:23552
	global_load_lds_dwordx4 v[190:191], off
	s_add_i32 m0, s86, 0x2000
	s_add_u32 s86, s44, 0x160000
	v_lshl_add_u64 v[216:217], s[44:45], 0, v[174:175]
	s_addc_u32 s87, s45, 0
	s_add_i32 s88, s59, s27
	global_load_lds_dwordx4 v[216:217], off
	v_lshl_add_u64 v[218:219], s[86:87], 0, v[170:171]
	s_mov_b32 m0, s88
	v_lshl_add_u64 v[220:221], s[46:47], 0, v[172:173]
	global_load_lds_dwordx4 v[218:219], off
	v_lshl_add_u64 v[218:219], s[86:87], 0, v[174:175]
	s_add_i32 m0, s88, 0x2000
	s_nop 0
	global_load_lds_dwordx4 v[218:219], off
	v_lshl_add_u64 v[218:219], s[46:47], 0, v[168:169]
	s_mov_b32 m0, s48
	s_nop 0
	global_load_lds_dwordx4 v[218:219], off
	s_mov_b32 m0, s49
	s_nop 0
	global_load_lds_dwordx4 v[220:221], off
	s_waitcnt vmcnt(8) lgkmcnt(0)
	s_barrier
; #define PG8_STAGE(bufoff, gbase, voff) do { _Pragma("unroll") for (int _i = 0; _i < 2; ++_i) \
;         __builtin_amdgcn_global_load_lds((const unsigned*)((const char*)(gbase) + (voff)[_i]), (LAS unsigned*)(lds + (bufoff) + ldsw + _i * 8192), 16, 0, 0); } while (0)
; #define PG8_LDA(dst, b, h) do { _Pragma("unroll") for (int m = 0; m < 4; ++m) _Pragma("unroll") for (int k = 0; k < 2; ++k) dst[m][k] = *(const LAS bf16x8*)(lds + PG8_SA(b, h) + aoff + m * 2048 + k * 1024); } while (0)
; #define PG8_LDB(dst, b, h) do { _Pragma("unroll") for (int n = 0; n < 2; ++n) _Pragma("unroll") for (int k = 0; k < 2; ++k) dst[n][k] = *(const LAS bf16x8*)(lds + PG8_SB(b, h) + boff + n * 2048 + k * 1024); } while (0)
; #define PG8_MMA(ai, bj, At, Bt) do { __builtin_amdgcn_s_setprio(1); _Pragma("unroll") for (int m = 0; m < 4; ++m) _Pragma("unroll") for (int n = 0; n < 2; ++n) _Pragma("unroll") for (int k = 0; k < 2; ++k) \
;         acc[ai][bj][m][n] = __builtin_amdgcn_mfma_f32_16x16x32_bf16(Bt[n][k], At[m][k], acc[ai][bj][m][n], 0, 0, 0); __builtin_amdgcn_s_setprio(0); } while (0)
; #define PG8_WAIT_V(n) asm volatile("s_waitcnt vmcnt(" #n ")" ::: "memory")
; #define PG8_WAIT_L(n) asm volatile("s_waitcnt lgkmcnt(" #n ")" ::: "memory")
; #define PG8_BAR __builtin_amdgcn_s_barrier()
; #define PG8_SCHED __builtin_amdgcn_sched_barrier(0)
; template <class Epi, class Sched = StaticOrder, class EpiSub = NoSub, bool FAST = false>
; __device__ __forceinline__ void gemm_phase(LAS unsigned char* lds, const Gemm g, const Sched& S, const Epi& E, const EpiSub& ES = EpiSub()) {
;     ...
;             PG8_WAIT_V(8); PG8_WAIT_L(0); PG8_BAR; PG8_MMA(0, 0, At, B0); PG8_MMA(0, 1, At, B1); PG8_BAR; PG8_SCHED;
;             PG8_LDA(At, 0, 1); PG8_STAGE(PG8_SB(0, 0), b2, voffB); PG8_STAGE(PG8_SB(0, 1), b2 + hstepB, voffB); PG8_STAGE(PG8_SA(0, 0), a2, voffA);
;             PG8_WAIT_V(8); PG8_WAIT_L(0); PG8_BAR; PG8_MMA(1, 0, At, B0); PG8_MMA(1, 1, At, B1); PG8_BAR; PG8_SCHED;
;             PG8_LDB(B0, 1, 0); PG8_LDB(B1, 1, 1); PG8_SCHED; PG8_LDA(At, 1, 0); PG8_STAGE(PG8_SA(0, 1), a2 + hstepA, voffA);
;             PG8_WAIT_V(8); PG8_WAIT_L(0); PG8_BAR; PG8_MMA(0, 0, At, B0); PG8_MMA(0, 1, At, B1); PG8_BAR; PG8_SCHED;
	v_mfma_f32_16x16x32_bf16 v[60:63], v[96:99], v[160:163], 0
	v_mfma_f32_16x16x32_bf16 v[56:59], v[108:111], v[160:163], 0
	v_mfma_f32_16x16x32_bf16 v[44:47], v[96:99], v[182:185], 0
	v_mfma_f32_16x16x32_bf16 v[40:43], v[108:111], v[182:185], 0
	v_mfma_f32_16x16x32_bf16 v[28:31], v[96:99], v[194:197], 0
	v_mfma_f32_16x16x32_bf16 v[24:27], v[108:111], v[194:197], 0
	v_mfma_f32_16x16x32_bf16 v[12:15], v[96:99], v[208:211], 0
	v_mfma_f32_16x16x32_bf16 v[8:11], v[108:111], v[208:211], 0
	v_mfma_f32_16x16x32_bf16 v[60:63], v[100:103], v[164:167], v[60:63]
	v_mfma_f32_16x16x32_bf16 v[56:59], v[116:119], v[164:167], v[56:59]
	v_mfma_f32_16x16x32_bf16 v[44:47], v[100:103], v[186:189], v[44:47]
	v_mfma_f32_16x16x32_bf16 v[40:43], v[116:119], v[186:189], v[40:43]
	v_mfma_f32_16x16x32_bf16 v[28:31], v[100:103], v[204:207], v[28:31]
	v_mfma_f32_16x16x32_bf16 v[24:27], v[116:119], v[204:207], v[24:27]
	v_mfma_f32_16x16x32_bf16 v[12:15], v[100:103], v[212:215], v[12:15]
	v_mfma_f32_16x16x32_bf16 v[8:11], v[116:119], v[212:215], v[8:11]
	v_mfma_f32_16x16x32_bf16 v[52:55], v[144:147], v[160:163], 0
	v_mfma_f32_16x16x32_bf16 v[48:51], v[152:155], v[160:163], 0
	v_mfma_f32_16x16x32_bf16 v[36:39], v[144:147], v[182:185], 0
	v_mfma_f32_16x16x32_bf16 v[32:35], v[152:155], v[182:185], 0
	v_mfma_f32_16x16x32_bf16 v[20:23], v[144:147], v[194:197], 0
	v_mfma_f32_16x16x32_bf16 v[16:19], v[152:155], v[194:197], 0
	v_mfma_f32_16x16x32_bf16 v[4:7], v[144:147], v[208:211], 0
	v_mfma_f32_16x16x32_bf16 v[0:3], v[152:155], v[208:211], 0
	v_mfma_f32_16x16x32_bf16 v[52:55], v[148:151], v[164:167], v[52:55]
	v_mfma_f32_16x16x32_bf16 v[48:51], v[156:159], v[164:167], v[48:51]
	v_mfma_f32_16x16x32_bf16 v[36:39], v[148:151], v[186:189], v[36:39]
	v_mfma_f32_16x16x32_bf16 v[32:35], v[156:159], v[186:189], v[32:35]
	v_mfma_f32_16x16x32_bf16 v[20:23], v[148:151], v[204:207], v[20:23]
	v_mfma_f32_16x16x32_bf16 v[16:19], v[156:159], v[204:207], v[16:19]
	v_mfma_f32_16x16x32_bf16 v[4:7], v[148:151], v[212:215], v[4:7]
	v_mfma_f32_16x16x32_bf16 v[0:3], v[156:159], v[212:215], v[0:3]
	s_barrier
	s_add_i32 s86, 0, 0x18000
	s_add_i32 s87, 0, 0x1c000
	v_add_u32_e32 v116, s86, v198
	v_add_u32_e32 v156, s87, v198
	ds_read_b128 v[96:99], v116
	ds_read_b128 v[100:103], v116 offset:1024
	ds_read_b128 v[108:111], v116 offset:2048
	ds_read_b128 v[116:119], v116 offset:3072
	ds_read_b128 v[144:147], v156
	ds_read_b128 v[148:151], v156 offset:1024
	ds_read_b128 v[152:155], v156 offset:2048
	ds_read_b128 v[156:159], v156 offset:3072
	s_add_u32 s46, s46, 0x160000
	s_addc_u32 s47, s47, 0
	s_mov_b32 m0, s50
	v_lshl_add_u64 v[222:223], s[46:47], 0, v[168:169]
	ds_read_b128 v[160:163], v203 offset:32768
	ds_read_b128 v[164:167], v203 offset:33792
	ds_read_b128 v[182:185], v203 offset:34816
	ds_read_b128 v[186:189], v203 offset:35840
	ds_read_b128 v[194:197], v203 offset:36864
	ds_read_b128 v[204:207], v203 offset:37888
	ds_read_b128 v[208:211], v203 offset:38912
	ds_read_b128 v[212:215], v203 offset:39936
	global_load_lds_dwordx4 v[222:223], off
	v_lshl_add_u64 v[222:223], s[46:47], 0, v[172:173]
	s_mov_b32 m0, s51
	s_nop 0
	global_load_lds_dwordx4 v[222:223], off
	s_waitcnt vmcnt(8) lgkmcnt(0)
	s_barrier
	v_mfma_f32_16x16x32_bf16 v[140:143], v[96:99], v[160:163], v[140:143]
	v_mfma_f32_16x16x32_bf16 v[136:139], v[108:111], v[160:163], v[136:139]
	v_mfma_f32_16x16x32_bf16 v[124:127], v[96:99], v[182:185], v[124:127]
	v_mfma_f32_16x16x32_bf16 v[120:123], v[108:111], v[182:185], v[120:123]
	v_mfma_f32_16x16x32_bf16 v[92:95], v[96:99], v[194:197], v[92:95]
	v_mfma_f32_16x16x32_bf16 v[88:91], v[108:111], v[194:197], v[88:91]
	v_mfma_f32_16x16x32_bf16 v[76:79], v[96:99], v[208:211], v[76:79]
	v_mfma_f32_16x16x32_bf16 v[72:75], v[108:111], v[208:211], v[72:75]
	v_mfma_f32_16x16x32_bf16 v[140:143], v[100:103], v[164:167], v[140:143]
	v_mfma_f32_16x16x32_bf16 v[136:139], v[116:119], v[164:167], v[136:139]
	v_mfma_f32_16x16x32_bf16 v[124:127], v[100:103], v[186:189], v[124:127]
	v_mfma_f32_16x16x32_bf16 v[120:123], v[116:119], v[186:189], v[120:123]
	v_mfma_f32_16x16x32_bf16 v[92:95], v[100:103], v[204:207], v[92:95]
	v_mfma_f32_16x16x32_bf16 v[88:91], v[116:119], v[204:207], v[88:91]
	v_mfma_f32_16x16x32_bf16 v[76:79], v[100:103], v[212:215], v[76:79]
	v_mfma_f32_16x16x32_bf16 v[72:75], v[116:119], v[212:215], v[72:75]
	v_mfma_f32_16x16x32_bf16 v[132:135], v[144:147], v[160:163], v[132:135]
	v_mfma_f32_16x16x32_bf16 v[128:131], v[152:155], v[160:163], v[128:131]
	v_mfma_f32_16x16x32_bf16 v[112:115], v[144:147], v[182:185], v[112:115]
	v_mfma_f32_16x16x32_bf16 v[104:107], v[152:155], v[182:185], v[104:107]
	v_mfma_f32_16x16x32_bf16 v[84:87], v[144:147], v[194:197], v[84:87]
	v_mfma_f32_16x16x32_bf16 v[80:83], v[152:155], v[194:197], v[80:83]
	v_mfma_f32_16x16x32_bf16 v[68:71], v[144:147], v[208:211], v[68:71]
	v_mfma_f32_16x16x32_bf16 v[64:67], v[152:155], v[208:211], v[64:67]
	v_mfma_f32_16x16x32_bf16 v[132:135], v[148:151], v[164:167], v[132:135]
	v_mfma_f32_16x16x32_bf16 v[128:131], v[156:159], v[164:167], v[128:131]
	v_mfma_f32_16x16x32_bf16 v[112:115], v[148:151], v[186:189], v[112:115]
	v_mfma_f32_16x16x32_bf16 v[104:107], v[156:159], v[186:189], v[104:107]
	v_mfma_f32_16x16x32_bf16 v[84:87], v[148:151], v[204:207], v[84:87]
	v_mfma_f32_16x16x32_bf16 v[80:83], v[156:159], v[204:207], v[80:83]
	v_mfma_f32_16x16x32_bf16 v[68:71], v[148:151], v[212:215], v[68:71]
	v_mfma_f32_16x16x32_bf16 v[64:67], v[156:159], v[212:215], v[64:67]
	s_barrier
; #define PG8_STAGE(bufoff, gbase, voff) do { _Pragma("unroll") for (int _i = 0; _i < 2; ++_i) \
;         __builtin_amdgcn_global_load_lds((const unsigned*)((const char*)(gbase) + (voff)[_i]), (LAS unsigned*)(lds + (bufoff) + ldsw + _i * 8192), 16, 0, 0); } while (0)
; #define PG8_LDA(dst, b, h) do { _Pragma("unroll") for (int m = 0; m < 4; ++m) _Pragma("unroll") for (int k = 0; k < 2; ++k) dst[m][k] = *(const LAS bf16x8*)(lds + PG8_SA(b, h) + aoff + m * 2048 + k * 1024); } while (0)
; #define PG8_LDB(dst, b, h) do { _Pragma("unroll") for (int n = 0; n < 2; ++n) _Pragma("unroll") for (int k = 0; k < 2; ++k) dst[n][k] = *(const LAS bf16x8*)(lds + PG8_SB(b, h) + boff + n * 2048 + k * 1024); } while (0)
; template <class Epi, class Sched = StaticOrder, class EpiSub = NoSub, bool FAST = false>
; __device__ __forceinline__ void gemm_phase(LAS unsigned char* lds, const Gemm g, const Sched& S, const Epi& E, const EpiSub& ES = EpiSub()) {
;     ...
;         for (int t = 0; t < nt; t += 2) {
;             const bool last = (t == nt - 2);
;             const char* a1 = cA + (size_t)(t + 1) * kstep;
;             const char* a2 = last ? nA : cA + (size_t)(t + 2) * kstep; const char* b2 = last ? nB : cB + (size_t)(t + 2) * kstep;
;             const char* a3 = a2 + kstep; const char* b3 = b2 + kstep;
;             if constexpr (FAST && PG8_SP2) {
;             PG8_LDB(B0, 0, 0); PG8_LDB(B1, 0, 1); PG8_SCHED; PG8_LDA(At, 0, 0); PG8_STAGE(PG8_SA(1, 1), a1 + hstepA, voffA);
;             PG8_WAIT_V(8); PG8_WAIT_L(0); PG8_BAR; PG8_MMA(0, 0, At, B0); PG8_MMA(0, 1, At, B1); PG8_BAR; PG8_SCHED;
;             PG8_LDA(At, 0, 1); PG8_STAGE(PG8_SB(0, 0), b2, voffB); PG8_STAGE(PG8_SB(0, 1), b2 + hstepB, voffB); PG8_STAGE(PG8_SA(0, 0), a2, voffA);
;             PG8_WAIT_V(8); PG8_WAIT_L(0); PG8_BAR; PG8_MMA(1, 0, At, B0); PG8_MMA(1, 1, At, B1); PG8_BAR; PG8_SCHED;
;             PG8_LDB(B0, 1, 0); PG8_LDB(B1, 1, 1); PG8_SCHED; PG8_LDA(At, 1, 0); PG8_STAGE(PG8_SA(0, 1), a2 + hstepA, voffA);
;             PG8_WAIT_V(8); PG8_WAIT_L(0); PG8_BAR; PG8_MMA(0, 0, At, B0); PG8_MMA(0, 1, At, B1); PG8_BAR; PG8_SCHED;
;             PG8_LDA(At, 1, 1); PG8_STAGE(PG8_SB(1, 0), b3, voffB); PG8_STAGE(PG8_SB(1, 1), b3 + hstepB, voffB); PG8_STAGE(PG8_SA(1, 0), a3, voffA);
;             PG8_WAIT_V(8); PG8_WAIT_L(0); PG8_BAR; PG8_MMA(1, 0, At, B0); PG8_MMA(1, 1, At, B1); PG8_BAR; PG8_SCHED;
	s_add_i32 s46, s86, s27
	v_lshl_add_u64 v[190:191], v[190:191], 0, s[16:17]
	s_mov_b32 m0, s46
	ds_read_b128 v[160:163], v203 offset:49152
	ds_read_b128 v[164:167], v203 offset:50176
	ds_read_b128 v[182:185], v203 offset:51200
	ds_read_b128 v[186:189], v203 offset:52224
	ds_read_b128 v[194:197], v203 offset:53248
	ds_read_b128 v[204:207], v203 offset:54272
	ds_read_b128 v[208:211], v203 offset:55296
	ds_read_b128 v[212:215], v203 offset:56320
	global_load_lds_dwordx4 v[190:191], off
	s_add_i32 m0, s46, 0x2000
	s_add_u32 s44, s44, 0x160080
	v_lshl_add_u64 v[190:191], v[216:217], 0, s[16:17]
	s_addc_u32 s45, s45, 0
	s_add_i32 s46, s87, s27
	global_load_lds_dwordx4 v[190:191], off
	v_lshl_add_u64 v[190:191], s[44:45], 0, v[170:171]
	s_mov_b32 m0, s46
	s_nop 0
	global_load_lds_dwordx4 v[190:191], off
	v_lshl_add_u64 v[190:191], s[44:45], 0, v[174:175]
	s_add_i32 m0, s46, 0x2000
	s_nop 0
	global_load_lds_dwordx4 v[190:191], off
	v_lshl_add_u64 v[190:191], v[218:219], 0, s[16:17]
	s_mov_b32 m0, s53
	s_nop 0
	global_load_lds_dwordx4 v[190:191], off
	v_lshl_add_u64 v[190:191], v[220:221], 0, s[16:17]
	s_mov_b32 m0, s54
	s_nop 0
	global_load_lds_dwordx4 v[190:191], off
	s_waitcnt vmcnt(8) lgkmcnt(0)
	s_barrier
	v_mfma_f32_16x16x32_bf16 v[60:63], v[96:99], v[160:163], v[60:63]
	v_mfma_f32_16x16x32_bf16 v[56:59], v[108:111], v[160:163], v[56:59]
	v_mfma_f32_16x16x32_bf16 v[44:47], v[96:99], v[182:185], v[44:47]
	v_mfma_f32_16x16x32_bf16 v[40:43], v[108:111], v[182:185], v[40:43]
	v_mfma_f32_16x16x32_bf16 v[28:31], v[96:99], v[194:197], v[28:31]
	v_mfma_f32_16x16x32_bf16 v[24:27], v[108:111], v[194:197], v[24:27]
	v_mfma_f32_16x16x32_bf16 v[12:15], v[96:99], v[208:211], v[12:15]
	v_mfma_f32_16x16x32_bf16 v[8:11], v[108:111], v[208:211], v[8:11]
	v_mfma_f32_16x16x32_bf16 v[60:63], v[100:103], v[164:167], v[60:63]
	v_mfma_f32_16x16x32_bf16 v[56:59], v[116:119], v[164:167], v[56:59]
	v_mfma_f32_16x16x32_bf16 v[44:47], v[100:103], v[186:189], v[44:47]
	v_mfma_f32_16x16x32_bf16 v[40:43], v[116:119], v[186:189], v[40:43]
	v_mfma_f32_16x16x32_bf16 v[28:31], v[100:103], v[204:207], v[28:31]
	v_mfma_f32_16x16x32_bf16 v[24:27], v[116:119], v[204:207], v[24:27]
	v_mfma_f32_16x16x32_bf16 v[12:15], v[100:103], v[212:215], v[12:15]
	v_mfma_f32_16x16x32_bf16 v[8:11], v[116:119], v[212:215], v[8:11]
	v_mfma_f32_16x16x32_bf16 v[52:55], v[144:147], v[160:163], v[52:55]
	v_mfma_f32_16x16x32_bf16 v[48:51], v[152:155], v[160:163], v[48:51]
	v_mfma_f32_16x16x32_bf16 v[36:39], v[144:147], v[182:185], v[36:39]
	v_mfma_f32_16x16x32_bf16 v[32:35], v[152:155], v[182:185], v[32:35]
	v_mfma_f32_16x16x32_bf16 v[20:23], v[144:147], v[194:197], v[20:23]
	v_mfma_f32_16x16x32_bf16 v[16:19], v[152:155], v[194:197], v[16:19]
	v_mfma_f32_16x16x32_bf16 v[4:7], v[144:147], v[208:211], v[4:7]
	v_mfma_f32_16x16x32_bf16 v[0:3], v[152:155], v[208:211], v[0:3]
	v_mfma_f32_16x16x32_bf16 v[52:55], v[148:151], v[164:167], v[52:55]
	v_mfma_f32_16x16x32_bf16 v[48:51], v[156:159], v[164:167], v[48:51]
	v_mfma_f32_16x16x32_bf16 v[36:39], v[148:151], v[186:189], v[36:39]
	v_mfma_f32_16x16x32_bf16 v[32:35], v[156:159], v[186:189], v[32:35]
	v_mfma_f32_16x16x32_bf16 v[20:23], v[148:151], v[204:207], v[20:23]
	v_mfma_f32_16x16x32_bf16 v[16:19], v[156:159], v[204:207], v[16:19]
	v_mfma_f32_16x16x32_bf16 v[4:7], v[148:151], v[212:215], v[4:7]
	v_mfma_f32_16x16x32_bf16 v[0:3], v[156:159], v[212:215], v[0:3]
	s_barrier
	s_add_u32 s42, s42, 0x100
	s_addc_u32 s43, s43, 0
	s_add_u32 s83, s83, 0x100
	s_addc_u32 s84, s84, 0
	s_cmp_ge_u32 s85, s70
	s_mov_b32 s46, s85
	s_cbranch_scc1 .Lkpeel_1079_exit
.LBB0_1079:
	ds_read_b128 v[96:99], v201
	ds_read_b128 v[100:103], v201 offset:1024
	ds_read_b128 v[108:111], v201 offset:2048
	ds_read_b128 v[116:119], v201 offset:3072
	ds_read_b128 v[144:147], v202
	ds_read_b128 v[148:151], v202 offset:1024
	ds_read_b128 v[152:155], v202 offset:2048
	ds_read_b128 v[156:159], v202 offset:3072
	s_add_i32 s85, s46, 2
	s_add_u32 s44, s42, 0xffea0080
	s_addc_u32 s45, s43, -1
	s_cmp_eq_u32 s71, s46
	s_cselect_b32 s46, s38, s44
	s_cselect_b32 s47, s39, s45
	s_cselect_b32 s45, s41, s84
	s_cselect_b32 s44, s40, s83
	v_lshl_add_u64 v[190:191], s[42:43], 0, v[176:177]
	s_add_i32 m0, s48, 0xc000
	ds_read_b128 v[160:163], v203
	ds_read_b128 v[164:167], v203 offset:1024
	ds_read_b128 v[182:185], v203 offset:2048
	ds_read_b128 v[186:189], v203 offset:3072
	ds_read_b128 v[194:197], v203 offset:4096
	ds_read_b128 v[204:207], v203 offset:5120
	ds_read_b128 v[208:211], v203 offset:6144
	ds_read_b128 v[212:215], v203 offset:7168
	global_load_lds_dwordx4 v[190:191], off
	v_lshl_add_u64 v[190:191], s[42:43], 0, v[178:179]
	s_add_i32 m0, s48, 0xe000
	s_nop 0
	global_load_lds_dwordx4 v[190:191], off
	s_waitcnt vmcnt(8) lgkmcnt(0)
	s_barrier
; #define PG8_STAGE(bufoff, gbase, voff) do { _Pragma("unroll") for (int _i = 0; _i < 2; ++_i) \
;         __builtin_amdgcn_global_load_lds((const unsigned*)((const char*)(gbase) + (voff)[_i]), (LAS unsigned*)(lds + (bufoff) + ldsw + _i * 8192), 16, 0, 0); } while (0)
; #define PG8_LDA(dst, b, h) do { _Pragma("unroll") for (int m = 0; m < 4; ++m) _Pragma("unroll") for (int k = 0; k < 2; ++k) dst[m][k] = *(const LAS bf16x8*)(lds + PG8_SA(b, h) + aoff + m * 2048 + k * 1024); } while (0)
; #define PG8_LDB(dst, b, h) do { _Pragma("unroll") for (int n = 0; n < 2; ++n) _Pragma("unroll") for (int k = 0; k < 2; ++k) dst[n][k] = *(const LAS bf16x8*)(lds + PG8_SB(b, h) + boff + n * 2048 + k * 1024); } while (0)
; #define PG8_MMA(ai, bj, At, Bt) do { __builtin_amdgcn_s_setprio(1); _Pragma("unroll") for (int m = 0; m < 4; ++m) _Pragma("unroll") for (int n = 0; n < 2; ++n) _Pragma("unroll") for (int k = 0; k < 2; ++k) \
;         acc[ai][bj][m][n] = __builtin_amdgcn_mfma_f32_16x16x32_bf16(Bt[n][k], At[m][k], acc[ai][bj][m][n], 0, 0, 0); __builtin_amdgcn_s_setprio(0); } while (0)
; #define PG8_WAIT_V(n) asm volatile("s_waitcnt vmcnt(" #n ")" ::: "memory")
; #define PG8_WAIT_L(n) asm volatile("s_waitcnt lgkmcnt(" #n ")" ::: "memory")
; #define PG8_BAR __builtin_amdgcn_s_barrier()
; #define PG8_SCHED __builtin_amdgcn_sched_barrier(0)
; template <class Epi, class Sched = StaticOrder, class EpiSub = NoSub, bool FAST = false>
; __device__ __forceinline__ void gemm_phase(LAS unsigned char* lds, const Gemm g, const Sched& S, const Epi& E, const EpiSub& ES = EpiSub()) {
;     ...
;             PG8_LDB(B0, 0, 0); PG8_LDB(B1, 0, 1); PG8_SCHED; PG8_LDA(At, 0, 0); PG8_STAGE(PG8_SA(1, 1), a1 + hstepA, voffA);
;             PG8_WAIT_V(8); PG8_WAIT_L(0); PG8_BAR; PG8_MMA(0, 0, At, B0); PG8_MMA(0, 1, At, B1); PG8_BAR; PG8_SCHED;
;             PG8_LDA(At, 0, 1); PG8_STAGE(PG8_SB(0, 0), b2, voffB); PG8_STAGE(PG8_SB(0, 1), b2 + hstepB, voffB); PG8_STAGE(PG8_SA(0, 0), a2, voffA);
;             PG8_WAIT_V(8); PG8_WAIT_L(0); PG8_BAR; PG8_MMA(1, 0, At, B0); PG8_MMA(1, 1, At, B1); PG8_BAR; PG8_SCHED;
	v_mfma_f32_16x16x32_bf16 v[140:143], v[96:99], v[160:163], v[140:143]
	v_mfma_f32_16x16x32_bf16 v[136:139], v[108:111], v[160:163], v[136:139]
	v_mfma_f32_16x16x32_bf16 v[124:127], v[96:99], v[182:185], v[124:127]
	v_mfma_f32_16x16x32_bf16 v[120:123], v[108:111], v[182:185], v[120:123]
	v_mfma_f32_16x16x32_bf16 v[92:95], v[96:99], v[194:197], v[92:95]
	v_mfma_f32_16x16x32_bf16 v[88:91], v[108:111], v[194:197], v[88:91]
	v_mfma_f32_16x16x32_bf16 v[76:79], v[96:99], v[208:211], v[76:79]
	v_mfma_f32_16x16x32_bf16 v[72:75], v[108:111], v[208:211], v[72:75]
	v_mfma_f32_16x16x32_bf16 v[140:143], v[100:103], v[164:167], v[140:143]
	v_mfma_f32_16x16x32_bf16 v[136:139], v[116:119], v[164:167], v[136:139]
	v_mfma_f32_16x16x32_bf16 v[124:127], v[100:103], v[186:189], v[124:127]
	v_mfma_f32_16x16x32_bf16 v[120:123], v[116:119], v[186:189], v[120:123]
	v_mfma_f32_16x16x32_bf16 v[92:95], v[100:103], v[204:207], v[92:95]
	v_mfma_f32_16x16x32_bf16 v[88:91], v[116:119], v[204:207], v[88:91]
	v_mfma_f32_16x16x32_bf16 v[76:79], v[100:103], v[212:215], v[76:79]
	v_mfma_f32_16x16x32_bf16 v[72:75], v[116:119], v[212:215], v[72:75]
	v_mfma_f32_16x16x32_bf16 v[132:135], v[144:147], v[160:163], v[132:135]
	v_mfma_f32_16x16x32_bf16 v[128:131], v[152:155], v[160:163], v[128:131]
	v_mfma_f32_16x16x32_bf16 v[112:115], v[144:147], v[182:185], v[112:115]
	v_mfma_f32_16x16x32_bf16 v[104:107], v[152:155], v[182:185], v[104:107]
	v_mfma_f32_16x16x32_bf16 v[84:87], v[144:147], v[194:197], v[84:87]
	v_mfma_f32_16x16x32_bf16 v[80:83], v[152:155], v[194:197], v[80:83]
	v_mfma_f32_16x16x32_bf16 v[68:71], v[144:147], v[208:211], v[68:71]
	v_mfma_f32_16x16x32_bf16 v[64:67], v[152:155], v[208:211], v[64:67]
	v_mfma_f32_16x16x32_bf16 v[132:135], v[148:151], v[164:167], v[132:135]
	v_mfma_f32_16x16x32_bf16 v[128:131], v[156:159], v[164:167], v[128:131]
	v_mfma_f32_16x16x32_bf16 v[112:115], v[148:151], v[186:189], v[112:115]
	v_mfma_f32_16x16x32_bf16 v[104:107], v[156:159], v[186:189], v[104:107]
	v_mfma_f32_16x16x32_bf16 v[84:87], v[148:151], v[204:207], v[84:87]
	v_mfma_f32_16x16x32_bf16 v[80:83], v[156:159], v[204:207], v[80:83]
	v_mfma_f32_16x16x32_bf16 v[68:71], v[148:151], v[212:215], v[68:71]
	v_mfma_f32_16x16x32_bf16 v[64:67], v[156:159], v[212:215], v[64:67]
	s_barrier
	s_add_i32 s86, s58, s27
	v_lshl_add_u64 v[190:191], s[44:45], 0, v[170:171]
	s_mov_b32 m0, s86
	ds_read_b128 v[160:163], v203 offset:16384
	ds_read_b128 v[164:167], v203 offset:17408
	ds_read_b128 v[182:185], v203 offset:18432
	ds_read_b128 v[186:189], v203 offset:19456
	ds_read_b128 v[194:197], v203 offset:20480
	ds_read_b128 v[204:207], v203 offset:21504
	ds_read_b128 v[208:211], v203 offset:22528
	ds_read_b128 v[212:215], v203 offset:23552
	global_load_lds_dwordx4 v[190:191], off
	s_add_i32 m0, s86, 0x2000
	s_add_u32 s86, s44, 0x160000
	v_lshl_add_u64 v[216:217], s[44:45], 0, v[174:175]
	s_addc_u32 s87, s45, 0
	s_add_i32 s88, s59, s27
	global_load_lds_dwordx4 v[216:217], off
	v_lshl_add_u64 v[218:219], s[86:87], 0, v[170:171]
	s_mov_b32 m0, s88
	v_lshl_add_u64 v[220:221], s[46:47], 0, v[172:173]
	global_load_lds_dwordx4 v[218:219], off
	v_lshl_add_u64 v[218:219], s[86:87], 0, v[174:175]
	s_add_i32 m0, s88, 0x2000
	s_nop 0
	global_load_lds_dwordx4 v[218:219], off
	v_lshl_add_u64 v[218:219], s[46:47], 0, v[168:169]
	s_mov_b32 m0, s48
	s_nop 0
	global_load_lds_dwordx4 v[218:219], off
	s_mov_b32 m0, s49
	s_nop 0
	global_load_lds_dwordx4 v[220:221], off
	s_waitcnt vmcnt(8) lgkmcnt(0)
	s_barrier
	v_mfma_f32_16x16x32_bf16 v[60:63], v[96:99], v[160:163], v[60:63]
	v_mfma_f32_16x16x32_bf16 v[56:59], v[108:111], v[160:163], v[56:59]
	v_mfma_f32_16x16x32_bf16 v[44:47], v[96:99], v[182:185], v[44:47]
	v_mfma_f32_16x16x32_bf16 v[40:43], v[108:111], v[182:185], v[40:43]
	v_mfma_f32_16x16x32_bf16 v[28:31], v[96:99], v[194:197], v[28:31]
	v_mfma_f32_16x16x32_bf16 v[24:27], v[108:111], v[194:197], v[24:27]
	v_mfma_f32_16x16x32_bf16 v[12:15], v[96:99], v[208:211], v[12:15]
	v_mfma_f32_16x16x32_bf16 v[8:11], v[108:111], v[208:211], v[8:11]
	v_mfma_f32_16x16x32_bf16 v[60:63], v[100:103], v[164:167], v[60:63]
	v_mfma_f32_16x16x32_bf16 v[56:59], v[116:119], v[164:167], v[56:59]
	v_mfma_f32_16x16x32_bf16 v[44:47], v[100:103], v[186:189], v[44:47]
	v_mfma_f32_16x16x32_bf16 v[40:43], v[116:119], v[186:189], v[40:43]
	v_mfma_f32_16x16x32_bf16 v[28:31], v[100:103], v[204:207], v[28:31]
	v_mfma_f32_16x16x32_bf16 v[24:27], v[116:119], v[204:207], v[24:27]
	v_mfma_f32_16x16x32_bf16 v[12:15], v[100:103], v[212:215], v[12:15]
	v_mfma_f32_16x16x32_bf16 v[8:11], v[116:119], v[212:215], v[8:11]
	v_mfma_f32_16x16x32_bf16 v[52:55], v[144:147], v[160:163], v[52:55]
	v_mfma_f32_16x16x32_bf16 v[48:51], v[152:155], v[160:163], v[48:51]
	v_mfma_f32_16x16x32_bf16 v[36:39], v[144:147], v[182:185], v[36:39]
	v_mfma_f32_16x16x32_bf16 v[32:35], v[152:155], v[182:185], v[32:35]
	v_mfma_f32_16x16x32_bf16 v[20:23], v[144:147], v[194:197], v[20:23]
	v_mfma_f32_16x16x32_bf16 v[16:19], v[152:155], v[194:197], v[16:19]
	v_mfma_f32_16x16x32_bf16 v[4:7], v[144:147], v[208:211], v[4:7]
	v_mfma_f32_16x16x32_bf16 v[0:3], v[152:155], v[208:211], v[0:3]
	v_mfma_f32_16x16x32_bf16 v[52:55], v[148:151], v[164:167], v[52:55]
	v_mfma_f32_16x16x32_bf16 v[48:51], v[156:159], v[164:167], v[48:51]
	v_mfma_f32_16x16x32_bf16 v[36:39], v[148:151], v[186:189], v[36:39]
	v_mfma_f32_16x16x32_bf16 v[32:35], v[156:159], v[186:189], v[32:35]
	v_mfma_f32_16x16x32_bf16 v[20:23], v[148:151], v[204:207], v[20:23]
	v_mfma_f32_16x16x32_bf16 v[16:19], v[156:159], v[204:207], v[16:19]
	v_mfma_f32_16x16x32_bf16 v[4:7], v[148:151], v[212:215], v[4:7]
	v_mfma_f32_16x16x32_bf16 v[0:3], v[156:159], v[212:215], v[0:3]
	s_barrier
; #define PG8_STAGE(bufoff, gbase, voff) do { _Pragma("unroll") for (int _i = 0; _i < 2; ++_i) \
;         __builtin_amdgcn_global_load_lds((const unsigned*)((const char*)(gbase) + (voff)[_i]), (LAS unsigned*)(lds + (bufoff) + ldsw + _i * 8192), 16, 0, 0); } while (0)
; #define PG8_LDA(dst, b, h) do { _Pragma("unroll") for (int m = 0; m < 4; ++m) _Pragma("unroll") for (int k = 0; k < 2; ++k) dst[m][k] = *(const LAS bf16x8*)(lds + PG8_SA(b, h) + aoff + m * 2048 + k * 1024); } while (0)
; #define PG8_LDB(dst, b, h) do { _Pragma("unroll") for (int n = 0; n < 2; ++n) _Pragma("unroll") for (int k = 0; k < 2; ++k) dst[n][k] = *(const LAS bf16x8*)(lds + PG8_SB(b, h) + boff + n * 2048 + k * 1024); } while (0)
; template <class Epi, class Sched = StaticOrder, class EpiSub = NoSub, bool FAST = false>
; __device__ __forceinline__ void gemm_phase(LAS unsigned char* lds, const Gemm g, const Sched& S, const Epi& E, const EpiSub& ES = EpiSub()) {
;     ...
;         for (int t = 0; t < nt; t += 2) {
;             const bool last = (t == nt - 2);
;             const char* a1 = cA + (size_t)(t + 1) * kstep;
;             const char* a2 = last ? nA : cA + (size_t)(t + 2) * kstep; const char* b2 = last ? nB : cB + (size_t)(t + 2) * kstep;
;             const char* a3 = a2 + kstep; const char* b3 = b2 + kstep;
;             if constexpr (FAST && PG8_SP2) {
;             PG8_LDB(B0, 0, 0); PG8_LDB(B1, 0, 1); PG8_SCHED; PG8_LDA(At, 0, 0); PG8_STAGE(PG8_SA(1, 1), a1 + hstepA, voffA);
;             PG8_WAIT_V(8); PG8_WAIT_L(0); PG8_BAR; PG8_MMA(0, 0, At, B0); PG8_MMA(0, 1, At, B1); PG8_BAR; PG8_SCHED;
;             PG8_LDA(At, 0, 1); PG8_STAGE(PG8_SB(0, 0), b2, voffB); PG8_STAGE(PG8_SB(0, 1), b2 + hstepB, voffB); PG8_STAGE(PG8_SA(0, 0), a2, voffA);
;             PG8_WAIT_V(8); PG8_WAIT_L(0); PG8_BAR; PG8_MMA(1, 0, At, B0); PG8_MMA(1, 1, At, B1); PG8_BAR; PG8_SCHED;
;             PG8_LDB(B0, 1, 0); PG8_LDB(B1, 1, 1); PG8_SCHED; PG8_LDA(At, 1, 0); PG8_STAGE(PG8_SA(0, 1), a2 + hstepA, voffA);
;             PG8_WAIT_V(8); PG8_WAIT_L(0); PG8_BAR; PG8_MMA(0, 0, At, B0); PG8_MMA(0, 1, At, B1); PG8_BAR; PG8_SCHED;
;             PG8_LDA(At, 1, 1); PG8_STAGE(PG8_SB(1, 0), b3, voffB); PG8_STAGE(PG8_SB(1, 1), b3 + hstepB, voffB); PG8_STAGE(PG8_SA(1, 0), a3, voffA);
;             PG8_WAIT_V(8); PG8_WAIT_L(0); PG8_BAR; PG8_MMA(1, 0, At, B0); PG8_MMA(1, 1, At, B1); PG8_BAR; PG8_SCHED;
	s_add_i32 s86, 0, 0x18000
	s_add_i32 s87, 0, 0x1c000
	v_add_u32_e32 v116, s86, v198
	v_add_u32_e32 v156, s87, v198
	ds_read_b128 v[96:99], v116
	ds_read_b128 v[100:103], v116 offset:1024
	ds_read_b128 v[108:111], v116 offset:2048
	ds_read_b128 v[116:119], v116 offset:3072
	ds_read_b128 v[144:147], v156
	ds_read_b128 v[148:151], v156 offset:1024
	ds_read_b128 v[152:155], v156 offset:2048
	ds_read_b128 v[156:159], v156 offset:3072
	s_add_u32 s46, s46, 0x160000
	s_addc_u32 s47, s47, 0
	s_mov_b32 m0, s50
	v_lshl_add_u64 v[222:223], s[46:47], 0, v[168:169]
	ds_read_b128 v[160:163], v203 offset:32768
	ds_read_b128 v[164:167], v203 offset:33792
	ds_read_b128 v[182:185], v203 offset:34816
	ds_read_b128 v[186:189], v203 offset:35840
	ds_read_b128 v[194:197], v203 offset:36864
	ds_read_b128 v[204:207], v203 offset:37888
	ds_read_b128 v[208:211], v203 offset:38912
	ds_read_b128 v[212:215], v203 offset:39936
	global_load_lds_dwordx4 v[222:223], off
	v_lshl_add_u64 v[222:223], s[46:47], 0, v[172:173]
	s_mov_b32 m0, s51
	s_nop 0
	global_load_lds_dwordx4 v[222:223], off
	s_waitcnt vmcnt(8) lgkmcnt(0)
	s_barrier
	v_mfma_f32_16x16x32_bf16 v[140:143], v[96:99], v[160:163], v[140:143]
	v_mfma_f32_16x16x32_bf16 v[136:139], v[108:111], v[160:163], v[136:139]
	v_mfma_f32_16x16x32_bf16 v[124:127], v[96:99], v[182:185], v[124:127]
	v_mfma_f32_16x16x32_bf16 v[120:123], v[108:111], v[182:185], v[120:123]
	v_mfma_f32_16x16x32_bf16 v[92:95], v[96:99], v[194:197], v[92:95]
	v_mfma_f32_16x16x32_bf16 v[88:91], v[108:111], v[194:197], v[88:91]
	v_mfma_f32_16x16x32_bf16 v[76:79], v[96:99], v[208:211], v[76:79]
	v_mfma_f32_16x16x32_bf16 v[72:75], v[108:111], v[208:211], v[72:75]
	v_mfma_f32_16x16x32_bf16 v[140:143], v[100:103], v[164:167], v[140:143]
	v_mfma_f32_16x16x32_bf16 v[136:139], v[116:119], v[164:167], v[136:139]
	v_mfma_f32_16x16x32_bf16 v[124:127], v[100:103], v[186:189], v[124:127]
	v_mfma_f32_16x16x32_bf16 v[120:123], v[116:119], v[186:189], v[120:123]
	v_mfma_f32_16x16x32_bf16 v[92:95], v[100:103], v[204:207], v[92:95]
	v_mfma_f32_16x16x32_bf16 v[88:91], v[116:119], v[204:207], v[88:91]
	v_mfma_f32_16x16x32_bf16 v[76:79], v[100:103], v[212:215], v[76:79]
	v_mfma_f32_16x16x32_bf16 v[72:75], v[116:119], v[212:215], v[72:75]
	v_mfma_f32_16x16x32_bf16 v[132:135], v[144:147], v[160:163], v[132:135]
	v_mfma_f32_16x16x32_bf16 v[128:131], v[152:155], v[160:163], v[128:131]
	v_mfma_f32_16x16x32_bf16 v[112:115], v[144:147], v[182:185], v[112:115]
	v_mfma_f32_16x16x32_bf16 v[104:107], v[152:155], v[182:185], v[104:107]
	v_mfma_f32_16x16x32_bf16 v[84:87], v[144:147], v[194:197], v[84:87]
	v_mfma_f32_16x16x32_bf16 v[80:83], v[152:155], v[194:197], v[80:83]
	v_mfma_f32_16x16x32_bf16 v[68:71], v[144:147], v[208:211], v[68:71]
	v_mfma_f32_16x16x32_bf16 v[64:67], v[152:155], v[208:211], v[64:67]
	v_mfma_f32_16x16x32_bf16 v[132:135], v[148:151], v[164:167], v[132:135]
	v_mfma_f32_16x16x32_bf16 v[128:131], v[156:159], v[164:167], v[128:131]
	v_mfma_f32_16x16x32_bf16 v[112:115], v[148:151], v[186:189], v[112:115]
	v_mfma_f32_16x16x32_bf16 v[104:107], v[156:159], v[186:189], v[104:107]
	v_mfma_f32_16x16x32_bf16 v[84:87], v[148:151], v[204:207], v[84:87]
	v_mfma_f32_16x16x32_bf16 v[80:83], v[156:159], v[204:207], v[80:83]
	v_mfma_f32_16x16x32_bf16 v[68:71], v[148:151], v[212:215], v[68:71]
	v_mfma_f32_16x16x32_bf16 v[64:67], v[156:159], v[212:215], v[64:67]
	s_barrier
	s_add_i32 s46, s86, s27
	v_lshl_add_u64 v[190:191], v[190:191], 0, s[16:17]
	s_mov_b32 m0, s46
	ds_read_b128 v[160:163], v203 offset:49152
	ds_read_b128 v[164:167], v203 offset:50176
	ds_read_b128 v[182:185], v203 offset:51200
	ds_read_b128 v[186:189], v203 offset:52224
	ds_read_b128 v[194:197], v203 offset:53248
	ds_read_b128 v[204:207], v203 offset:54272
	ds_read_b128 v[208:211], v203 offset:55296
	ds_read_b128 v[212:215], v203 offset:56320
	global_load_lds_dwordx4 v[190:191], off
	s_add_i32 m0, s46, 0x2000
	s_add_u32 s44, s44, 0x160080
	v_lshl_add_u64 v[190:191], v[216:217], 0, s[16:17]
	s_addc_u32 s45, s45, 0
	s_add_i32 s46, s87, s27
	global_load_lds_dwordx4 v[190:191], off
	v_lshl_add_u64 v[190:191], s[44:45], 0, v[170:171]
	s_mov_b32 m0, s46
	s_nop 0
	global_load_lds_dwordx4 v[190:191], off
	v_lshl_add_u64 v[190:191], s[44:45], 0, v[174:175]
	s_add_i32 m0, s46, 0x2000
	s_nop 0
	global_load_lds_dwordx4 v[190:191], off
	v_lshl_add_u64 v[190:191], v[218:219], 0, s[16:17]
	s_mov_b32 m0, s53
	s_nop 0
	global_load_lds_dwordx4 v[190:191], off
	v_lshl_add_u64 v[190:191], v[220:221], 0, s[16:17]
	s_mov_b32 m0, s54
	s_nop 0
	global_load_lds_dwordx4 v[190:191], off
	s_waitcnt vmcnt(8) lgkmcnt(0)
	s_barrier
	v_mfma_f32_16x16x32_bf16 v[60:63], v[96:99], v[160:163], v[60:63]
	v_mfma_f32_16x16x32_bf16 v[56:59], v[108:111], v[160:163], v[56:59]
	v_mfma_f32_16x16x32_bf16 v[44:47], v[96:99], v[182:185], v[44:47]
	v_mfma_f32_16x16x32_bf16 v[40:43], v[108:111], v[182:185], v[40:43]
	v_mfma_f32_16x16x32_bf16 v[28:31], v[96:99], v[194:197], v[28:31]
	v_mfma_f32_16x16x32_bf16 v[24:27], v[108:111], v[194:197], v[24:27]
	v_mfma_f32_16x16x32_bf16 v[12:15], v[96:99], v[208:211], v[12:15]
	v_mfma_f32_16x16x32_bf16 v[8:11], v[108:111], v[208:211], v[8:11]
	v_mfma_f32_16x16x32_bf16 v[60:63], v[100:103], v[164:167], v[60:63]
	v_mfma_f32_16x16x32_bf16 v[56:59], v[116:119], v[164:167], v[56:59]
	v_mfma_f32_16x16x32_bf16 v[44:47], v[100:103], v[186:189], v[44:47]
	v_mfma_f32_16x16x32_bf16 v[40:43], v[116:119], v[186:189], v[40:43]
	v_mfma_f32_16x16x32_bf16 v[28:31], v[100:103], v[204:207], v[28:31]
	v_mfma_f32_16x16x32_bf16 v[24:27], v[116:119], v[204:207], v[24:27]
	v_mfma_f32_16x16x32_bf16 v[12:15], v[100:103], v[212:215], v[12:15]
	v_mfma_f32_16x16x32_bf16 v[8:11], v[116:119], v[212:215], v[8:11]
	v_mfma_f32_16x16x32_bf16 v[52:55], v[144:147], v[160:163], v[52:55]
	v_mfma_f32_16x16x32_bf16 v[48:51], v[152:155], v[160:163], v[48:51]
	v_mfma_f32_16x16x32_bf16 v[36:39], v[144:147], v[182:185], v[36:39]
	v_mfma_f32_16x16x32_bf16 v[32:35], v[152:155], v[182:185], v[32:35]
	v_mfma_f32_16x16x32_bf16 v[20:23], v[144:147], v[194:197], v[20:23]
	v_mfma_f32_16x16x32_bf16 v[16:19], v[152:155], v[194:197], v[16:19]
	v_mfma_f32_16x16x32_bf16 v[4:7], v[144:147], v[208:211], v[4:7]
	v_mfma_f32_16x16x32_bf16 v[0:3], v[152:155], v[208:211], v[0:3]
	v_mfma_f32_16x16x32_bf16 v[52:55], v[148:151], v[164:167], v[52:55]
	v_mfma_f32_16x16x32_bf16 v[48:51], v[156:159], v[164:167], v[48:51]
	v_mfma_f32_16x16x32_bf16 v[36:39], v[148:151], v[186:189], v[36:39]
	v_mfma_f32_16x16x32_bf16 v[32:35], v[156:159], v[186:189], v[32:35]
	v_mfma_f32_16x16x32_bf16 v[20:23], v[148:151], v[204:207], v[20:23]
	v_mfma_f32_16x16x32_bf16 v[16:19], v[156:159], v[204:207], v[16:19]
	v_mfma_f32_16x16x32_bf16 v[4:7], v[148:151], v[212:215], v[4:7]
	v_mfma_f32_16x16x32_bf16 v[0:3], v[156:159], v[212:215], v[0:3]
	s_barrier
	s_add_u32 s42, s42, 0x100
	s_addc_u32 s43, s43, 0
	s_add_u32 s83, s83, 0x100
	s_addc_u32 s84, s84, 0
	s_cmp_ge_u32 s85, s70
	s_mov_b32 s46, s85
	s_cbranch_scc0 .LBB0_1079
